# speedup vs baseline: 1.0330x; 1.0254x over previous
; template <bool SWAP, class RowA, class Epi>
; DEV void gemm_tile(unsigned char* smem, RowA rowA, const bf16_t* Bt, int K, Epi epi) {
;     ...
;   for (int t = 0; t < nk; ++t) {
;     asm volatile("s_waitcnt vmcnt(0)" ::: "memory");
;     __syncthreads();
;     if (t + 1 < nk) stage(t + 1, (t + 1) & 1);
;     const unsigned char* SA = smem + (t & 1) * 16384;
;     const unsigned char* SB = SA + 8192;
;     bf16x8 At[4], Bl[4];
; #pragma unroll
;     for (int m = 0; m < 4; ++m) At[m] = *reinterpret_cast<const bf16x8*>(SA + (wr * 64 + m * 16) * 64 + rdoff);
; #pragma unroll
;     for (int n = 0; n < 4; ++n) Bl[n] = *reinterpret_cast<const bf16x8*>(SB + (wc * 64 + n * 16) * 64 + rdoff);
; #pragma unroll
;     for (int m = 0; m < 4; ++m)
; #pragma unroll
;       for (int n = 0; n < 4; ++n)
;         acc[m][n] = SWAP ? __builtin_amdgcn_mfma_f32_16x16x32_bf16(Bl[n], At[m], acc[m][n], 0, 0, 0)
;                          : __builtin_amdgcn_mfma_f32_16x16x32_bf16(At[m], Bl[n], acc[m][n], 0, 0, 0);
;   }
; DEV void phase_moe1(const Params& p, int l, unsigned char* smem) {
;     ...
;         for (int n = 0; n < 2; ++n) {
;           const int acol = nt * 64 + wc * 32 + n * 16 + fq * 4;
;           const float4 bg4 = *reinterpret_cast<const float4*>(bgu + acol);
;           const float4 bl4 = *reinterpret_cast<const float4*>(bgu + 1024 + acol);
.LBB0_650:
	s_add_i32 s7, s6, 0x4000
	s_and_b32 s8, s7, 0x4000
	v_add_u32_e32 v72, s8, v70
	v_add_u32_e32 v94, 0x1000, v72
	v_readfirstlane_b32 s8, v72
	v_lshl_add_u64 v[92:93], v[64:65], 0, s[4:5]
	s_mov_b32 m0, s8
	v_readfirstlane_b32 s8, v94
	s_waitcnt vmcnt(0)
	s_waitcnt vmcnt(0) lgkmcnt(0)
	s_barrier
	global_load_lds_dwordx4 v[92:93], off
	v_lshl_add_u64 v[92:93], v[66:67], 0, s[4:5]
	s_mov_b32 m0, s8
	s_mov_b32 s8, 0xffc00040
	v_add_u32_e32 v96, 0x2000, v72
	global_load_lds_dwordx4 v[92:93], off
	v_lshl_add_u64 v[92:93], v[68:69], 0, s[4:5]
	s_mov_b32 s9, -1
	v_lshl_add_u64 v[94:95], v[92:93], 0, s[8:9]
	v_readfirstlane_b32 s8, v96
	s_mov_b32 m0, s8
	s_mov_b32 s8, 0xffc20040
	s_mov_b32 s9, -1
	v_add_u32_e32 v72, 0x3000, v72
	v_lshl_add_u64 v[92:93], v[92:93], 0, s[8:9]
	v_readfirstlane_b32 s8, v72
	global_load_lds_dwordx4 v[94:95], off
	s_mov_b32 m0, s8
	s_and_b32 s6, s6, 0x4000
	global_load_lds_dwordx4 v[92:93], off
	v_or_b32_e32 v72, s6, v71
	v_add_u32_e32 v104, v72, v80
	v_add_u32_e32 v72, v72, v81
	ds_read_b128 v[92:95], v104
	ds_read_b128 v[96:99], v104 offset:1024
	ds_read_b128 v[100:103], v104 offset:2048
	ds_read_b128 v[104:107], v104 offset:3072
	ds_read_b128 v[108:111], v72 offset:8192
	ds_read_b128 v[112:115], v72 offset:9216
	ds_read_b128 v[116:119], v72 offset:10240
	ds_read_b128 v[124:127], v72 offset:11264
	s_waitcnt lgkmcnt(0)
	v_mfma_f32_16x16x32_bf16 v[60:63], v[108:111], v[92:95], v[60:63]
	s_add_u32 s4, s4, 64
	s_addc_u32 s5, s5, 0
	s_cmpk_eq_i32 s4, 0x7c0
	v_mfma_f32_16x16x32_bf16 v[24:27], v[112:115], v[92:95], v[24:27]
	s_mov_b32 s6, s7
	v_mfma_f32_16x16x32_bf16 v[56:59], v[116:119], v[92:95], v[56:59]
	v_mfma_f32_16x16x32_bf16 v[28:31], v[124:127], v[92:95], v[28:31]
	v_mfma_f32_16x16x32_bf16 v[52:55], v[108:111], v[96:99], v[52:55]
	v_mfma_f32_16x16x32_bf16 v[16:19], v[112:115], v[96:99], v[16:19]
	v_mfma_f32_16x16x32_bf16 v[48:51], v[116:119], v[96:99], v[48:51]
	v_mfma_f32_16x16x32_bf16 v[20:23], v[124:127], v[96:99], v[20:23]
	v_mfma_f32_16x16x32_bf16 v[40:43], v[108:111], v[100:103], v[40:43]
	v_mfma_f32_16x16x32_bf16 v[8:11], v[112:115], v[100:103], v[8:11]
	v_mfma_f32_16x16x32_bf16 v[36:39], v[116:119], v[100:103], v[36:39]
	v_mfma_f32_16x16x32_bf16 v[12:15], v[124:127], v[100:103], v[12:15]
	v_mfma_f32_16x16x32_bf16 v[32:35], v[108:111], v[104:107], v[32:35]
	v_mfma_f32_16x16x32_bf16 v[0:3], v[112:115], v[104:107], v[0:3]
	v_mfma_f32_16x16x32_bf16 v[44:47], v[116:119], v[104:107], v[44:47]
	v_mfma_f32_16x16x32_bf16 v[4:7], v[124:127], v[104:107], v[4:7]
	s_cbranch_scc0 .LBB0_650
	v_add_u32_e32 v72, v71, v81
	s_waitcnt vmcnt(0)
	s_waitcnt vmcnt(0)
	s_barrier
	ds_read_b128 v[92:95], v72 offset:24576
	ds_read_b128 v[100:103], v72 offset:25600
	ds_read_b128 v[104:107], v72 offset:26624
	ds_read_b128 v[108:111], v72 offset:27648
	v_add_u32_e32 v80, v71, v80
	ds_read_b128 v[96:99], v80 offset:16384
	ds_read_b128 v[112:115], v80 offset:19456
	s_waitcnt lgkmcnt(1)
	v_mfma_f32_16x16x32_bf16 v[64:67], v[92:95], v[96:99], v[60:63]
	v_readlane_b32 s72, v166, 55
	v_readlane_b32 s84, v165, 3
	v_readlane_b32 s85, v165, 4
	v_mfma_f32_16x16x32_bf16 v[24:27], v[100:103], v[96:99], v[24:27]
	s_lshl_b64 s[0:1], s[0:1], 2
	s_mov_b64 s[64:65], s[84:85]
	s_add_u32 s0, s64, s0
	v_mfma_f32_16x16x32_bf16 v[68:71], v[104:107], v[96:99], v[56:59]
	s_addc_u32 s1, s65, s1
	s_lshl_b32 s4, s10, 6
	v_lshl_add_u32 v72, v78, 6, s11
	v_mfma_f32_16x16x32_bf16 v[28:31], v[108:111], v[96:99], v[28:31]
	ds_read_b128 v[96:99], v80 offset:17408
	v_or_b32_e32 v72, v72, v79
	v_add_u32_e32 v78, v72, v77
	s_waitcnt lgkmcnt(0)
	v_mfma_f32_16x16x32_bf16 v[56:59], v[92:95], v[96:99], v[52:55]
	v_ashrrev_i32_e32 v79, 31, v78
	v_readlane_b32 s73, v166, 56
	v_readlane_b32 s74, v166, 57
	v_mfma_f32_16x16x32_bf16 v[16:19], v[100:103], v[96:99], v[16:19]
	v_readlane_b32 s75, v166, 58
	v_readlane_b32 s76, v166, 59
	v_readlane_b32 s77, v166, 60
	v_mfma_f32_16x16x32_bf16 v[60:63], v[104:107], v[96:99], v[48:51]
	v_readlane_b32 s78, v166, 61
	v_readlane_b32 s79, v166, 62
	v_readlane_b32 s80, v166, 63
	v_mfma_f32_16x16x32_bf16 v[20:23], v[108:111], v[96:99], v[20:23]
	ds_read_b128 v[96:99], v80 offset:18432
	v_readlane_b32 s81, v165, 0
	v_readlane_b32 s82, v165, 1
	s_waitcnt lgkmcnt(0)
	v_mfma_f32_16x16x32_bf16 v[48:51], v[92:95], v[96:99], v[40:43]
	v_readlane_b32 s83, v165, 2
	s_nop 1
	v_lshlrev_b32_e32 v40, 5, v74
	v_readlane_b32 s86, v165, 5
	v_mfma_f32_16x16x32_bf16 v[52:55], v[104:107], v[96:99], v[36:39]
	v_readlane_b32 s87, v165, 6
	s_nop 1
	v_lshlrev_b32_e32 v36, 2, v75
	v_or3_b32 v74, v40, s4, v36
	v_ashrrev_i32_e32 v75, 31, v74
	v_lshlrev_b64 v[40:41], 2, v[74:75]
	v_lshl_add_u64 v[80:81], s[0:1], 0, v[40:41]
	s_add_u32 s0, s0, 0x1000
	s_addc_u32 s1, s1, 0
	v_lshl_add_u64 v[40:41], s[0:1], 0, v[40:41]
	global_load_dwordx4 v[36:39], v[80:81], off
	v_mfma_f32_16x16x32_bf16 v[8:11], v[100:103], v[96:99], v[8:11]
	global_load_dwordx4 v[40:43], v[40:41], off
	v_cmp_lt_i32_e64 s[4:5], v72, v76
	v_mfma_f32_16x16x32_bf16 v[12:15], v[108:111], v[96:99], v[12:15]
	v_mfma_f32_16x16x32_bf16 v[32:35], v[92:95], v[112:115], v[32:35]
	v_mfma_f32_16x16x32_bf16 v[0:3], v[100:103], v[112:115], v[0:3]
	v_mfma_f32_16x16x32_bf16 v[44:47], v[104:107], v[112:115], v[44:47]
	v_mfma_f32_16x16x32_bf16 v[4:7], v[108:111], v[112:115], v[4:7]
	s_waitcnt vmcnt(0)
	s_and_saveexec_b64 s[6:7], s[4:5]
	s_cbranch_execz .LBB0_653
; DEV unsigned pack2(float a, float b) { return (unsigned)f2bf(a) | ((unsigned)f2bf(b) << 16); }
; DEV float sigmoidf_(float x) { return 1.f / (1.f + __expf(-x)); }
; DEV void phase_moe1(const Params& p, int l, unsigned char* smem) {
;     ...
;             const int i = mt * 128 + wr * 64 + m * 16 + fr;
;             if (i < cnt) {
;               float a[4];
; #pragma unroll
;               for (int j = 0; j < 4; ++j) {
;                 float gl = fminf(acc[m][n][j] + bgv[j], 7.f);
;                 float li = fminf(fmaxf(acc[m][n + 2][j] + blv[j], -7.f), 7.f);
;                 a[j] = gl * sigmoidf_(1.702f * gl) * (li + 1.f);
;               }
;               *reinterpret_cast<uint2*>(p.act + (size_t)(rowoff + i) * 1024 + acol) = make_uint2(pack2(a[0], a[1]), pack2(a[2], a[3]));
	v_add_f32_e32 v64, v64, v36
	v_min_f32_e32 v92, 0x40e00000, v64
	v_add_f32_e32 v64, v68, v40
	v_med3_f32 v94, v64, s2, v89
	v_mul_f32_e32 v64, 0x3fd9db23, v92
	v_mul_f32_e32 v64, 0xbfb8aa3b, v64
	v_exp_f32_e32 v96, v64
	v_add_f32_e32 v64, v65, v37
	v_min_f32_e32 v68, 0x40e00000, v64
	v_mul_f32_e32 v65, 0x3fd9db23, v68
	v_mul_f32_e32 v65, 0xbfb8aa3b, v65
	v_exp_f32_e32 v98, v65
	v_add_f32_e32 v65, v66, v38
	v_min_f32_e32 v93, 0x40e00000, v65
	v_add_f32_e32 v65, v70, v42
	v_med3_f32 v95, v65, s2, v89
	v_mul_f32_e32 v65, 0x3fd9db23, v93
	v_mul_f32_e32 v65, 0xbfb8aa3b, v65
	v_exp_f32_e32 v97, v65
	v_add_f32_e32 v65, v67, v39
	v_add_f32_e32 v64, v69, v41
	v_min_f32_e32 v69, 0x40e00000, v65
	v_add_f32_e32 v65, v71, v43
	v_pk_add_f32 v[70:71], v[96:97], 1.0 op_sel_hi:[1,0]
	v_mul_f32_e32 v66, 0x3fd9db23, v69
	v_div_scale_f32 v96, s[8:9], v71, v71, 1.0
	v_rcp_f32_e32 v97, v96
	v_mul_f32_e32 v66, 0xbfb8aa3b, v66
	v_exp_f32_e32 v99, v66
	v_med3_f32 v64, v64, s2, v89
	v_fma_f32 v100, -v96, v97, 1.0
	v_fmac_f32_e32 v97, v100, v97
	v_div_scale_f32 v100, vcc, 1.0, v71, 1.0
	v_mul_f32_e32 v101, v100, v97
	v_fma_f32 v102, -v96, v101, v100
	v_fmac_f32_e32 v101, v102, v97
	v_fma_f32 v96, -v96, v101, v100
	v_div_fmas_f32 v96, v96, v97, v101
	v_div_fixup_f32 v71, v96, v71, 1.0
	v_div_scale_f32 v96, s[8:9], v70, v70, 1.0
	v_rcp_f32_e32 v97, v96
	v_med3_f32 v65, v65, s2, v89
	v_pk_add_f32 v[64:65], v[64:65], 1.0 op_sel_hi:[1,0]
	v_readlane_b32 s72, v166, 7
	v_fma_f32 v100, -v96, v97, 1.0
	v_fmac_f32_e32 v97, v100, v97
	v_div_scale_f32 v100, vcc, 1.0, v70, 1.0
	v_mul_f32_e32 v101, v100, v97
	v_fma_f32 v102, -v96, v101, v100
	v_fmac_f32_e32 v101, v102, v97
	v_fma_f32 v96, -v96, v101, v100
	v_div_fmas_f32 v96, v96, v97, v101
	v_div_fixup_f32 v70, v96, v70, 1.0
	v_pk_mul_f32 v[70:71], v[92:93], v[70:71]
	v_pk_add_f32 v[92:93], v[94:95], 1.0 op_sel_hi:[1,0]
	v_lshlrev_b64 v[66:67], 11, v[78:79]
	v_pk_mul_f32 v[70:71], v[92:93], v[70:71]
	v_pk_add_f32 v[92:93], v[98:99], 1.0 op_sel_hi:[1,0]
	v_readlane_b32 s80, v166, 15
	v_div_scale_f32 v94, s[8:9], v93, v93, 1.0
	v_rcp_f32_e32 v95, v94
	v_readlane_b32 s81, v166, 16
	v_readlane_b32 s73, v166, 8
	v_readlane_b32 s74, v166, 9
	v_fma_f32 v96, -v94, v95, 1.0
	v_fmac_f32_e32 v95, v96, v95
	v_div_scale_f32 v96, vcc, 1.0, v93, 1.0
	v_mul_f32_e32 v97, v96, v95
	v_fma_f32 v98, -v94, v97, v96
	v_fmac_f32_e32 v97, v98, v95
	v_fma_f32 v94, -v94, v97, v96
	v_div_fmas_f32 v94, v94, v95, v97
	v_div_fixup_f32 v93, v94, v93, 1.0
	v_div_scale_f32 v94, s[8:9], v92, v92, 1.0
	v_rcp_f32_e32 v95, v94
	v_lshl_add_u64 v[66:67], s[80:81], 0, v[66:67]
	v_lshl_add_u64 v[66:67], v[74:75], 1, v[66:67]
	v_readlane_b32 s75, v166, 10
	v_fma_f32 v96, -v94, v95, 1.0
	v_fmac_f32_e32 v95, v96, v95
	v_div_scale_f32 v96, vcc, 1.0, v92, 1.0
	v_mul_f32_e32 v97, v96, v95
	v_fma_f32 v98, -v94, v97, v96
	v_fmac_f32_e32 v97, v98, v95
	v_fma_f32 v94, -v94, v97, v96
	v_div_fmas_f32 v94, v94, v95, v97
	v_div_fixup_f32 v92, v94, v92, 1.0
	v_pk_mul_f32 v[68:69], v[68:69], v[92:93]
	v_readlane_b32 s76, v166, 11
	v_pk_mul_f32 v[64:65], v[64:65], v[68:69]
	v_and_b32_sdwa v68, v71, v90 dst_sel:DWORD dst_unused:UNUSED_PAD src0_sel:WORD_1 src1_sel:DWORD
	v_and_b32_sdwa v69, v70, v90 dst_sel:DWORD dst_unused:UNUSED_PAD src0_sel:WORD_1 src1_sel:DWORD
	v_add3_u32 v69, v70, v69, s3
	v_add3_u32 v68, v71, v68, s3
	v_and_b32_sdwa v70, v65, v90 dst_sel:DWORD dst_unused:UNUSED_PAD src0_sel:WORD_1 src1_sel:DWORD
	v_and_b32_sdwa v71, v64, v90 dst_sel:DWORD dst_unused:UNUSED_PAD src0_sel:WORD_1 src1_sel:DWORD
	v_add3_u32 v65, v65, v70, s3
	v_add3_u32 v64, v64, v71, s3
	v_and_b32_e32 v65, 0xffff0000, v65
	v_and_b32_e32 v64, 0xffff0000, v64
	v_or_b32_sdwa v65, v65, v68 dst_sel:DWORD dst_unused:UNUSED_PAD src0_sel:DWORD src1_sel:WORD_1
	v_or_b32_sdwa v64, v64, v69 dst_sel:DWORD dst_unused:UNUSED_PAD src0_sel:DWORD src1_sel:WORD_1
	v_readlane_b32 s77, v166, 12
	v_readlane_b32 s78, v166, 13
	v_readlane_b32 s79, v166, 14
	v_readlane_b32 s82, v166, 17
	v_readlane_b32 s83, v166, 18
	v_readlane_b32 s84, v166, 19
	v_readlane_b32 s85, v166, 20
	v_readlane_b32 s86, v166, 21
	v_readlane_b32 s87, v166, 22
	global_store_dwordx2 v[66:67], v[64:65], off
.LBB0_653:
	s_or_b64 exec, exec, s[6:7]
	v_or_b32_e32 v64, 16, v72
	v_cmp_lt_i32_e64 s[6:7], v64, v76
	v_add_u32_e32 v64, v64, v77
	v_ashrrev_i32_e32 v65, 31, v64
	s_and_saveexec_b64 s[8:9], s[6:7]
	s_cbranch_execz .LBB0_655
; DEV unsigned pack2(float a, float b) { return (unsigned)f2bf(a) | ((unsigned)f2bf(b) << 16); }
; DEV float sigmoidf_(float x) { return 1.f / (1.f + __expf(-x)); }
; DEV void phase_moe1(const Params& p, int l, unsigned char* smem) {
;     ...
;             const int i = mt * 128 + wr * 64 + m * 16 + fr;
;             if (i < cnt) {
;               float a[4];
; #pragma unroll
;               for (int j = 0; j < 4; ++j) {
;                 float gl = fminf(acc[m][n][j] + bgv[j], 7.f);
;                 float li = fminf(fmaxf(acc[m][n + 2][j] + blv[j], -7.f), 7.f);
;                 a[j] = gl * sigmoidf_(1.702f * gl) * (li + 1.f);
;               }
;               *reinterpret_cast<uint2*>(p.act + (size_t)(rowoff + i) * 1024 + acol) = make_uint2(pack2(a[0], a[1]), pack2(a[2], a[3]));
	v_add_f32_e32 v56, v56, v36
	v_min_f32_e32 v66, 0x40e00000, v56
	v_add_f32_e32 v56, v60, v40
	v_med3_f32 v68, v56, s2, v89
	v_mul_f32_e32 v56, 0x3fd9db23, v66
	v_mul_f32_e32 v56, 0xbfb8aa3b, v56
	v_exp_f32_e32 v70, v56
	v_add_f32_e32 v56, v57, v37
	v_min_f32_e32 v60, 0x40e00000, v56
	v_mul_f32_e32 v57, 0x3fd9db23, v60
	v_mul_f32_e32 v57, 0xbfb8aa3b, v57
	v_exp_f32_e32 v92, v57
	v_add_f32_e32 v57, v58, v38
	v_min_f32_e32 v67, 0x40e00000, v57
	v_add_f32_e32 v57, v62, v42
	v_med3_f32 v69, v57, s2, v89
	v_mul_f32_e32 v57, 0x3fd9db23, v67
	v_mul_f32_e32 v57, 0xbfb8aa3b, v57
	v_exp_f32_e32 v71, v57
	v_add_f32_e32 v57, v59, v39
	v_add_f32_e32 v56, v61, v41
	v_min_f32_e32 v61, 0x40e00000, v57
	v_add_f32_e32 v57, v63, v43
	v_pk_add_f32 v[62:63], v[70:71], 1.0 op_sel_hi:[1,0]
	v_mul_f32_e32 v58, 0x3fd9db23, v61
	v_div_scale_f32 v70, s[10:11], v63, v63, 1.0
	v_rcp_f32_e32 v71, v70
	v_mul_f32_e32 v58, 0xbfb8aa3b, v58
	v_exp_f32_e32 v93, v58
	v_med3_f32 v56, v56, s2, v89
	v_fma_f32 v94, -v70, v71, 1.0
	v_fmac_f32_e32 v71, v94, v71
	v_div_scale_f32 v94, vcc, 1.0, v63, 1.0
	v_mul_f32_e32 v95, v94, v71
	v_fma_f32 v96, -v70, v95, v94
	v_fmac_f32_e32 v95, v96, v71
	v_fma_f32 v70, -v70, v95, v94
	v_div_fmas_f32 v70, v70, v71, v95
	v_div_fixup_f32 v63, v70, v63, 1.0
	v_div_scale_f32 v70, s[10:11], v62, v62, 1.0
	v_rcp_f32_e32 v71, v70
	v_med3_f32 v57, v57, s2, v89
	v_pk_add_f32 v[56:57], v[56:57], 1.0 op_sel_hi:[1,0]
	v_readlane_b32 s72, v166, 7
	v_fma_f32 v94, -v70, v71, 1.0
	v_fmac_f32_e32 v71, v94, v71
	v_div_scale_f32 v94, vcc, 1.0, v62, 1.0
	v_mul_f32_e32 v95, v94, v71
	v_fma_f32 v96, -v70, v95, v94
	v_fmac_f32_e32 v95, v96, v71
	v_fma_f32 v70, -v70, v95, v94
	v_div_fmas_f32 v70, v70, v71, v95
	v_div_fixup_f32 v62, v70, v62, 1.0
	v_pk_mul_f32 v[62:63], v[66:67], v[62:63]
	v_pk_add_f32 v[66:67], v[68:69], 1.0 op_sel_hi:[1,0]
	v_lshlrev_b64 v[58:59], 11, v[64:65]
	v_pk_mul_f32 v[62:63], v[66:67], v[62:63]
	v_pk_add_f32 v[66:67], v[92:93], 1.0 op_sel_hi:[1,0]
	v_readlane_b32 s80, v166, 15
	v_div_scale_f32 v68, s[10:11], v67, v67, 1.0
	v_rcp_f32_e32 v69, v68
	v_readlane_b32 s81, v166, 16
	v_readlane_b32 s73, v166, 8
	v_readlane_b32 s74, v166, 9
	v_fma_f32 v70, -v68, v69, 1.0
	v_fmac_f32_e32 v69, v70, v69
	v_div_scale_f32 v70, vcc, 1.0, v67, 1.0
	v_mul_f32_e32 v71, v70, v69
	v_fma_f32 v92, -v68, v71, v70
	v_fmac_f32_e32 v71, v92, v69
	v_fma_f32 v68, -v68, v71, v70
	v_div_fmas_f32 v68, v68, v69, v71
	v_div_fixup_f32 v67, v68, v67, 1.0
	v_div_scale_f32 v68, s[10:11], v66, v66, 1.0
	v_rcp_f32_e32 v69, v68
	v_lshl_add_u64 v[58:59], s[80:81], 0, v[58:59]
	v_lshl_add_u64 v[58:59], v[74:75], 1, v[58:59]
	v_readlane_b32 s75, v166, 10
	v_fma_f32 v70, -v68, v69, 1.0
	v_fmac_f32_e32 v69, v70, v69
	v_div_scale_f32 v70, vcc, 1.0, v66, 1.0
	v_mul_f32_e32 v71, v70, v69
	v_fma_f32 v92, -v68, v71, v70
	v_fmac_f32_e32 v71, v92, v69
	v_fma_f32 v68, -v68, v71, v70
	v_div_fmas_f32 v68, v68, v69, v71
	v_div_fixup_f32 v66, v68, v66, 1.0
	v_pk_mul_f32 v[60:61], v[60:61], v[66:67]
	v_readlane_b32 s76, v166, 11
	v_pk_mul_f32 v[56:57], v[56:57], v[60:61]
	v_and_b32_sdwa v60, v63, v90 dst_sel:DWORD dst_unused:UNUSED_PAD src0_sel:WORD_1 src1_sel:DWORD
	v_and_b32_sdwa v61, v62, v90 dst_sel:DWORD dst_unused:UNUSED_PAD src0_sel:WORD_1 src1_sel:DWORD
	v_add3_u32 v61, v62, v61, s3
	v_add3_u32 v60, v63, v60, s3
	v_and_b32_sdwa v62, v57, v90 dst_sel:DWORD dst_unused:UNUSED_PAD src0_sel:WORD_1 src1_sel:DWORD
	v_and_b32_sdwa v63, v56, v90 dst_sel:DWORD dst_unused:UNUSED_PAD src0_sel:WORD_1 src1_sel:DWORD
	v_add3_u32 v57, v57, v62, s3
	v_add3_u32 v56, v56, v63, s3
	v_and_b32_e32 v57, 0xffff0000, v57
	v_and_b32_e32 v56, 0xffff0000, v56
	v_or_b32_sdwa v57, v57, v60 dst_sel:DWORD dst_unused:UNUSED_PAD src0_sel:DWORD src1_sel:WORD_1
	v_or_b32_sdwa v56, v56, v61 dst_sel:DWORD dst_unused:UNUSED_PAD src0_sel:DWORD src1_sel:WORD_1
	v_readlane_b32 s77, v166, 12
	v_readlane_b32 s78, v166, 13
	v_readlane_b32 s79, v166, 14
	v_readlane_b32 s82, v166, 17
	v_readlane_b32 s83, v166, 18
	v_readlane_b32 s84, v166, 19
	v_readlane_b32 s85, v166, 20
	v_readlane_b32 s86, v166, 21
	v_readlane_b32 s87, v166, 22
	global_store_dwordx2 v[58:59], v[56:57], off
.LBB0_655:
	s_or_b64 exec, exec, s[8:9]
	v_or_b32_e32 v56, 32, v72
	v_cmp_lt_i32_e64 s[8:9], v56, v76
	v_add_u32_e32 v56, v56, v77
	v_ashrrev_i32_e32 v57, 31, v56
	s_and_saveexec_b64 s[10:11], s[8:9]
	v_readlane_b32 s56, v165, 39
	v_readlane_b32 s66, v165, 49
	v_readlane_b32 s67, v165, 50
	v_readlane_b32 s68, v165, 51
	v_readlane_b32 s69, v165, 52
	v_readlane_b32 s57, v165, 40
	v_readlane_b32 s58, v165, 41
	v_readlane_b32 s59, v165, 42
	v_readlane_b32 s60, v165, 43
	v_readlane_b32 s61, v165, 44
	v_readlane_b32 s62, v165, 45
	v_readlane_b32 s63, v165, 46
	v_readlane_b32 s64, v165, 47
	v_readlane_b32 s65, v165, 48
	v_readlane_b32 s70, v165, 53
	v_readlane_b32 s71, v165, 54
	s_cbranch_execz .LBB0_657
; DEV unsigned pack2(float a, float b) { return (unsigned)f2bf(a) | ((unsigned)f2bf(b) << 16); }
; DEV float sigmoidf_(float x) { return 1.f / (1.f + __expf(-x)); }
; DEV void phase_moe1(const Params& p, int l, unsigned char* smem) {
;     ...
;             const int i = mt * 128 + wr * 64 + m * 16 + fr;
;             if (i < cnt) {
;               float a[4];
; #pragma unroll
;               for (int j = 0; j < 4; ++j) {
;                 float gl = fminf(acc[m][n][j] + bgv[j], 7.f);
;                 float li = fminf(fmaxf(acc[m][n + 2][j] + blv[j], -7.f), 7.f);
;                 a[j] = gl * sigmoidf_(1.702f * gl) * (li + 1.f);
;               }
;               *reinterpret_cast<uint2*>(p.act + (size_t)(rowoff + i) * 1024 + acol) = make_uint2(pack2(a[0], a[1]), pack2(a[2], a[3]));
	v_add_f32_e32 v48, v48, v36
	v_min_f32_e32 v58, 0x40e00000, v48
	v_add_f32_e32 v48, v52, v40
	v_med3_f32 v60, v48, s2, v89
	v_mul_f32_e32 v48, 0x3fd9db23, v58
	v_mul_f32_e32 v48, 0xbfb8aa3b, v48
	v_exp_f32_e32 v62, v48
	v_add_f32_e32 v48, v49, v37
	v_min_f32_e32 v52, 0x40e00000, v48
	v_mul_f32_e32 v49, 0x3fd9db23, v52
	v_mul_f32_e32 v49, 0xbfb8aa3b, v49
	v_exp_f32_e32 v66, v49
	v_add_f32_e32 v49, v50, v38
	v_min_f32_e32 v59, 0x40e00000, v49
	v_add_f32_e32 v49, v54, v42
	v_med3_f32 v61, v49, s2, v89
	v_mul_f32_e32 v49, 0x3fd9db23, v59
	v_mul_f32_e32 v49, 0xbfb8aa3b, v49
	v_exp_f32_e32 v63, v49
	v_add_f32_e32 v49, v51, v39
	v_add_f32_e32 v48, v53, v41
	v_min_f32_e32 v53, 0x40e00000, v49
	v_add_f32_e32 v49, v55, v43
	v_pk_add_f32 v[54:55], v[62:63], 1.0 op_sel_hi:[1,0]
	v_mul_f32_e32 v50, 0x3fd9db23, v53
	v_div_scale_f32 v62, s[20:21], v55, v55, 1.0
	v_rcp_f32_e32 v63, v62
	v_mul_f32_e32 v50, 0xbfb8aa3b, v50
	v_exp_f32_e32 v67, v50
	v_med3_f32 v48, v48, s2, v89
	v_fma_f32 v68, -v62, v63, 1.0
	v_fmac_f32_e32 v63, v68, v63
	v_div_scale_f32 v68, vcc, 1.0, v55, 1.0
	v_mul_f32_e32 v69, v68, v63
	v_fma_f32 v70, -v62, v69, v68
	v_fmac_f32_e32 v69, v70, v63
	v_fma_f32 v62, -v62, v69, v68
	v_div_fmas_f32 v62, v62, v63, v69
	v_div_fixup_f32 v55, v62, v55, 1.0
	v_div_scale_f32 v62, s[20:21], v54, v54, 1.0
	v_rcp_f32_e32 v63, v62
	v_med3_f32 v49, v49, s2, v89
	v_pk_add_f32 v[48:49], v[48:49], 1.0 op_sel_hi:[1,0]
	v_readlane_b32 s72, v166, 7
	v_fma_f32 v68, -v62, v63, 1.0
	v_fmac_f32_e32 v63, v68, v63
	v_div_scale_f32 v68, vcc, 1.0, v54, 1.0
	v_mul_f32_e32 v69, v68, v63
	v_fma_f32 v70, -v62, v69, v68
	v_fmac_f32_e32 v69, v70, v63
	v_fma_f32 v62, -v62, v69, v68
	v_div_fmas_f32 v62, v62, v63, v69
	v_div_fixup_f32 v54, v62, v54, 1.0
	v_pk_mul_f32 v[54:55], v[58:59], v[54:55]
	v_pk_add_f32 v[58:59], v[60:61], 1.0 op_sel_hi:[1,0]
	v_lshlrev_b64 v[50:51], 11, v[56:57]
	v_pk_mul_f32 v[54:55], v[58:59], v[54:55]
	v_pk_add_f32 v[58:59], v[66:67], 1.0 op_sel_hi:[1,0]
	v_readlane_b32 s80, v166, 15
	v_div_scale_f32 v60, s[20:21], v59, v59, 1.0
	v_rcp_f32_e32 v61, v60
	v_readlane_b32 s81, v166, 16
	v_readlane_b32 s73, v166, 8
	v_readlane_b32 s74, v166, 9
	v_fma_f32 v62, -v60, v61, 1.0
	v_fmac_f32_e32 v61, v62, v61
	v_div_scale_f32 v62, vcc, 1.0, v59, 1.0
	v_mul_f32_e32 v63, v62, v61
	v_fma_f32 v66, -v60, v63, v62
	v_fmac_f32_e32 v63, v66, v61
	v_fma_f32 v60, -v60, v63, v62
	v_div_fmas_f32 v60, v60, v61, v63
	v_div_fixup_f32 v59, v60, v59, 1.0
	v_div_scale_f32 v60, s[20:21], v58, v58, 1.0
	v_rcp_f32_e32 v61, v60
	v_lshl_add_u64 v[50:51], s[80:81], 0, v[50:51]
	v_lshl_add_u64 v[50:51], v[74:75], 1, v[50:51]
	v_readlane_b32 s75, v166, 10
	v_fma_f32 v62, -v60, v61, 1.0
	v_fmac_f32_e32 v61, v62, v61
	v_div_scale_f32 v62, vcc, 1.0, v58, 1.0
	v_mul_f32_e32 v63, v62, v61
	v_fma_f32 v66, -v60, v63, v62
	v_fmac_f32_e32 v63, v66, v61
	v_fma_f32 v60, -v60, v63, v62
	v_div_fmas_f32 v60, v60, v61, v63
	v_div_fixup_f32 v58, v60, v58, 1.0
	v_pk_mul_f32 v[52:53], v[52:53], v[58:59]
	v_readlane_b32 s76, v166, 11
	v_pk_mul_f32 v[48:49], v[48:49], v[52:53]
	v_and_b32_sdwa v52, v55, v90 dst_sel:DWORD dst_unused:UNUSED_PAD src0_sel:WORD_1 src1_sel:DWORD
	v_and_b32_sdwa v53, v54, v90 dst_sel:DWORD dst_unused:UNUSED_PAD src0_sel:WORD_1 src1_sel:DWORD
	v_add3_u32 v53, v54, v53, s3
	v_add3_u32 v52, v55, v52, s3
	v_and_b32_sdwa v54, v49, v90 dst_sel:DWORD dst_unused:UNUSED_PAD src0_sel:WORD_1 src1_sel:DWORD
	v_and_b32_sdwa v55, v48, v90 dst_sel:DWORD dst_unused:UNUSED_PAD src0_sel:WORD_1 src1_sel:DWORD
	v_add3_u32 v49, v49, v54, s3
	v_add3_u32 v48, v48, v55, s3
	v_and_b32_e32 v49, 0xffff0000, v49
	v_and_b32_e32 v48, 0xffff0000, v48
	v_or_b32_sdwa v49, v49, v52 dst_sel:DWORD dst_unused:UNUSED_PAD src0_sel:DWORD src1_sel:WORD_1
	v_or_b32_sdwa v48, v48, v53 dst_sel:DWORD dst_unused:UNUSED_PAD src0_sel:DWORD src1_sel:WORD_1
	v_readlane_b32 s77, v166, 12
	v_readlane_b32 s78, v166, 13
	v_readlane_b32 s79, v166, 14
	v_readlane_b32 s82, v166, 17
	v_readlane_b32 s83, v166, 18
	v_readlane_b32 s84, v166, 19
	v_readlane_b32 s85, v166, 20
	v_readlane_b32 s86, v166, 21
	v_readlane_b32 s87, v166, 22
	global_store_dwordx2 v[50:51], v[48:49], off
; DEV unsigned pack2(float a, float b) { return (unsigned)f2bf(a) | ((unsigned)f2bf(b) << 16); }
; DEV float sigmoidf_(float x) { return 1.f / (1.f + __expf(-x)); }
; DEV void phase_moe1(const Params& p, int l, unsigned char* smem) {
;     ...
;         for (int n = 0; n < 2; ++n) {
;           const int acol = nt * 64 + wc * 32 + n * 16 + fq * 4;
;           const float4 bg4 = *reinterpret_cast<const float4*>(bgu + acol);
;           const float4 bl4 = *reinterpret_cast<const float4*>(bgu + 1024 + acol);
;           const float bgv[4] = {bg4.x, bg4.y, bg4.z, bg4.w}, blv[4] = {bl4.x, bl4.y, bl4.z, bl4.w};
; #pragma unroll
;           for (int m = 0; m < 4; ++m) {
;             const int i = mt * 128 + wr * 64 + m * 16 + fr;
;             if (i < cnt) {
;               float a[4];
; #pragma unroll
;               for (int j = 0; j < 4; ++j) {
;                 float gl = fminf(acc[m][n][j] + bgv[j], 7.f);
;                 float li = fminf(fmaxf(acc[m][n + 2][j] + blv[j], -7.f), 7.f);
;                 a[j] = gl * sigmoidf_(1.702f * gl) * (li + 1.f);
;               }
;               *reinterpret_cast<uint2*>(p.act + (size_t)(rowoff + i) * 1024 + acol) = make_uint2(pack2(a[0], a[1]), pack2(a[2], a[3]));
.LBB0_657:
	s_or_b64 exec, exec, s[10:11]
	v_or_b32_e32 v48, 48, v72
	v_cmp_lt_i32_e64 s[10:11], v48, v76
	v_add_u32_e32 v48, v48, v77
	v_ashrrev_i32_e32 v49, 31, v48
	s_and_saveexec_b64 s[20:21], s[10:11]
	s_cbranch_execz .LBB0_659
	v_add_f32_e32 v32, v32, v36
	v_min_f32_e32 v50, 0x40e00000, v32
	v_add_f32_e32 v32, v44, v40
	v_med3_f32 v40, v32, s2, v89
	v_mul_f32_e32 v32, 0x3fd9db23, v50
	v_mul_f32_e32 v32, 0xbfb8aa3b, v32
	v_exp_f32_e32 v44, v32
	v_add_f32_e32 v32, v33, v37
	v_min_f32_e32 v36, 0x40e00000, v32
	v_mul_f32_e32 v33, 0x3fd9db23, v36
	v_mul_f32_e32 v33, 0xbfb8aa3b, v33
	v_exp_f32_e32 v52, v33
	v_add_f32_e32 v33, v34, v38
	v_min_f32_e32 v51, 0x40e00000, v33
	v_add_f32_e32 v33, v46, v42
	v_add_f32_e32 v32, v45, v41
	v_med3_f32 v41, v33, s2, v89
	v_mul_f32_e32 v33, 0x3fd9db23, v51
	v_mul_f32_e32 v33, 0xbfb8aa3b, v33
	v_exp_f32_e32 v45, v33
	v_add_f32_e32 v33, v35, v39
	v_min_f32_e32 v37, 0x40e00000, v33
	v_add_f32_e32 v33, v47, v43
	v_pk_add_f32 v[38:39], v[44:45], 1.0 op_sel_hi:[1,0]
	v_mul_f32_e32 v34, 0x3fd9db23, v37
	v_div_scale_f32 v42, s[28:29], v39, v39, 1.0
	v_rcp_f32_e32 v43, v42
	v_mul_f32_e32 v34, 0xbfb8aa3b, v34
	v_exp_f32_e32 v53, v34
	v_pk_add_f32 v[40:41], v[40:41], 1.0 op_sel_hi:[1,0]
	v_fma_f32 v44, -v42, v43, 1.0
	v_fmac_f32_e32 v43, v44, v43
	v_div_scale_f32 v44, vcc, 1.0, v39, 1.0
	v_mul_f32_e32 v45, v44, v43
	v_fma_f32 v46, -v42, v45, v44
	v_fmac_f32_e32 v45, v46, v43
	v_fma_f32 v42, -v42, v45, v44
	v_div_fmas_f32 v42, v42, v43, v45
	v_div_fixup_f32 v39, v42, v39, 1.0
	v_div_scale_f32 v42, s[28:29], v38, v38, 1.0
	v_rcp_f32_e32 v43, v42
	v_med3_f32 v32, v32, s2, v89
	v_med3_f32 v33, v33, s2, v89
	v_pk_add_f32 v[32:33], v[32:33], 1.0 op_sel_hi:[1,0]
	v_fma_f32 v44, -v42, v43, 1.0
	v_fmac_f32_e32 v43, v44, v43
	v_div_scale_f32 v44, vcc, 1.0, v38, 1.0
	v_mul_f32_e32 v45, v44, v43
	v_fma_f32 v46, -v42, v45, v44
	v_fmac_f32_e32 v45, v46, v43
	v_fma_f32 v42, -v42, v45, v44
	v_div_fmas_f32 v42, v42, v43, v45
	v_div_fixup_f32 v38, v42, v38, 1.0
	v_pk_mul_f32 v[38:39], v[50:51], v[38:39]
	v_readlane_b32 s72, v166, 7
	v_pk_mul_f32 v[38:39], v[40:41], v[38:39]
	v_pk_add_f32 v[40:41], v[52:53], 1.0 op_sel_hi:[1,0]
	v_lshlrev_b64 v[34:35], 11, v[48:49]
	v_div_scale_f32 v42, s[28:29], v41, v41, 1.0
	v_rcp_f32_e32 v43, v42
	v_readlane_b32 s80, v166, 15
	v_readlane_b32 s81, v166, 16
	v_readlane_b32 s73, v166, 8
	v_fma_f32 v44, -v42, v43, 1.0
	v_fmac_f32_e32 v43, v44, v43
	v_div_scale_f32 v44, vcc, 1.0, v41, 1.0
	v_mul_f32_e32 v45, v44, v43
	v_fma_f32 v46, -v42, v45, v44
	v_fmac_f32_e32 v45, v46, v43
	v_fma_f32 v42, -v42, v45, v44
	v_div_fmas_f32 v42, v42, v43, v45
	v_div_fixup_f32 v41, v42, v41, 1.0
	v_div_scale_f32 v42, s[28:29], v40, v40, 1.0
	v_rcp_f32_e32 v43, v42
	v_lshl_add_u64 v[34:35], s[80:81], 0, v[34:35]
	v_lshl_add_u64 v[34:35], v[74:75], 1, v[34:35]
	v_readlane_b32 s74, v166, 9
	v_fma_f32 v44, -v42, v43, 1.0
	v_fmac_f32_e32 v43, v44, v43
	v_div_scale_f32 v44, vcc, 1.0, v40, 1.0
	v_mul_f32_e32 v45, v44, v43
	v_fma_f32 v46, -v42, v45, v44
	v_fmac_f32_e32 v45, v46, v43
	v_fma_f32 v42, -v42, v45, v44
	v_div_fmas_f32 v42, v42, v43, v45
	v_div_fixup_f32 v40, v42, v40, 1.0
	v_pk_mul_f32 v[36:37], v[36:37], v[40:41]
	v_readlane_b32 s75, v166, 10
	v_pk_mul_f32 v[32:33], v[32:33], v[36:37]
	v_and_b32_sdwa v36, v39, v90 dst_sel:DWORD dst_unused:UNUSED_PAD src0_sel:WORD_1 src1_sel:DWORD
	v_and_b32_sdwa v37, v38, v90 dst_sel:DWORD dst_unused:UNUSED_PAD src0_sel:WORD_1 src1_sel:DWORD
	v_add3_u32 v37, v38, v37, s3
	v_add3_u32 v36, v39, v36, s3
	v_and_b32_sdwa v38, v33, v90 dst_sel:DWORD dst_unused:UNUSED_PAD src0_sel:WORD_1 src1_sel:DWORD
	v_and_b32_sdwa v39, v32, v90 dst_sel:DWORD dst_unused:UNUSED_PAD src0_sel:WORD_1 src1_sel:DWORD
	v_add3_u32 v33, v33, v38, s3
	v_add3_u32 v32, v32, v39, s3
	v_and_b32_e32 v33, 0xffff0000, v33
	v_and_b32_e32 v32, 0xffff0000, v32
	v_or_b32_sdwa v33, v33, v36 dst_sel:DWORD dst_unused:UNUSED_PAD src0_sel:DWORD src1_sel:WORD_1
	v_or_b32_sdwa v32, v32, v37 dst_sel:DWORD dst_unused:UNUSED_PAD src0_sel:DWORD src1_sel:WORD_1
	v_readlane_b32 s76, v166, 11
	v_readlane_b32 s77, v166, 12
	v_readlane_b32 s78, v166, 13
	v_readlane_b32 s79, v166, 14
	v_readlane_b32 s82, v166, 17
	v_readlane_b32 s83, v166, 18
	v_readlane_b32 s84, v166, 19
	v_readlane_b32 s85, v166, 20
	v_readlane_b32 s86, v166, 21
	v_readlane_b32 s87, v166, 22
	global_store_dwordx2 v[34:35], v[32:33], off
.LBB0_659:
	s_or_b64 exec, exec, s[20:21]
	v_or_b32_e32 v32, 16, v74
	v_ashrrev_i32_e32 v33, 31, v32
	v_lshl_add_u64 v[32:33], v[32:33], 2, s[0:1]
	global_load_dwordx4 v[36:39], v[80:81], off offset:64
	s_nop 0
	global_load_dwordx4 v[32:35], v[32:33], off
	s_waitcnt vmcnt(0)
	s_and_saveexec_b64 s[0:1], s[4:5]
	s_cbranch_execnz .LBB0_663
	s_or_b64 exec, exec, s[0:1]
	s_and_saveexec_b64 s[0:1], s[6:7]
	s_cbranch_execnz .LBB0_664

; DEV unsigned pack2(float a, float b) { return (unsigned)f2bf(a) | ((unsigned)f2bf(b) << 16); }
; DEV float sigmoidf_(float x) { return 1.f / (1.f + __expf(-x)); }
; DEV void phase_moe1(const Params& p, int l, unsigned char* smem) {
;     ...
;             const int i = mt * 128 + wr * 64 + m * 16 + fr;
;             if (i < cnt) {
;               float a[4];
; #pragma unroll
;               for (int j = 0; j < 4; ++j) {
;                 float gl = fminf(acc[m][n][j] + bgv[j], 7.f);
;                 float li = fminf(fmaxf(acc[m][n + 2][j] + blv[j], -7.f), 7.f);
;                 a[j] = gl * sigmoidf_(1.702f * gl) * (li + 1.f);
;               }
;               *reinterpret_cast<uint2*>(p.act + (size_t)(rowoff + i) * 1024 + acol) = make_uint2(pack2(a[0], a[1]), pack2(a[2], a[3]));
.LBB0_663:
	v_add_f32_e32 v24, v24, v36
	v_min_f32_e32 v40, 0x40e00000, v24
	v_add_f32_e32 v24, v28, v32
	v_med3_f32 v42, v24, s2, v89
	v_mul_f32_e32 v24, 0x3fd9db23, v40
	v_mul_f32_e32 v24, 0xbfb8aa3b, v24
	v_exp_f32_e32 v44, v24
	v_add_f32_e32 v24, v25, v37
	v_min_f32_e32 v28, 0x40e00000, v24
	v_mul_f32_e32 v25, 0x3fd9db23, v28
	v_mul_f32_e32 v25, 0xbfb8aa3b, v25
	v_exp_f32_e32 v46, v25
	v_add_f32_e32 v25, v26, v38
	v_min_f32_e32 v41, 0x40e00000, v25
	v_add_f32_e32 v25, v30, v34
	v_med3_f32 v43, v25, s2, v89
	v_mul_f32_e32 v25, 0x3fd9db23, v41
	v_mul_f32_e32 v25, 0xbfb8aa3b, v25
	v_exp_f32_e32 v45, v25
	v_add_f32_e32 v25, v27, v39
	v_add_f32_e32 v24, v29, v33
	v_min_f32_e32 v29, 0x40e00000, v25
	v_add_f32_e32 v25, v31, v35
	v_pk_add_f32 v[30:31], v[44:45], 1.0 op_sel_hi:[1,0]
	v_mul_f32_e32 v26, 0x3fd9db23, v29
	v_div_scale_f32 v44, s[4:5], v31, v31, 1.0
	v_rcp_f32_e32 v45, v44
	v_mul_f32_e32 v26, 0xbfb8aa3b, v26
	v_exp_f32_e32 v47, v26
	v_med3_f32 v24, v24, s2, v89
	v_fma_f32 v50, -v44, v45, 1.0
	v_fmac_f32_e32 v45, v50, v45
	v_div_scale_f32 v50, vcc, 1.0, v31, 1.0
	v_mul_f32_e32 v51, v50, v45
	v_fma_f32 v52, -v44, v51, v50
	v_fmac_f32_e32 v51, v52, v45
	v_fma_f32 v44, -v44, v51, v50
	v_div_fmas_f32 v44, v44, v45, v51
	v_div_fixup_f32 v31, v44, v31, 1.0
	v_div_scale_f32 v44, s[4:5], v30, v30, 1.0
	v_rcp_f32_e32 v45, v44
	v_med3_f32 v25, v25, s2, v89
	v_pk_add_f32 v[24:25], v[24:25], 1.0 op_sel_hi:[1,0]
	v_readlane_b32 s72, v166, 7
	v_fma_f32 v50, -v44, v45, 1.0
	v_fmac_f32_e32 v45, v50, v45
	v_div_scale_f32 v50, vcc, 1.0, v30, 1.0
	v_mul_f32_e32 v51, v50, v45
	v_fma_f32 v52, -v44, v51, v50
	v_fmac_f32_e32 v51, v52, v45
	v_fma_f32 v44, -v44, v51, v50
	v_div_fmas_f32 v44, v44, v45, v51
	v_div_fixup_f32 v30, v44, v30, 1.0
	v_pk_mul_f32 v[30:31], v[40:41], v[30:31]
	v_pk_add_f32 v[40:41], v[42:43], 1.0 op_sel_hi:[1,0]
	v_lshlrev_b64 v[26:27], 11, v[78:79]
	v_pk_mul_f32 v[30:31], v[40:41], v[30:31]
	v_pk_add_f32 v[40:41], v[46:47], 1.0 op_sel_hi:[1,0]
	v_readlane_b32 s80, v166, 15
	v_div_scale_f32 v42, s[4:5], v41, v41, 1.0
	v_rcp_f32_e32 v43, v42
	v_readlane_b32 s81, v166, 16
	v_readlane_b32 s73, v166, 8
	v_readlane_b32 s74, v166, 9
	v_fma_f32 v44, -v42, v43, 1.0
	v_fmac_f32_e32 v43, v44, v43
	v_div_scale_f32 v44, vcc, 1.0, v41, 1.0
	v_mul_f32_e32 v45, v44, v43
	v_fma_f32 v46, -v42, v45, v44
	v_fmac_f32_e32 v45, v46, v43
	v_fma_f32 v42, -v42, v45, v44
	v_div_fmas_f32 v42, v42, v43, v45
	v_div_fixup_f32 v41, v42, v41, 1.0
	v_div_scale_f32 v42, s[4:5], v40, v40, 1.0
	v_rcp_f32_e32 v43, v42
	v_lshl_add_u64 v[26:27], s[80:81], 0, v[26:27]
	v_lshl_add_u64 v[26:27], v[74:75], 1, v[26:27]
	v_readlane_b32 s75, v166, 10
	v_fma_f32 v44, -v42, v43, 1.0
	v_fmac_f32_e32 v43, v44, v43
	v_div_scale_f32 v44, vcc, 1.0, v40, 1.0
	v_mul_f32_e32 v45, v44, v43
	v_fma_f32 v46, -v42, v45, v44
	v_fmac_f32_e32 v45, v46, v43
	v_fma_f32 v42, -v42, v45, v44
	v_div_fmas_f32 v42, v42, v43, v45
	v_div_fixup_f32 v40, v42, v40, 1.0
	v_pk_mul_f32 v[28:29], v[28:29], v[40:41]
	v_readlane_b32 s76, v166, 11
	v_pk_mul_f32 v[24:25], v[24:25], v[28:29]
	v_and_b32_sdwa v28, v31, v90 dst_sel:DWORD dst_unused:UNUSED_PAD src0_sel:WORD_1 src1_sel:DWORD
	v_and_b32_sdwa v29, v30, v90 dst_sel:DWORD dst_unused:UNUSED_PAD src0_sel:WORD_1 src1_sel:DWORD
	v_add3_u32 v29, v30, v29, s3
	v_add3_u32 v28, v31, v28, s3
	v_and_b32_sdwa v30, v25, v90 dst_sel:DWORD dst_unused:UNUSED_PAD src0_sel:WORD_1 src1_sel:DWORD
	v_and_b32_sdwa v31, v24, v90 dst_sel:DWORD dst_unused:UNUSED_PAD src0_sel:WORD_1 src1_sel:DWORD
	v_add3_u32 v25, v25, v30, s3
	v_add3_u32 v24, v24, v31, s3
	v_and_b32_e32 v25, 0xffff0000, v25
	v_and_b32_e32 v24, 0xffff0000, v24
	v_or_b32_sdwa v25, v25, v28 dst_sel:DWORD dst_unused:UNUSED_PAD src0_sel:DWORD src1_sel:WORD_1
	v_or_b32_sdwa v24, v24, v29 dst_sel:DWORD dst_unused:UNUSED_PAD src0_sel:DWORD src1_sel:WORD_1
	v_readlane_b32 s77, v166, 12
	v_readlane_b32 s78, v166, 13
	v_readlane_b32 s79, v166, 14
	v_readlane_b32 s82, v166, 17
	v_readlane_b32 s83, v166, 18
	v_readlane_b32 s84, v166, 19
	v_readlane_b32 s85, v166, 20
	v_readlane_b32 s86, v166, 21
	v_readlane_b32 s87, v166, 22
	global_store_dwordx2 v[26:27], v[24:25], off offset:32
	s_or_b64 exec, exec, s[0:1]
	s_and_saveexec_b64 s[0:1], s[6:7]
	s_cbranch_execz .LBB0_661
; DEV unsigned pack2(float a, float b) { return (unsigned)f2bf(a) | ((unsigned)f2bf(b) << 16); }
; DEV float sigmoidf_(float x) { return 1.f / (1.f + __expf(-x)); }
; DEV void phase_moe1(const Params& p, int l, unsigned char* smem) {
;     ...
;             const int i = mt * 128 + wr * 64 + m * 16 + fr;
;             if (i < cnt) {
;               float a[4];
; #pragma unroll
;               for (int j = 0; j < 4; ++j) {
;                 float gl = fminf(acc[m][n][j] + bgv[j], 7.f);
;                 float li = fminf(fmaxf(acc[m][n + 2][j] + blv[j], -7.f), 7.f);
;                 a[j] = gl * sigmoidf_(1.702f * gl) * (li + 1.f);
;               }
;               *reinterpret_cast<uint2*>(p.act + (size_t)(rowoff + i) * 1024 + acol) = make_uint2(pack2(a[0], a[1]), pack2(a[2], a[3]));
.LBB0_664:
	v_add_f32_e32 v16, v16, v36
	v_min_f32_e32 v24, 0x40e00000, v16
	v_add_f32_e32 v16, v20, v32
	v_med3_f32 v26, v16, s2, v89
	v_mul_f32_e32 v16, 0x3fd9db23, v24
	v_mul_f32_e32 v16, 0xbfb8aa3b, v16
	v_exp_f32_e32 v28, v16
	v_add_f32_e32 v16, v17, v37
	v_min_f32_e32 v20, 0x40e00000, v16
	v_mul_f32_e32 v17, 0x3fd9db23, v20
	v_mul_f32_e32 v17, 0xbfb8aa3b, v17
	v_exp_f32_e32 v30, v17
	v_add_f32_e32 v17, v18, v38
	v_min_f32_e32 v25, 0x40e00000, v17
	v_add_f32_e32 v17, v22, v34
	v_med3_f32 v27, v17, s2, v89
	v_mul_f32_e32 v17, 0x3fd9db23, v25
	v_mul_f32_e32 v17, 0xbfb8aa3b, v17
	v_exp_f32_e32 v29, v17
	v_add_f32_e32 v17, v19, v39
	v_add_f32_e32 v16, v21, v33
	v_min_f32_e32 v21, 0x40e00000, v17
	v_add_f32_e32 v17, v23, v35
	v_pk_add_f32 v[22:23], v[28:29], 1.0 op_sel_hi:[1,0]
	v_mul_f32_e32 v18, 0x3fd9db23, v21
	v_div_scale_f32 v28, s[4:5], v23, v23, 1.0
	v_rcp_f32_e32 v29, v28
	v_mul_f32_e32 v18, 0xbfb8aa3b, v18
	v_exp_f32_e32 v31, v18
	v_med3_f32 v16, v16, s2, v89
	v_fma_f32 v40, -v28, v29, 1.0
	v_fmac_f32_e32 v29, v40, v29
	v_div_scale_f32 v40, vcc, 1.0, v23, 1.0
	v_mul_f32_e32 v41, v40, v29
	v_fma_f32 v42, -v28, v41, v40
	v_fmac_f32_e32 v41, v42, v29
	v_fma_f32 v28, -v28, v41, v40
	v_div_fmas_f32 v28, v28, v29, v41
	v_div_fixup_f32 v23, v28, v23, 1.0
	v_div_scale_f32 v28, s[4:5], v22, v22, 1.0
	v_rcp_f32_e32 v29, v28
	v_med3_f32 v17, v17, s2, v89
	v_pk_add_f32 v[16:17], v[16:17], 1.0 op_sel_hi:[1,0]
	v_readlane_b32 s72, v166, 7
	v_fma_f32 v40, -v28, v29, 1.0
	v_fmac_f32_e32 v29, v40, v29
	v_div_scale_f32 v40, vcc, 1.0, v22, 1.0
	v_mul_f32_e32 v41, v40, v29
	v_fma_f32 v42, -v28, v41, v40
	v_fmac_f32_e32 v41, v42, v29
	v_fma_f32 v28, -v28, v41, v40
	v_div_fmas_f32 v28, v28, v29, v41
	v_div_fixup_f32 v22, v28, v22, 1.0
	v_pk_mul_f32 v[22:23], v[24:25], v[22:23]
	v_pk_add_f32 v[24:25], v[26:27], 1.0 op_sel_hi:[1,0]
	v_lshlrev_b64 v[18:19], 11, v[64:65]
	v_pk_mul_f32 v[22:23], v[24:25], v[22:23]
	v_pk_add_f32 v[24:25], v[30:31], 1.0 op_sel_hi:[1,0]
	v_readlane_b32 s80, v166, 15
	v_div_scale_f32 v26, s[4:5], v25, v25, 1.0
	v_rcp_f32_e32 v27, v26
	v_readlane_b32 s81, v166, 16
	v_readlane_b32 s73, v166, 8
	v_readlane_b32 s74, v166, 9
	v_fma_f32 v28, -v26, v27, 1.0
	v_fmac_f32_e32 v27, v28, v27
	v_div_scale_f32 v28, vcc, 1.0, v25, 1.0
	v_mul_f32_e32 v29, v28, v27
	v_fma_f32 v30, -v26, v29, v28
	v_fmac_f32_e32 v29, v30, v27
	v_fma_f32 v26, -v26, v29, v28
	v_div_fmas_f32 v26, v26, v27, v29
	v_div_fixup_f32 v25, v26, v25, 1.0
	v_div_scale_f32 v26, s[4:5], v24, v24, 1.0
	v_rcp_f32_e32 v27, v26
	v_lshl_add_u64 v[18:19], s[80:81], 0, v[18:19]
	v_lshl_add_u64 v[18:19], v[74:75], 1, v[18:19]
	v_readlane_b32 s75, v166, 10
	v_fma_f32 v28, -v26, v27, 1.0
	v_fmac_f32_e32 v27, v28, v27
	v_div_scale_f32 v28, vcc, 1.0, v24, 1.0
	v_mul_f32_e32 v29, v28, v27
	v_fma_f32 v30, -v26, v29, v28
	v_fmac_f32_e32 v29, v30, v27
	v_fma_f32 v26, -v26, v29, v28
	v_div_fmas_f32 v26, v26, v27, v29
	v_div_fixup_f32 v24, v26, v24, 1.0
	v_pk_mul_f32 v[20:21], v[20:21], v[24:25]
	v_readlane_b32 s76, v166, 11
	v_pk_mul_f32 v[16:17], v[16:17], v[20:21]
	v_and_b32_sdwa v20, v23, v90 dst_sel:DWORD dst_unused:UNUSED_PAD src0_sel:WORD_1 src1_sel:DWORD
	v_and_b32_sdwa v21, v22, v90 dst_sel:DWORD dst_unused:UNUSED_PAD src0_sel:WORD_1 src1_sel:DWORD
	v_add3_u32 v21, v22, v21, s3
	v_add3_u32 v20, v23, v20, s3
	v_and_b32_sdwa v22, v17, v90 dst_sel:DWORD dst_unused:UNUSED_PAD src0_sel:WORD_1 src1_sel:DWORD
	v_and_b32_sdwa v23, v16, v90 dst_sel:DWORD dst_unused:UNUSED_PAD src0_sel:WORD_1 src1_sel:DWORD
	v_add3_u32 v17, v17, v22, s3
	v_add3_u32 v16, v16, v23, s3
	v_and_b32_e32 v17, 0xffff0000, v17
	v_and_b32_e32 v16, 0xffff0000, v16
	v_or_b32_sdwa v17, v17, v20 dst_sel:DWORD dst_unused:UNUSED_PAD src0_sel:DWORD src1_sel:WORD_1
	v_or_b32_sdwa v16, v16, v21 dst_sel:DWORD dst_unused:UNUSED_PAD src0_sel:DWORD src1_sel:WORD_1
	v_readlane_b32 s77, v166, 12
	v_readlane_b32 s78, v166, 13
	v_readlane_b32 s79, v166, 14
	v_readlane_b32 s82, v166, 17
	v_readlane_b32 s83, v166, 18
	v_readlane_b32 s84, v166, 19
	v_readlane_b32 s85, v166, 20
	v_readlane_b32 s86, v166, 21
	v_readlane_b32 s87, v166, 22
	global_store_dwordx2 v[18:19], v[16:17], off offset:32
	s_or_b64 exec, exec, s[0:1]
	s_and_saveexec_b64 s[0:1], s[8:9]
	s_cbranch_execz .LBB0_662
; DEV unsigned pack2(float a, float b) { return (unsigned)f2bf(a) | ((unsigned)f2bf(b) << 16); }
; DEV float sigmoidf_(float x) { return 1.f / (1.f + __expf(-x)); }
; DEV void phase_moe1(const Params& p, int l, unsigned char* smem) {
;     ...
;             const int i = mt * 128 + wr * 64 + m * 16 + fr;
;             if (i < cnt) {
;               float a[4];
; #pragma unroll
;               for (int j = 0; j < 4; ++j) {
;                 float gl = fminf(acc[m][n][j] + bgv[j], 7.f);
;                 float li = fminf(fmaxf(acc[m][n + 2][j] + blv[j], -7.f), 7.f);
;                 a[j] = gl * sigmoidf_(1.702f * gl) * (li + 1.f);
;               }
;               *reinterpret_cast<uint2*>(p.act + (size_t)(rowoff + i) * 1024 + acol) = make_uint2(pack2(a[0], a[1]), pack2(a[2], a[3]));
.LBB0_665:
	v_add_f32_e32 v8, v8, v36
	v_min_f32_e32 v16, 0x40e00000, v8
	v_add_f32_e32 v8, v12, v32
	v_med3_f32 v18, v8, s2, v89
	v_mul_f32_e32 v8, 0x3fd9db23, v16
	v_mul_f32_e32 v8, 0xbfb8aa3b, v8
	v_exp_f32_e32 v20, v8
	v_add_f32_e32 v8, v9, v37
	v_min_f32_e32 v12, 0x40e00000, v8
	v_mul_f32_e32 v9, 0x3fd9db23, v12
	v_mul_f32_e32 v9, 0xbfb8aa3b, v9
	v_exp_f32_e32 v22, v9
	v_add_f32_e32 v9, v10, v38
	v_min_f32_e32 v17, 0x40e00000, v9
	v_add_f32_e32 v9, v14, v34
	v_med3_f32 v19, v9, s2, v89
	v_mul_f32_e32 v9, 0x3fd9db23, v17
	v_mul_f32_e32 v9, 0xbfb8aa3b, v9
	v_exp_f32_e32 v21, v9
	v_add_f32_e32 v9, v11, v39
	v_add_f32_e32 v8, v13, v33
	v_min_f32_e32 v13, 0x40e00000, v9
	v_add_f32_e32 v9, v15, v35
	v_pk_add_f32 v[14:15], v[20:21], 1.0 op_sel_hi:[1,0]
	v_mul_f32_e32 v10, 0x3fd9db23, v13
	v_div_scale_f32 v20, s[4:5], v15, v15, 1.0
	v_rcp_f32_e32 v21, v20
	v_mul_f32_e32 v10, 0xbfb8aa3b, v10
	v_exp_f32_e32 v23, v10
	v_med3_f32 v8, v8, s2, v89
	v_fma_f32 v24, -v20, v21, 1.0
	v_fmac_f32_e32 v21, v24, v21
	v_div_scale_f32 v24, vcc, 1.0, v15, 1.0
	v_mul_f32_e32 v25, v24, v21
	v_fma_f32 v26, -v20, v25, v24
	v_fmac_f32_e32 v25, v26, v21
	v_fma_f32 v20, -v20, v25, v24
	v_div_fmas_f32 v20, v20, v21, v25
	v_div_fixup_f32 v15, v20, v15, 1.0
	v_div_scale_f32 v20, s[4:5], v14, v14, 1.0
	v_rcp_f32_e32 v21, v20
	v_med3_f32 v9, v9, s2, v89
	v_pk_add_f32 v[8:9], v[8:9], 1.0 op_sel_hi:[1,0]
	v_readlane_b32 s72, v166, 7
	v_fma_f32 v24, -v20, v21, 1.0
	v_fmac_f32_e32 v21, v24, v21
	v_div_scale_f32 v24, vcc, 1.0, v14, 1.0
	v_mul_f32_e32 v25, v24, v21
	v_fma_f32 v26, -v20, v25, v24
	v_fmac_f32_e32 v25, v26, v21
	v_fma_f32 v20, -v20, v25, v24
	v_div_fmas_f32 v20, v20, v21, v25
	v_div_fixup_f32 v14, v20, v14, 1.0
	v_pk_mul_f32 v[14:15], v[16:17], v[14:15]
	v_pk_add_f32 v[16:17], v[18:19], 1.0 op_sel_hi:[1,0]
	v_lshlrev_b64 v[10:11], 11, v[56:57]
	v_pk_mul_f32 v[14:15], v[16:17], v[14:15]
	v_pk_add_f32 v[16:17], v[22:23], 1.0 op_sel_hi:[1,0]
	v_readlane_b32 s80, v166, 15
	v_div_scale_f32 v18, s[4:5], v17, v17, 1.0
	v_rcp_f32_e32 v19, v18
	v_readlane_b32 s81, v166, 16
	v_readlane_b32 s73, v166, 8
	v_readlane_b32 s74, v166, 9
	v_fma_f32 v20, -v18, v19, 1.0
	v_fmac_f32_e32 v19, v20, v19
	v_div_scale_f32 v20, vcc, 1.0, v17, 1.0
	v_mul_f32_e32 v21, v20, v19
	v_fma_f32 v22, -v18, v21, v20
	v_fmac_f32_e32 v21, v22, v19
	v_fma_f32 v18, -v18, v21, v20
	v_div_fmas_f32 v18, v18, v19, v21
	v_div_fixup_f32 v17, v18, v17, 1.0
	v_div_scale_f32 v18, s[4:5], v16, v16, 1.0
	v_rcp_f32_e32 v19, v18
	v_lshl_add_u64 v[10:11], s[80:81], 0, v[10:11]
	v_lshl_add_u64 v[10:11], v[74:75], 1, v[10:11]
	v_readlane_b32 s75, v166, 10
	v_fma_f32 v20, -v18, v19, 1.0
	v_fmac_f32_e32 v19, v20, v19
	v_div_scale_f32 v20, vcc, 1.0, v16, 1.0
	v_mul_f32_e32 v21, v20, v19
	v_fma_f32 v22, -v18, v21, v20
	v_fmac_f32_e32 v21, v22, v19
	v_fma_f32 v18, -v18, v21, v20
	v_div_fmas_f32 v18, v18, v19, v21
	v_div_fixup_f32 v16, v18, v16, 1.0
	v_pk_mul_f32 v[12:13], v[12:13], v[16:17]
	v_readlane_b32 s76, v166, 11
	v_pk_mul_f32 v[8:9], v[8:9], v[12:13]
	v_and_b32_sdwa v12, v15, v90 dst_sel:DWORD dst_unused:UNUSED_PAD src0_sel:WORD_1 src1_sel:DWORD
	v_and_b32_sdwa v13, v14, v90 dst_sel:DWORD dst_unused:UNUSED_PAD src0_sel:WORD_1 src1_sel:DWORD
	v_add3_u32 v13, v14, v13, s3
	v_add3_u32 v12, v15, v12, s3
	v_and_b32_sdwa v14, v9, v90 dst_sel:DWORD dst_unused:UNUSED_PAD src0_sel:WORD_1 src1_sel:DWORD
	v_and_b32_sdwa v15, v8, v90 dst_sel:DWORD dst_unused:UNUSED_PAD src0_sel:WORD_1 src1_sel:DWORD
	v_add3_u32 v9, v9, v14, s3
	v_add3_u32 v8, v8, v15, s3
	v_and_b32_e32 v9, 0xffff0000, v9
	v_and_b32_e32 v8, 0xffff0000, v8
	v_or_b32_sdwa v9, v9, v12 dst_sel:DWORD dst_unused:UNUSED_PAD src0_sel:DWORD src1_sel:WORD_1
	v_or_b32_sdwa v8, v8, v13 dst_sel:DWORD dst_unused:UNUSED_PAD src0_sel:DWORD src1_sel:WORD_1
	v_readlane_b32 s77, v166, 12
	v_readlane_b32 s78, v166, 13
	v_readlane_b32 s79, v166, 14
	v_readlane_b32 s82, v166, 17
	v_readlane_b32 s83, v166, 18
	v_readlane_b32 s84, v166, 19
	v_readlane_b32 s85, v166, 20
	v_readlane_b32 s86, v166, 21
	v_readlane_b32 s87, v166, 22
	global_store_dwordx2 v[10:11], v[8:9], off offset:32
	s_or_b64 exec, exec, s[0:1]
	s_and_saveexec_b64 s[0:1], s[10:11]
	s_cbranch_execz .LBB0_646
; DEV unsigned pack2(float a, float b) { return (unsigned)f2bf(a) | ((unsigned)f2bf(b) << 16); }
; DEV float sigmoidf_(float x) { return 1.f / (1.f + __expf(-x)); }
; DEV void phase_moe1(const Params& p, int l, unsigned char* smem) {
;     ...
;             const int i = mt * 128 + wr * 64 + m * 16 + fr;
;             if (i < cnt) {
;               float a[4];
; #pragma unroll
;               for (int j = 0; j < 4; ++j) {
;                 float gl = fminf(acc[m][n][j] + bgv[j], 7.f);
;                 float li = fminf(fmaxf(acc[m][n + 2][j] + blv[j], -7.f), 7.f);
;                 a[j] = gl * sigmoidf_(1.702f * gl) * (li + 1.f);
;               }
;               *reinterpret_cast<uint2*>(p.act + (size_t)(rowoff + i) * 1024 + acol) = make_uint2(pack2(a[0], a[1]), pack2(a[2], a[3]));
.LBB0_666:
	v_add_f32_e32 v0, v0, v36
	v_min_f32_e32 v8, 0x40e00000, v0
	v_add_f32_e32 v0, v4, v32
	v_med3_f32 v10, v0, s2, v89
	v_mul_f32_e32 v0, 0x3fd9db23, v8
	v_mul_f32_e32 v0, 0xbfb8aa3b, v0
	v_exp_f32_e32 v12, v0
	v_add_f32_e32 v0, v1, v37
	v_min_f32_e32 v4, 0x40e00000, v0
	v_mul_f32_e32 v1, 0x3fd9db23, v4
	v_mul_f32_e32 v1, 0xbfb8aa3b, v1
	v_exp_f32_e32 v14, v1
	v_add_f32_e32 v1, v2, v38
	v_min_f32_e32 v9, 0x40e00000, v1
	v_add_f32_e32 v1, v6, v34
	v_med3_f32 v11, v1, s2, v89
	v_mul_f32_e32 v1, 0x3fd9db23, v9
	v_mul_f32_e32 v1, 0xbfb8aa3b, v1
	v_exp_f32_e32 v13, v1
	v_add_f32_e32 v1, v3, v39
	v_add_f32_e32 v0, v5, v33
	v_min_f32_e32 v5, 0x40e00000, v1
	v_add_f32_e32 v1, v7, v35
	v_pk_add_f32 v[6:7], v[12:13], 1.0 op_sel_hi:[1,0]
	v_mul_f32_e32 v2, 0x3fd9db23, v5
	v_div_scale_f32 v12, s[4:5], v7, v7, 1.0
	v_rcp_f32_e32 v13, v12
	v_mul_f32_e32 v2, 0xbfb8aa3b, v2
	v_exp_f32_e32 v15, v2
	v_med3_f32 v0, v0, s2, v89
	v_fma_f32 v16, -v12, v13, 1.0
	v_fmac_f32_e32 v13, v16, v13
	v_div_scale_f32 v16, vcc, 1.0, v7, 1.0
	v_mul_f32_e32 v17, v16, v13
	v_fma_f32 v18, -v12, v17, v16
	v_fmac_f32_e32 v17, v18, v13
	v_fma_f32 v12, -v12, v17, v16
	v_div_fmas_f32 v12, v12, v13, v17
	v_div_fixup_f32 v7, v12, v7, 1.0
	v_div_scale_f32 v12, s[4:5], v6, v6, 1.0
	v_rcp_f32_e32 v13, v12
	v_med3_f32 v1, v1, s2, v89
	v_pk_add_f32 v[0:1], v[0:1], 1.0 op_sel_hi:[1,0]
	v_readlane_b32 s72, v166, 7
	v_fma_f32 v16, -v12, v13, 1.0
	v_fmac_f32_e32 v13, v16, v13
	v_div_scale_f32 v16, vcc, 1.0, v6, 1.0
	v_mul_f32_e32 v17, v16, v13
	v_fma_f32 v18, -v12, v17, v16
	v_fmac_f32_e32 v17, v18, v13
	v_fma_f32 v12, -v12, v17, v16
	v_div_fmas_f32 v12, v12, v13, v17
	v_div_fixup_f32 v6, v12, v6, 1.0
	v_pk_mul_f32 v[6:7], v[8:9], v[6:7]
	v_pk_add_f32 v[8:9], v[10:11], 1.0 op_sel_hi:[1,0]
	v_lshlrev_b64 v[2:3], 11, v[48:49]
	v_pk_mul_f32 v[6:7], v[8:9], v[6:7]
	v_pk_add_f32 v[8:9], v[14:15], 1.0 op_sel_hi:[1,0]
	v_readlane_b32 s80, v166, 15
	v_div_scale_f32 v10, s[4:5], v9, v9, 1.0
	v_rcp_f32_e32 v11, v10
	v_readlane_b32 s81, v166, 16
	v_readlane_b32 s73, v166, 8
	v_readlane_b32 s74, v166, 9
	v_fma_f32 v12, -v10, v11, 1.0
	v_fmac_f32_e32 v11, v12, v11
	v_div_scale_f32 v12, vcc, 1.0, v9, 1.0
	v_mul_f32_e32 v13, v12, v11
	v_fma_f32 v14, -v10, v13, v12
	v_fmac_f32_e32 v13, v14, v11
	v_fma_f32 v10, -v10, v13, v12
	v_div_fmas_f32 v10, v10, v11, v13
	v_div_fixup_f32 v9, v10, v9, 1.0
	v_div_scale_f32 v10, s[4:5], v8, v8, 1.0
	v_rcp_f32_e32 v11, v10
	v_lshl_add_u64 v[2:3], s[80:81], 0, v[2:3]
	v_lshl_add_u64 v[2:3], v[74:75], 1, v[2:3]
	v_readlane_b32 s75, v166, 10
	v_fma_f32 v12, -v10, v11, 1.0
	v_fmac_f32_e32 v11, v12, v11
	v_div_scale_f32 v12, vcc, 1.0, v8, 1.0
	v_mul_f32_e32 v13, v12, v11
	v_fma_f32 v14, -v10, v13, v12
	v_fmac_f32_e32 v13, v14, v11
	v_fma_f32 v10, -v10, v13, v12
	v_div_fmas_f32 v10, v10, v11, v13
	v_div_fixup_f32 v8, v10, v8, 1.0
	v_pk_mul_f32 v[4:5], v[4:5], v[8:9]
	v_readlane_b32 s76, v166, 11
	v_pk_mul_f32 v[0:1], v[0:1], v[4:5]
	v_and_b32_sdwa v4, v7, v90 dst_sel:DWORD dst_unused:UNUSED_PAD src0_sel:WORD_1 src1_sel:DWORD
	v_and_b32_sdwa v5, v6, v90 dst_sel:DWORD dst_unused:UNUSED_PAD src0_sel:WORD_1 src1_sel:DWORD
	v_add3_u32 v5, v6, v5, s3
	v_add3_u32 v4, v7, v4, s3
	v_and_b32_sdwa v6, v1, v90 dst_sel:DWORD dst_unused:UNUSED_PAD src0_sel:WORD_1 src1_sel:DWORD
	v_and_b32_sdwa v7, v0, v90 dst_sel:DWORD dst_unused:UNUSED_PAD src0_sel:WORD_1 src1_sel:DWORD
	v_add3_u32 v1, v1, v6, s3
	v_add3_u32 v0, v0, v7, s3
	v_and_b32_e32 v1, 0xffff0000, v1
	v_and_b32_e32 v0, 0xffff0000, v0
	v_or_b32_sdwa v1, v1, v4 dst_sel:DWORD dst_unused:UNUSED_PAD src0_sel:DWORD src1_sel:WORD_1
	v_or_b32_sdwa v0, v0, v5 dst_sel:DWORD dst_unused:UNUSED_PAD src0_sel:DWORD src1_sel:WORD_1
	v_readlane_b32 s77, v166, 12
	v_readlane_b32 s78, v166, 13
	v_readlane_b32 s79, v166, 14
	v_readlane_b32 s82, v166, 17
	v_readlane_b32 s83, v166, 18
	v_readlane_b32 s84, v166, 19
	v_readlane_b32 s85, v166, 20
	v_readlane_b32 s86, v166, 21
	v_readlane_b32 s87, v166, 22
	global_store_dwordx2 v[2:3], v[0:1], off offset:32
	s_branch .LBB0_646

; template <bool SWAP, class RowA, class Epi>
; DEV void gemm_tile(unsigned char* smem, RowA rowA, const bf16_t* Bt, int K, Epi epi) {
;     ...
;   for (int t = 0; t < nk; ++t) {
;     asm volatile("s_waitcnt vmcnt(0)" ::: "memory");
;     __syncthreads();
;     if (t + 1 < nk) stage(t + 1, (t + 1) & 1);
;     const unsigned char* SA = smem + (t & 1) * 16384;
;     const unsigned char* SB = SA + 8192;
;     bf16x8 At[4], Bl[4];
; #pragma unroll
;     for (int m = 0; m < 4; ++m) At[m] = *reinterpret_cast<const bf16x8*>(SA + (wr * 64 + m * 16) * 64 + rdoff);
; #pragma unroll
;     for (int n = 0; n < 4; ++n) Bl[n] = *reinterpret_cast<const bf16x8*>(SB + (wc * 64 + n * 16) * 64 + rdoff);
; #pragma unroll
;     for (int m = 0; m < 4; ++m)
; #pragma unroll
;       for (int n = 0; n < 4; ++n)
;         acc[m][n] = SWAP ? __builtin_amdgcn_mfma_f32_16x16x32_bf16(Bl[n], At[m], acc[m][n], 0, 0, 0)
;                          : __builtin_amdgcn_mfma_f32_16x16x32_bf16(At[m], Bl[n], acc[m][n], 0, 0, 0);
;   }
; DEV void phase_moe2(const Params& p, int l, unsigned char* smem) {
;     ...
; #pragma unroll
;         for (int n = 0; n < 4; ++n) {
;           const int col = nt * 128 + wc * 64 + n * 16 + fq * 4;
;           const float4 b4 = *reinterpret_cast<const float4*>(bd + col);
; #pragma unroll
;           for (int m = 0; m < 4; ++m) {
;             const int i = mt * 128 + wr * 64 + m * 16 + fr;
;             if (i < cnt) {
;               const float g = gl[i];
.LBB0_719:
	s_add_i32 s9, s5, 0x4000
	s_and_b32 s16, s9, 0x4000
	v_add_u32_e32 v68, s16, v78
	v_lshl_add_u64 v[90:91], v[64:65], 0, s[6:7]
	v_readfirstlane_b32 s16, v68
	v_lshl_add_u64 v[92:93], v[90:91], 0, 64
	s_mov_b32 m0, s16
	s_waitcnt vmcnt(0)
	s_waitcnt lgkmcnt(0)
	s_barrier
	global_load_lds_dwordx4 v[92:93], off
	s_mov_b64 s[16:17], 0x20040
	v_add_u32_e32 v92, 0x1000, v68
	v_lshl_add_u64 v[90:91], v[90:91], 0, s[16:17]
	v_readfirstlane_b32 s16, v92
	s_mov_b32 m0, s16
	s_mov_b32 s16, 0xffe00040
	v_add_u32_e32 v89, 0x2000, v68
	global_load_lds_dwordx4 v[90:91], off
	v_lshl_add_u64 v[90:91], v[66:67], 0, s[6:7]
	s_mov_b32 s17, -1
	v_lshl_add_u64 v[92:93], v[90:91], 0, s[16:17]
	v_readfirstlane_b32 s16, v89
	s_mov_b32 m0, s16
	s_mov_b32 s16, 0xffe20040
	s_mov_b32 s17, -1
	v_add_u32_e32 v68, 0x3000, v68
	v_lshl_add_u64 v[90:91], v[90:91], 0, s[16:17]
	v_readfirstlane_b32 s16, v68
	global_load_lds_dwordx4 v[92:93], off
	s_mov_b32 m0, s16
	s_and_b32 s5, s5, 0x4000
	global_load_lds_dwordx4 v[90:91], off
	v_or_b32_e32 v68, s5, v76
	v_add_u32_e32 v89, v68, v77
	v_add_u32_e32 v68, v68, v79
	ds_read_b128 v[90:93], v89
	ds_read_b128 v[94:97], v89 offset:1024
	ds_read_b128 v[98:101], v89 offset:2048
	ds_read_b128 v[102:105], v89 offset:3072
	ds_read_b128 v[106:109], v68 offset:8192
	ds_read_b128 v[110:113], v68 offset:9216
	ds_read_b128 v[114:117], v68 offset:10240
	ds_read_b128 v[118:121], v68 offset:11264
	s_waitcnt lgkmcnt(0)
	v_mfma_f32_16x16x32_bf16 v[60:63], v[106:109], v[90:93], v[60:63]
	s_add_u32 s6, s6, 64
	s_addc_u32 s7, s7, 0
	s_cmpk_eq_i32 s6, 0x7c0
	v_mfma_f32_16x16x32_bf16 v[56:59], v[110:113], v[90:93], v[56:59]
	s_mov_b32 s5, s9
	v_mfma_f32_16x16x32_bf16 v[28:31], v[114:117], v[90:93], v[28:31]
	v_mfma_f32_16x16x32_bf16 v[12:15], v[118:121], v[90:93], v[12:15]
	v_mfma_f32_16x16x32_bf16 v[52:55], v[106:109], v[94:97], v[52:55]
	v_mfma_f32_16x16x32_bf16 v[48:51], v[110:113], v[94:97], v[48:51]
	v_mfma_f32_16x16x32_bf16 v[24:27], v[114:117], v[94:97], v[24:27]
	v_mfma_f32_16x16x32_bf16 v[8:11], v[118:121], v[94:97], v[8:11]
	v_mfma_f32_16x16x32_bf16 v[44:47], v[106:109], v[98:101], v[44:47]
	v_mfma_f32_16x16x32_bf16 v[36:39], v[110:113], v[98:101], v[36:39]
	v_mfma_f32_16x16x32_bf16 v[20:23], v[114:117], v[98:101], v[20:23]
	v_mfma_f32_16x16x32_bf16 v[4:7], v[118:121], v[98:101], v[4:7]
	v_mfma_f32_16x16x32_bf16 v[40:43], v[106:109], v[102:105], v[40:43]
	v_mfma_f32_16x16x32_bf16 v[32:35], v[110:113], v[102:105], v[32:35]
	v_mfma_f32_16x16x32_bf16 v[16:19], v[114:117], v[102:105], v[16:19]
	v_mfma_f32_16x16x32_bf16 v[0:3], v[118:121], v[102:105], v[0:3]
	s_cbranch_scc0 .LBB0_719
	v_add_u32_e32 v68, v76, v79
	s_waitcnt vmcnt(0)
	s_waitcnt vmcnt(0)
	s_barrier
	ds_read_b128 v[90:93], v68 offset:24576
	v_add_u32_e32 v89, v76, v77
	ds_read_b128 v[94:97], v68 offset:25600
	ds_read_b128 v[76:79], v89 offset:16384
	ds_read_b128 v[98:101], v89 offset:17408
	ds_read_b128 v[102:105], v68 offset:26624
	ds_read_b128 v[106:109], v68 offset:27648
	s_waitcnt lgkmcnt(3)
	v_mfma_f32_16x16x32_bf16 v[64:67], v[90:93], v[76:79], v[60:63]
	v_readlane_b32 s72, v165, 7
	v_readlane_b32 s73, v165, 8
	s_lshl_b64 s[0:1], s[0:1], 2
	s_waitcnt lgkmcnt(2)
	v_mfma_f32_16x16x32_bf16 v[60:63], v[90:93], v[98:101], v[52:55]
	v_readlane_b32 s74, v165, 9
	v_readlane_b32 s75, v165, 10
	v_readlane_b32 s76, v165, 11
	v_mfma_f32_16x16x32_bf16 v[48:51], v[94:97], v[98:101], v[48:51]
	v_readlane_b32 s77, v165, 12
	s_mov_b64 s[60:61], s[72:73]
	s_add_u32 s0, s60, s0
	s_waitcnt lgkmcnt(1)
	v_mfma_f32_16x16x32_bf16 v[24:27], v[102:105], v[98:101], v[24:27]
	s_addc_u32 s1, s61, s1
	v_readlane_b32 s78, v165, 13
	v_readlane_b32 s79, v165, 14
	s_waitcnt lgkmcnt(0)
	v_mfma_f32_16x16x32_bf16 v[8:11], v[106:109], v[98:101], v[8:11]
	ds_read_b128 v[98:101], v89 offset:18432
	ds_read_b128 v[110:113], v89 offset:19456
	v_readlane_b32 s80, v165, 15
	v_readlane_b32 s81, v165, 16
	s_waitcnt lgkmcnt(1)
	v_mfma_f32_16x16x32_bf16 v[52:55], v[90:93], v[98:101], v[44:47]
	v_readlane_b32 s82, v165, 17
	v_readlane_b32 s83, v165, 18
	s_nop 0
	v_lshlrev_b32_e32 v44, 6, v70
	v_lshlrev_b32_e32 v45, 2, v71
	v_or3_b32 v70, v44, v45, s4
	v_ashrrev_i32_e32 v71, 31, v70
	v_mfma_f32_16x16x32_bf16 v[56:59], v[94:97], v[76:79], v[56:59]
	v_readlane_b32 s84, v165, 19
	v_readlane_b32 s85, v165, 20
	v_readlane_b32 s86, v165, 21
	v_mfma_f32_16x16x32_bf16 v[28:31], v[102:105], v[76:79], v[28:31]
	v_readlane_b32 s87, v165, 22
	s_mov_b64 s[62:63], s[74:75]
	s_mov_b64 s[64:65], s[76:77]
	v_mfma_f32_16x16x32_bf16 v[12:15], v[106:109], v[76:79], v[12:15]
	v_lshl_add_u64 v[76:77], v[70:71], 2, s[0:1]
	global_load_dwordx4 v[44:47], v[76:77], off
	s_mulk_i32 s10, 0x4200
	v_mfma_f32_16x16x32_bf16 v[36:39], v[94:97], v[98:101], v[36:39]
	v_readlane_b32 s72, v166, 7
	v_lshl_add_u32 v68, v72, 6, s8
	s_lshl_b64 s[0:1], s[10:11], 2
	v_mfma_f32_16x16x32_bf16 v[20:23], v[102:105], v[98:101], v[20:23]
	v_readlane_b32 s78, v166, 13
	v_or_b32_e32 v72, v68, v73
	v_readlane_b32 s79, v166, 14
	v_mfma_f32_16x16x32_bf16 v[4:7], v[106:109], v[98:101], v[4:7]
	s_add_u32 s0, s78, s0
	v_add_u32_e32 v78, v72, v75
	s_addc_u32 s1, s79, s1
	s_waitcnt lgkmcnt(0)
	v_mfma_f32_16x16x32_bf16 v[40:43], v[90:93], v[110:113], v[40:43]
	v_cmp_lt_i32_e32 vcc, v72, v74
	v_ashrrev_i32_e32 v73, 31, v72
	v_ashrrev_i32_e32 v79, 31, v78
	v_mfma_f32_16x16x32_bf16 v[32:35], v[94:97], v[110:113], v[32:35]
	v_readlane_b32 s73, v166, 8
	v_readlane_b32 s74, v166, 9
	v_readlane_b32 s75, v166, 10
	v_mfma_f32_16x16x32_bf16 v[16:19], v[102:105], v[110:113], v[16:19]
	v_readlane_b32 s76, v166, 11
	v_readlane_b32 s77, v166, 12
	v_readlane_b32 s80, v166, 15
	v_mfma_f32_16x16x32_bf16 v[0:3], v[106:109], v[110:113], v[0:3]
	v_readlane_b32 s81, v166, 16
	v_readlane_b32 s82, v166, 17
	v_readlane_b32 s83, v166, 18
	v_readlane_b32 s84, v166, 19
	v_readlane_b32 s85, v166, 20
	v_readlane_b32 s86, v166, 21
	v_readlane_b32 s87, v166, 22
	v_lshl_add_u64 v[124:125], v[72:73], 2, s[0:1]
	global_load_dword v126, v[124:125], off
	global_load_dword v127, v[124:125], off offset:64
	global_load_dword v128, v[124:125], off offset:128
	global_load_dword v129, v[124:125], off offset:192
	global_load_dwordx4 v[130:133], v[76:77], off offset:64
	global_load_dwordx4 v[134:137], v[76:77], off offset:128
	global_load_dwordx4 v[138:141], v[76:77], off offset:192
	s_waitcnt vmcnt(0)
	s_and_saveexec_b64 s[4:5], vcc
	s_cbranch_execz .LBB0_722
; DEV unsigned pack2(float a, float b) { return (unsigned)f2bf(a) | ((unsigned)f2bf(b) << 16); }
; DEV void phase_moe2(const Params& p, int l, unsigned char* smem) {
;     ...
;         for (int n = 0; n < 4; ++n) {
;           const int col = nt * 128 + wc * 64 + n * 16 + fq * 4;
;           const float4 b4 = *reinterpret_cast<const float4*>(bd + col);
; #pragma unroll
;           for (int m = 0; m < 4; ++m) {
;             const int i = mt * 128 + wr * 64 + m * 16 + fr;
;             if (i < cnt) {
;               const float g = gl[i];
;               *reinterpret_cast<uint2*>(p.out2 + (size_t)(rowoff + i) * 1024 + col) =
;                   make_uint2(pack2((acc[m][n][0] + b4.x) * g, (acc[m][n][1] + b4.y) * g), pack2((acc[m][n][2] + b4.z) * g, (acc[m][n][3] + b4.w) * g));
;             }
	v_lshl_add_u64 v[90:91], v[72:73], 2, s[0:1]
	v_mov_b32_e32 v68, v126
	v_pk_add_f32 v[66:67], v[66:67], v[46:47]
	v_pk_add_f32 v[64:65], v[64:65], v[44:45]
	v_mov_b32_e32 v93, v66
	v_mov_b32_e32 v66, v65
	v_mov_b32_e32 v92, v64
	v_readlane_b32 s72, v166, 7
	v_lshlrev_b64 v[90:91], 11, v[78:79]
	v_readlane_b32 s82, v166, 17
	v_readlane_b32 s83, v166, 18
	v_readlane_b32 s73, v166, 8
	v_readlane_b32 s74, v166, 9
	v_lshl_add_u64 v[90:91], s[82:83], 0, v[90:91]
	v_lshl_add_u64 v[90:91], v[70:71], 1, v[90:91]
	v_readlane_b32 s75, v166, 10
	v_readlane_b32 s76, v166, 11
	v_readlane_b32 s77, v166, 12
	v_readlane_b32 s78, v166, 13
	v_readlane_b32 s79, v166, 14
	v_readlane_b32 s80, v166, 15
	v_readlane_b32 s81, v166, 16
	v_readlane_b32 s84, v166, 19
	v_readlane_b32 s85, v166, 20
	v_readlane_b32 s86, v166, 21
	v_readlane_b32 s87, v166, 22
	v_pk_mul_f32 v[64:65], v[66:67], v[68:69] op_sel_hi:[1,0]
	v_pk_mul_f32 v[92:93], v[92:93], v[68:69] op_sel_hi:[1,0]
	v_and_b32_sdwa v68, v65, v87 dst_sel:DWORD dst_unused:UNUSED_PAD src0_sel:WORD_1 src1_sel:DWORD
	v_and_b32_sdwa v89, v64, v87 dst_sel:DWORD dst_unused:UNUSED_PAD src0_sel:WORD_1 src1_sel:DWORD
	v_and_b32_sdwa v66, v93, v87 dst_sel:DWORD dst_unused:UNUSED_PAD src0_sel:WORD_1 src1_sel:DWORD
	v_and_b32_sdwa v67, v92, v87 dst_sel:DWORD dst_unused:UNUSED_PAD src0_sel:WORD_1 src1_sel:DWORD
	v_add3_u32 v65, v65, v68, s2
	v_add3_u32 v64, v64, v89, s2
	v_add3_u32 v67, v92, v67, s2
	v_add3_u32 v66, v93, v66, s2
	v_and_b32_e32 v65, 0xffff0000, v65
	v_and_b32_e32 v64, 0xffff0000, v64
	v_or_b32_sdwa v65, v65, v66 dst_sel:DWORD dst_unused:UNUSED_PAD src0_sel:DWORD src1_sel:WORD_1
	v_or_b32_sdwa v64, v64, v67 dst_sel:DWORD dst_unused:UNUSED_PAD src0_sel:DWORD src1_sel:WORD_1
	global_store_dwordx2 v[90:91], v[64:65], off
.LBB0_722:
	s_or_b64 exec, exec, s[4:5]
	v_or_b32_e32 v64, 16, v72
	v_cmp_lt_i32_e64 s[4:5], v64, v74
	v_add_u32_e32 v64, v64, v75
	v_ashrrev_i32_e32 v65, 31, v64
	s_and_saveexec_b64 s[6:7], s[4:5]
	s_cbranch_execz .LBB0_724
	v_lshl_add_u64 v[66:67], v[72:73], 2, s[0:1]
	v_mov_b32_e32 v66, v127
	v_pk_add_f32 v[62:63], v[62:63], v[46:47]
	v_pk_add_f32 v[60:61], v[60:61], v[44:45]
	v_mov_b32_e32 v93, v62
	v_mov_b32_e32 v62, v61
	v_mov_b32_e32 v92, v60
	v_readlane_b32 s72, v166, 7
	v_lshlrev_b64 v[90:91], 11, v[64:65]
	v_readlane_b32 s82, v166, 17
	v_readlane_b32 s83, v166, 18
	v_readlane_b32 s73, v166, 8
	v_readlane_b32 s74, v166, 9
	v_lshl_add_u64 v[90:91], s[82:83], 0, v[90:91]
	v_lshl_add_u64 v[90:91], v[70:71], 1, v[90:91]
	v_readlane_b32 s75, v166, 10
	v_readlane_b32 s76, v166, 11
	v_readlane_b32 s77, v166, 12
	v_readlane_b32 s78, v166, 13
	v_readlane_b32 s79, v166, 14
	v_readlane_b32 s80, v166, 15
	v_readlane_b32 s81, v166, 16
	v_readlane_b32 s84, v166, 19
	v_readlane_b32 s85, v166, 20
	v_readlane_b32 s86, v166, 21
	v_readlane_b32 s87, v166, 22
	v_pk_mul_f32 v[60:61], v[62:63], v[66:67] op_sel_hi:[1,0]
	v_pk_mul_f32 v[92:93], v[92:93], v[66:67] op_sel_hi:[1,0]
	v_and_b32_sdwa v66, v61, v87 dst_sel:DWORD dst_unused:UNUSED_PAD src0_sel:WORD_1 src1_sel:DWORD
	v_and_b32_sdwa v67, v60, v87 dst_sel:DWORD dst_unused:UNUSED_PAD src0_sel:WORD_1 src1_sel:DWORD
	v_and_b32_sdwa v62, v93, v87 dst_sel:DWORD dst_unused:UNUSED_PAD src0_sel:WORD_1 src1_sel:DWORD
	v_and_b32_sdwa v63, v92, v87 dst_sel:DWORD dst_unused:UNUSED_PAD src0_sel:WORD_1 src1_sel:DWORD
	v_add3_u32 v61, v61, v66, s2
	v_add3_u32 v60, v60, v67, s2
	v_add3_u32 v63, v92, v63, s2
	v_add3_u32 v62, v93, v62, s2
	v_and_b32_e32 v61, 0xffff0000, v61
	v_and_b32_e32 v60, 0xffff0000, v60
	v_or_b32_sdwa v61, v61, v62 dst_sel:DWORD dst_unused:UNUSED_PAD src0_sel:DWORD src1_sel:WORD_1
	v_or_b32_sdwa v60, v60, v63 dst_sel:DWORD dst_unused:UNUSED_PAD src0_sel:DWORD src1_sel:WORD_1
	global_store_dwordx2 v[90:91], v[60:61], off
.LBB0_724:
	s_or_b64 exec, exec, s[6:7]
	v_or_b32_e32 v60, 32, v72
	v_cmp_lt_i32_e64 s[6:7], v60, v74
	v_add_u32_e32 v60, v60, v75
	v_ashrrev_i32_e32 v61, 31, v60
	s_and_saveexec_b64 s[8:9], s[6:7]
	v_readlane_b32 s56, v165, 39
	v_readlane_b32 s66, v165, 49
	v_readlane_b32 s67, v165, 50
	v_readlane_b32 s57, v165, 40
	v_readlane_b32 s58, v165, 41
	v_readlane_b32 s59, v165, 42
	v_readlane_b32 s60, v165, 43
	v_readlane_b32 s61, v165, 44
	v_readlane_b32 s62, v165, 45
	v_readlane_b32 s63, v165, 46
	v_readlane_b32 s64, v165, 47
	v_readlane_b32 s65, v165, 48
	v_readlane_b32 s68, v165, 51
	v_readlane_b32 s69, v165, 52
	v_readlane_b32 s70, v165, 53
	v_readlane_b32 s71, v165, 54
	s_cbranch_execz .LBB0_726
	v_lshl_add_u64 v[62:63], v[72:73], 2, s[0:1]
	v_mov_b32_e32 v62, v128
	v_pk_add_f32 v[54:55], v[54:55], v[46:47]
	v_pk_add_f32 v[52:53], v[52:53], v[44:45]
	v_mov_b32_e32 v91, v54
	v_mov_b32_e32 v54, v53
	v_mov_b32_e32 v90, v52
	v_readlane_b32 s72, v166, 7
	v_lshlrev_b64 v[66:67], 11, v[60:61]
	v_readlane_b32 s82, v166, 17
	v_readlane_b32 s83, v166, 18
	v_readlane_b32 s73, v166, 8
	v_readlane_b32 s74, v166, 9
	v_lshl_add_u64 v[66:67], s[82:83], 0, v[66:67]
	v_lshl_add_u64 v[66:67], v[70:71], 1, v[66:67]
	v_readlane_b32 s75, v166, 10
	v_readlane_b32 s76, v166, 11
	v_readlane_b32 s77, v166, 12
	v_readlane_b32 s78, v166, 13
	v_readlane_b32 s79, v166, 14
	v_readlane_b32 s80, v166, 15
	v_readlane_b32 s81, v166, 16
	v_readlane_b32 s84, v166, 19
	v_readlane_b32 s85, v166, 20
	v_readlane_b32 s86, v166, 21
	v_readlane_b32 s87, v166, 22
	v_pk_mul_f32 v[52:53], v[54:55], v[62:63] op_sel_hi:[1,0]
	v_pk_mul_f32 v[90:91], v[90:91], v[62:63] op_sel_hi:[1,0]
	v_and_b32_sdwa v62, v53, v87 dst_sel:DWORD dst_unused:UNUSED_PAD src0_sel:WORD_1 src1_sel:DWORD
	v_and_b32_sdwa v63, v52, v87 dst_sel:DWORD dst_unused:UNUSED_PAD src0_sel:WORD_1 src1_sel:DWORD
	v_and_b32_sdwa v54, v91, v87 dst_sel:DWORD dst_unused:UNUSED_PAD src0_sel:WORD_1 src1_sel:DWORD
	v_and_b32_sdwa v55, v90, v87 dst_sel:DWORD dst_unused:UNUSED_PAD src0_sel:WORD_1 src1_sel:DWORD
	v_add3_u32 v53, v53, v62, s2
	v_add3_u32 v52, v52, v63, s2
	v_add3_u32 v55, v90, v55, s2
	v_add3_u32 v54, v91, v54, s2
	v_and_b32_e32 v53, 0xffff0000, v53
	v_and_b32_e32 v52, 0xffff0000, v52
	v_or_b32_sdwa v53, v53, v54 dst_sel:DWORD dst_unused:UNUSED_PAD src0_sel:DWORD src1_sel:WORD_1
	v_or_b32_sdwa v52, v52, v55 dst_sel:DWORD dst_unused:UNUSED_PAD src0_sel:DWORD src1_sel:WORD_1
	global_store_dwordx2 v[66:67], v[52:53], off
.LBB0_726:
	s_or_b64 exec, exec, s[8:9]
	v_or_b32_e32 v52, 48, v72
	v_cmp_lt_i32_e64 s[8:9], v52, v74
	v_add_u32_e32 v52, v52, v75
	v_ashrrev_i32_e32 v53, 31, v52
	s_and_saveexec_b64 s[16:17], s[8:9]
	s_cbranch_execnz .LBB0_739
	s_or_b64 exec, exec, s[16:17]
	v_mov_b64_e32 v[40:41], v[130:131]
	v_mov_b64_e32 v[42:43], v[132:133]
	s_and_saveexec_b64 s[16:17], vcc
	s_cbranch_execnz .LBB0_740

; DEV void phase_moe2(const Params& p, int l, unsigned char* smem) {
;     ...
;           const int col = nt * 128 + wc * 64 + n * 16 + fq * 4;
;           const float4 b4 = *reinterpret_cast<const float4*>(bd + col);
.LBB0_731:
	s_or_b64 exec, exec, s[16:17]
	v_mov_b64_e32 v[32:33], v[134:135]
	v_mov_b64_e32 v[34:35], v[136:137]
	s_and_saveexec_b64 s[16:17], vcc
	s_cbranch_execnz .LBB0_744

; DEV void phase_moe2(const Params& p, int l, unsigned char* smem) {
;     ...
;           const int col = nt * 128 + wc * 64 + n * 16 + fq * 4;
;           const float4 b4 = *reinterpret_cast<const float4*>(bd + col);
.LBB0_735:
	s_or_b64 exec, exec, s[16:17]
	v_mov_b64_e32 v[16:17], v[138:139]
	v_mov_b64_e32 v[18:19], v[140:141]
	s_and_saveexec_b64 s[16:17], vcc
	s_cbranch_execnz .LBB0_748

; DEV unsigned pack2(float a, float b) { return (unsigned)f2bf(a) | ((unsigned)f2bf(b) << 16); }
; DEV void phase_moe2(const Params& p, int l, unsigned char* smem) {
;     ...
;           for (int m = 0; m < 4; ++m) {
;             const int i = mt * 128 + wr * 64 + m * 16 + fr;
;             if (i < cnt) {
;               const float g = gl[i];
;               *reinterpret_cast<uint2*>(p.out2 + (size_t)(rowoff + i) * 1024 + col) =
;                   make_uint2(pack2((acc[m][n][0] + b4.x) * g, (acc[m][n][1] + b4.y) * g), pack2((acc[m][n][2] + b4.z) * g, (acc[m][n][3] + b4.w) * g));
;             }
.LBB0_739:
	v_lshl_add_u64 v[54:55], v[72:73], 2, s[0:1]
	v_mov_b32_e32 v54, v129
	v_pk_add_f32 v[42:43], v[42:43], v[46:47]
	v_pk_add_f32 v[40:41], v[40:41], v[44:45]
	v_readlane_b32 s72, v166, 7
	v_lshlrev_b64 v[62:63], 11, v[52:53]
	v_readlane_b32 s82, v166, 17
	v_readlane_b32 s83, v166, 18
	v_mov_b32_e32 v47, v42
	v_mov_b32_e32 v42, v41
	v_lshl_add_u64 v[44:45], s[82:83], 0, v[62:63]
	v_mov_b32_e32 v46, v40
	v_lshl_add_u64 v[40:41], v[70:71], 1, v[44:45]
	v_readlane_b32 s73, v166, 8
	v_readlane_b32 s74, v166, 9
	v_readlane_b32 s75, v166, 10
	v_readlane_b32 s76, v166, 11
	v_readlane_b32 s77, v166, 12
	v_readlane_b32 s78, v166, 13
	v_readlane_b32 s79, v166, 14
	v_readlane_b32 s80, v166, 15
	v_readlane_b32 s81, v166, 16
	v_readlane_b32 s84, v166, 19
	v_readlane_b32 s85, v166, 20
	v_readlane_b32 s86, v166, 21
	v_readlane_b32 s87, v166, 22
	v_pk_mul_f32 v[42:43], v[42:43], v[54:55] op_sel_hi:[1,0]
	v_pk_mul_f32 v[44:45], v[46:47], v[54:55] op_sel_hi:[1,0]
	v_and_b32_sdwa v54, v43, v87 dst_sel:DWORD dst_unused:UNUSED_PAD src0_sel:WORD_1 src1_sel:DWORD
	v_and_b32_sdwa v55, v42, v87 dst_sel:DWORD dst_unused:UNUSED_PAD src0_sel:WORD_1 src1_sel:DWORD
	v_and_b32_sdwa v46, v45, v87 dst_sel:DWORD dst_unused:UNUSED_PAD src0_sel:WORD_1 src1_sel:DWORD
	v_and_b32_sdwa v47, v44, v87 dst_sel:DWORD dst_unused:UNUSED_PAD src0_sel:WORD_1 src1_sel:DWORD
	v_add3_u32 v43, v43, v54, s2
	v_add3_u32 v42, v42, v55, s2
	v_add3_u32 v44, v44, v47, s2
	v_add3_u32 v45, v45, v46, s2
	v_and_b32_e32 v43, 0xffff0000, v43
	v_and_b32_e32 v42, 0xffff0000, v42
	v_or_b32_sdwa v43, v43, v45 dst_sel:DWORD dst_unused:UNUSED_PAD src0_sel:DWORD src1_sel:WORD_1
	v_or_b32_sdwa v42, v42, v44 dst_sel:DWORD dst_unused:UNUSED_PAD src0_sel:DWORD src1_sel:WORD_1
	global_store_dwordx2 v[40:41], v[42:43], off
	s_or_b64 exec, exec, s[16:17]
	v_mov_b64_e32 v[40:41], v[130:131]
	v_mov_b64_e32 v[42:43], v[132:133]
	s_and_saveexec_b64 s[16:17], vcc
	s_cbranch_execz .LBB0_728
.LBB0_740:
	v_lshl_add_u64 v[44:45], v[72:73], 2, s[0:1]
	v_mov_b32_e32 v44, v126
	v_pk_add_f32 v[54:55], v[58:59], v[42:43]
	v_pk_add_f32 v[56:57], v[56:57], v[40:41]
	v_mov_b32_e32 v59, v54
	v_mov_b32_e32 v58, v56
	v_mov_b32_e32 v54, v57
	v_readlane_b32 s72, v166, 7
	v_lshlrev_b64 v[46:47], 11, v[78:79]
	v_readlane_b32 s82, v166, 17
	v_readlane_b32 s83, v166, 18
	v_readlane_b32 s73, v166, 8
	v_readlane_b32 s74, v166, 9
	v_lshl_add_u64 v[46:47], s[82:83], 0, v[46:47]
	v_lshl_add_u64 v[46:47], v[70:71], 1, v[46:47]
	v_readlane_b32 s75, v166, 10
	v_readlane_b32 s76, v166, 11
	v_readlane_b32 s77, v166, 12
	v_readlane_b32 s78, v166, 13
	v_readlane_b32 s79, v166, 14
	v_readlane_b32 s80, v166, 15
	v_readlane_b32 s81, v166, 16
	v_readlane_b32 s84, v166, 19
	v_readlane_b32 s85, v166, 20
	v_readlane_b32 s86, v166, 21
	v_readlane_b32 s87, v166, 22
	v_pk_mul_f32 v[58:59], v[58:59], v[44:45] op_sel_hi:[1,0]
	v_pk_mul_f32 v[44:45], v[54:55], v[44:45] op_sel_hi:[1,0]
	v_and_b32_sdwa v54, v59, v87 dst_sel:DWORD dst_unused:UNUSED_PAD src0_sel:WORD_1 src1_sel:DWORD
	v_and_b32_sdwa v56, v45, v87 dst_sel:DWORD dst_unused:UNUSED_PAD src0_sel:WORD_1 src1_sel:DWORD
	v_and_b32_sdwa v57, v44, v87 dst_sel:DWORD dst_unused:UNUSED_PAD src0_sel:WORD_1 src1_sel:DWORD
	v_and_b32_sdwa v55, v58, v87 dst_sel:DWORD dst_unused:UNUSED_PAD src0_sel:WORD_1 src1_sel:DWORD
	v_add3_u32 v45, v45, v56, s2
	v_add3_u32 v44, v44, v57, s2
	v_add3_u32 v55, v58, v55, s2
	v_add3_u32 v54, v59, v54, s2
	v_and_b32_e32 v45, 0xffff0000, v45
	v_and_b32_e32 v44, 0xffff0000, v44
	v_or_b32_sdwa v45, v45, v54 dst_sel:DWORD dst_unused:UNUSED_PAD src0_sel:DWORD src1_sel:WORD_1
	v_or_b32_sdwa v44, v44, v55 dst_sel:DWORD dst_unused:UNUSED_PAD src0_sel:DWORD src1_sel:WORD_1
	global_store_dwordx2 v[46:47], v[44:45], off offset:32
	s_or_b64 exec, exec, s[16:17]
	s_and_saveexec_b64 s[16:17], s[4:5]
	s_cbranch_execz .LBB0_729
.LBB0_741:
	v_lshl_add_u64 v[44:45], v[72:73], 2, s[0:1]
	v_mov_b32_e32 v44, v127
	v_pk_add_f32 v[50:51], v[50:51], v[42:43]
	v_pk_add_f32 v[48:49], v[48:49], v[40:41]
	v_mov_b32_e32 v55, v50
	v_mov_b32_e32 v54, v48
	v_mov_b32_e32 v50, v49
	v_readlane_b32 s72, v166, 7
	v_lshlrev_b64 v[46:47], 11, v[64:65]
	v_readlane_b32 s82, v166, 17
	v_readlane_b32 s83, v166, 18
	v_readlane_b32 s73, v166, 8
	v_readlane_b32 s74, v166, 9
	v_lshl_add_u64 v[46:47], s[82:83], 0, v[46:47]
	v_lshl_add_u64 v[46:47], v[70:71], 1, v[46:47]
	v_readlane_b32 s75, v166, 10
	v_readlane_b32 s76, v166, 11
	v_readlane_b32 s77, v166, 12
	v_readlane_b32 s78, v166, 13
	v_readlane_b32 s79, v166, 14
	v_readlane_b32 s80, v166, 15
	v_readlane_b32 s81, v166, 16
	v_readlane_b32 s84, v166, 19
	v_readlane_b32 s85, v166, 20
	v_readlane_b32 s86, v166, 21
	v_readlane_b32 s87, v166, 22
	v_pk_mul_f32 v[54:55], v[54:55], v[44:45] op_sel_hi:[1,0]
	v_pk_mul_f32 v[44:45], v[50:51], v[44:45] op_sel_hi:[1,0]
	v_and_b32_sdwa v48, v55, v87 dst_sel:DWORD dst_unused:UNUSED_PAD src0_sel:WORD_1 src1_sel:DWORD
	v_and_b32_sdwa v50, v45, v87 dst_sel:DWORD dst_unused:UNUSED_PAD src0_sel:WORD_1 src1_sel:DWORD
	v_and_b32_sdwa v51, v44, v87 dst_sel:DWORD dst_unused:UNUSED_PAD src0_sel:WORD_1 src1_sel:DWORD
	v_and_b32_sdwa v49, v54, v87 dst_sel:DWORD dst_unused:UNUSED_PAD src0_sel:WORD_1 src1_sel:DWORD
	v_add3_u32 v45, v45, v50, s2
	v_add3_u32 v44, v44, v51, s2
	v_add3_u32 v49, v54, v49, s2
	v_add3_u32 v48, v55, v48, s2
	v_and_b32_e32 v45, 0xffff0000, v45
	v_and_b32_e32 v44, 0xffff0000, v44
	v_or_b32_sdwa v45, v45, v48 dst_sel:DWORD dst_unused:UNUSED_PAD src0_sel:DWORD src1_sel:WORD_1
	v_or_b32_sdwa v44, v44, v49 dst_sel:DWORD dst_unused:UNUSED_PAD src0_sel:DWORD src1_sel:WORD_1
	global_store_dwordx2 v[46:47], v[44:45], off offset:32
	s_or_b64 exec, exec, s[16:17]
	s_and_saveexec_b64 s[16:17], s[6:7]
	s_cbranch_execz .LBB0_730
; DEV unsigned pack2(float a, float b) { return (unsigned)f2bf(a) | ((unsigned)f2bf(b) << 16); }
; DEV void phase_moe2(const Params& p, int l, unsigned char* smem) {
;     ...
;           for (int m = 0; m < 4; ++m) {
;             const int i = mt * 128 + wr * 64 + m * 16 + fr;
;             if (i < cnt) {
;               const float g = gl[i];
;               *reinterpret_cast<uint2*>(p.out2 + (size_t)(rowoff + i) * 1024 + col) =
;                   make_uint2(pack2((acc[m][n][0] + b4.x) * g, (acc[m][n][1] + b4.y) * g), pack2((acc[m][n][2] + b4.z) * g, (acc[m][n][3] + b4.w) * g));
;             }
.LBB0_742:
	v_lshl_add_u64 v[44:45], v[72:73], 2, s[0:1]
	v_mov_b32_e32 v44, v128
	v_pk_add_f32 v[38:39], v[38:39], v[42:43]
	v_pk_add_f32 v[36:37], v[36:37], v[40:41]
	v_mov_b32_e32 v49, v38
	v_mov_b32_e32 v38, v37
	v_mov_b32_e32 v48, v36
	v_readlane_b32 s72, v166, 7
	v_lshlrev_b64 v[46:47], 11, v[60:61]
	v_readlane_b32 s82, v166, 17
	v_readlane_b32 s83, v166, 18
	v_readlane_b32 s73, v166, 8
	v_readlane_b32 s74, v166, 9
	v_lshl_add_u64 v[46:47], s[82:83], 0, v[46:47]
	v_lshl_add_u64 v[46:47], v[70:71], 1, v[46:47]
	v_readlane_b32 s75, v166, 10
	v_readlane_b32 s76, v166, 11
	v_readlane_b32 s77, v166, 12
	v_readlane_b32 s78, v166, 13
	v_readlane_b32 s79, v166, 14
	v_readlane_b32 s80, v166, 15
	v_readlane_b32 s81, v166, 16
	v_readlane_b32 s84, v166, 19
	v_readlane_b32 s85, v166, 20
	v_readlane_b32 s86, v166, 21
	v_readlane_b32 s87, v166, 22
	v_pk_mul_f32 v[36:37], v[38:39], v[44:45] op_sel_hi:[1,0]
	v_pk_mul_f32 v[48:49], v[48:49], v[44:45] op_sel_hi:[1,0]
	v_and_b32_sdwa v44, v37, v87 dst_sel:DWORD dst_unused:UNUSED_PAD src0_sel:WORD_1 src1_sel:DWORD
	v_and_b32_sdwa v45, v36, v87 dst_sel:DWORD dst_unused:UNUSED_PAD src0_sel:WORD_1 src1_sel:DWORD
	v_and_b32_sdwa v38, v49, v87 dst_sel:DWORD dst_unused:UNUSED_PAD src0_sel:WORD_1 src1_sel:DWORD
	v_and_b32_sdwa v39, v48, v87 dst_sel:DWORD dst_unused:UNUSED_PAD src0_sel:WORD_1 src1_sel:DWORD
	v_add3_u32 v37, v37, v44, s2
	v_add3_u32 v36, v36, v45, s2
	v_add3_u32 v39, v48, v39, s2
	v_add3_u32 v38, v49, v38, s2
	v_and_b32_e32 v37, 0xffff0000, v37
	v_and_b32_e32 v36, 0xffff0000, v36
	v_or_b32_sdwa v37, v37, v38 dst_sel:DWORD dst_unused:UNUSED_PAD src0_sel:DWORD src1_sel:WORD_1
	v_or_b32_sdwa v36, v36, v39 dst_sel:DWORD dst_unused:UNUSED_PAD src0_sel:DWORD src1_sel:WORD_1
	global_store_dwordx2 v[46:47], v[36:37], off offset:32
	s_or_b64 exec, exec, s[16:17]
	s_and_saveexec_b64 s[16:17], s[8:9]
	s_cbranch_execz .LBB0_731
.LBB0_743:
	v_lshl_add_u64 v[36:37], v[72:73], 2, s[0:1]
	v_mov_b32_e32 v36, v129
	v_pk_add_f32 v[34:35], v[34:35], v[42:43]
	v_pk_add_f32 v[32:33], v[32:33], v[40:41]
	v_readlane_b32 s72, v166, 7
	v_lshlrev_b64 v[38:39], 11, v[52:53]
	v_readlane_b32 s82, v166, 17
	v_readlane_b32 s83, v166, 18
	v_mov_b32_e32 v41, v34
	v_mov_b32_e32 v34, v33
	v_lshl_add_u64 v[38:39], s[82:83], 0, v[38:39]
	v_mov_b32_e32 v40, v32
	v_lshl_add_u64 v[32:33], v[70:71], 1, v[38:39]
	v_readlane_b32 s73, v166, 8
	v_readlane_b32 s74, v166, 9
	v_readlane_b32 s75, v166, 10
	v_readlane_b32 s76, v166, 11
	v_readlane_b32 s77, v166, 12
	v_readlane_b32 s78, v166, 13
	v_readlane_b32 s79, v166, 14
	v_readlane_b32 s80, v166, 15
	v_readlane_b32 s81, v166, 16
	v_readlane_b32 s84, v166, 19
	v_readlane_b32 s85, v166, 20
	v_readlane_b32 s86, v166, 21
	v_readlane_b32 s87, v166, 22
	v_pk_mul_f32 v[34:35], v[34:35], v[36:37] op_sel_hi:[1,0]
	v_pk_mul_f32 v[38:39], v[40:41], v[36:37] op_sel_hi:[1,0]
	v_and_b32_sdwa v40, v35, v87 dst_sel:DWORD dst_unused:UNUSED_PAD src0_sel:WORD_1 src1_sel:DWORD
	v_and_b32_sdwa v41, v34, v87 dst_sel:DWORD dst_unused:UNUSED_PAD src0_sel:WORD_1 src1_sel:DWORD
	v_and_b32_sdwa v36, v39, v87 dst_sel:DWORD dst_unused:UNUSED_PAD src0_sel:WORD_1 src1_sel:DWORD
	v_and_b32_sdwa v37, v38, v87 dst_sel:DWORD dst_unused:UNUSED_PAD src0_sel:WORD_1 src1_sel:DWORD
	v_add3_u32 v35, v35, v40, s2
	v_add3_u32 v34, v34, v41, s2
	v_add3_u32 v37, v38, v37, s2
	v_add3_u32 v36, v39, v36, s2
	v_and_b32_e32 v35, 0xffff0000, v35
	v_and_b32_e32 v34, 0xffff0000, v34
	v_or_b32_sdwa v35, v35, v36 dst_sel:DWORD dst_unused:UNUSED_PAD src0_sel:DWORD src1_sel:WORD_1
	v_or_b32_sdwa v34, v34, v37 dst_sel:DWORD dst_unused:UNUSED_PAD src0_sel:DWORD src1_sel:WORD_1
	global_store_dwordx2 v[32:33], v[34:35], off offset:32
	s_or_b64 exec, exec, s[16:17]
	v_mov_b64_e32 v[32:33], v[134:135]
	v_mov_b64_e32 v[34:35], v[136:137]
	s_and_saveexec_b64 s[16:17], vcc
	s_cbranch_execz .LBB0_732
.LBB0_744:
	v_lshl_add_u64 v[36:37], v[72:73], 2, s[0:1]
	v_mov_b32_e32 v36, v126
	v_pk_add_f32 v[30:31], v[30:31], v[34:35]
	v_pk_add_f32 v[28:29], v[28:29], v[32:33]
	v_mov_b32_e32 v41, v30
	v_mov_b32_e32 v30, v29
	v_mov_b32_e32 v40, v28
	v_readlane_b32 s72, v166, 7
	v_lshlrev_b64 v[38:39], 11, v[78:79]
	v_readlane_b32 s82, v166, 17
	v_readlane_b32 s83, v166, 18
	v_readlane_b32 s73, v166, 8
	v_readlane_b32 s74, v166, 9
	v_lshl_add_u64 v[38:39], s[82:83], 0, v[38:39]
	v_lshl_add_u64 v[38:39], v[70:71], 1, v[38:39]
	v_readlane_b32 s75, v166, 10
	v_readlane_b32 s76, v166, 11
	v_readlane_b32 s77, v166, 12
	v_readlane_b32 s78, v166, 13
	v_readlane_b32 s79, v166, 14
	v_readlane_b32 s80, v166, 15
	v_readlane_b32 s81, v166, 16
	v_readlane_b32 s84, v166, 19
	v_readlane_b32 s85, v166, 20
	v_readlane_b32 s86, v166, 21
	v_readlane_b32 s87, v166, 22
	v_pk_mul_f32 v[28:29], v[30:31], v[36:37] op_sel_hi:[1,0]
	v_pk_mul_f32 v[40:41], v[40:41], v[36:37] op_sel_hi:[1,0]
	v_and_b32_sdwa v36, v29, v87 dst_sel:DWORD dst_unused:UNUSED_PAD src0_sel:WORD_1 src1_sel:DWORD
	v_and_b32_sdwa v37, v28, v87 dst_sel:DWORD dst_unused:UNUSED_PAD src0_sel:WORD_1 src1_sel:DWORD
	v_and_b32_sdwa v30, v41, v87 dst_sel:DWORD dst_unused:UNUSED_PAD src0_sel:WORD_1 src1_sel:DWORD
	v_and_b32_sdwa v31, v40, v87 dst_sel:DWORD dst_unused:UNUSED_PAD src0_sel:WORD_1 src1_sel:DWORD
	v_add3_u32 v29, v29, v36, s2
	v_add3_u32 v28, v28, v37, s2
	v_add3_u32 v31, v40, v31, s2
	v_add3_u32 v30, v41, v30, s2
	v_and_b32_e32 v29, 0xffff0000, v29
	v_and_b32_e32 v28, 0xffff0000, v28
	v_or_b32_sdwa v29, v29, v30 dst_sel:DWORD dst_unused:UNUSED_PAD src0_sel:DWORD src1_sel:WORD_1
	v_or_b32_sdwa v28, v28, v31 dst_sel:DWORD dst_unused:UNUSED_PAD src0_sel:DWORD src1_sel:WORD_1
	global_store_dwordx2 v[38:39], v[28:29], off offset:64
	s_or_b64 exec, exec, s[16:17]
	s_and_saveexec_b64 s[16:17], s[4:5]
	s_cbranch_execz .LBB0_733
; DEV unsigned pack2(float a, float b) { return (unsigned)f2bf(a) | ((unsigned)f2bf(b) << 16); }
; DEV void phase_moe2(const Params& p, int l, unsigned char* smem) {
;     ...
;           for (int m = 0; m < 4; ++m) {
;             const int i = mt * 128 + wr * 64 + m * 16 + fr;
;             if (i < cnt) {
;               const float g = gl[i];
;               *reinterpret_cast<uint2*>(p.out2 + (size_t)(rowoff + i) * 1024 + col) =
;                   make_uint2(pack2((acc[m][n][0] + b4.x) * g, (acc[m][n][1] + b4.y) * g), pack2((acc[m][n][2] + b4.z) * g, (acc[m][n][3] + b4.w) * g));
;             }
.LBB0_745:
	v_lshl_add_u64 v[28:29], v[72:73], 2, s[0:1]
	v_mov_b32_e32 v28, v127
	v_pk_add_f32 v[26:27], v[26:27], v[34:35]
	v_pk_add_f32 v[24:25], v[24:25], v[32:33]
	v_mov_b32_e32 v37, v26
	v_mov_b32_e32 v26, v25
	v_mov_b32_e32 v36, v24
	v_readlane_b32 s72, v166, 7
	v_lshlrev_b64 v[30:31], 11, v[64:65]
	v_readlane_b32 s82, v166, 17
	v_readlane_b32 s83, v166, 18
	v_readlane_b32 s73, v166, 8
	v_readlane_b32 s74, v166, 9
	v_lshl_add_u64 v[30:31], s[82:83], 0, v[30:31]
	v_lshl_add_u64 v[30:31], v[70:71], 1, v[30:31]
	v_readlane_b32 s75, v166, 10
	v_readlane_b32 s76, v166, 11
	v_readlane_b32 s77, v166, 12
	v_readlane_b32 s78, v166, 13
	v_readlane_b32 s79, v166, 14
	v_readlane_b32 s80, v166, 15
	v_readlane_b32 s81, v166, 16
	v_readlane_b32 s84, v166, 19
	v_readlane_b32 s85, v166, 20
	v_readlane_b32 s86, v166, 21
	v_readlane_b32 s87, v166, 22
	v_pk_mul_f32 v[24:25], v[26:27], v[28:29] op_sel_hi:[1,0]
	v_pk_mul_f32 v[36:37], v[36:37], v[28:29] op_sel_hi:[1,0]
	v_and_b32_sdwa v28, v25, v87 dst_sel:DWORD dst_unused:UNUSED_PAD src0_sel:WORD_1 src1_sel:DWORD
	v_and_b32_sdwa v29, v24, v87 dst_sel:DWORD dst_unused:UNUSED_PAD src0_sel:WORD_1 src1_sel:DWORD
	v_and_b32_sdwa v26, v37, v87 dst_sel:DWORD dst_unused:UNUSED_PAD src0_sel:WORD_1 src1_sel:DWORD
	v_and_b32_sdwa v27, v36, v87 dst_sel:DWORD dst_unused:UNUSED_PAD src0_sel:WORD_1 src1_sel:DWORD
	v_add3_u32 v25, v25, v28, s2
	v_add3_u32 v24, v24, v29, s2
	v_add3_u32 v27, v36, v27, s2
	v_add3_u32 v26, v37, v26, s2
	v_and_b32_e32 v25, 0xffff0000, v25
	v_and_b32_e32 v24, 0xffff0000, v24
	v_or_b32_sdwa v25, v25, v26 dst_sel:DWORD dst_unused:UNUSED_PAD src0_sel:DWORD src1_sel:WORD_1
	v_or_b32_sdwa v24, v24, v27 dst_sel:DWORD dst_unused:UNUSED_PAD src0_sel:DWORD src1_sel:WORD_1
	global_store_dwordx2 v[30:31], v[24:25], off offset:64
	s_or_b64 exec, exec, s[16:17]
	s_and_saveexec_b64 s[16:17], s[6:7]
	s_cbranch_execz .LBB0_734
.LBB0_746:
	v_lshl_add_u64 v[24:25], v[72:73], 2, s[0:1]
	v_mov_b32_e32 v24, v128
	v_pk_add_f32 v[22:23], v[22:23], v[34:35]
	v_pk_add_f32 v[20:21], v[20:21], v[32:33]
	v_mov_b32_e32 v29, v22
	v_mov_b32_e32 v22, v21
	v_mov_b32_e32 v28, v20
	v_readlane_b32 s72, v166, 7
	v_lshlrev_b64 v[26:27], 11, v[60:61]
	v_readlane_b32 s82, v166, 17
	v_readlane_b32 s83, v166, 18
	v_readlane_b32 s73, v166, 8
	v_readlane_b32 s74, v166, 9
	v_lshl_add_u64 v[26:27], s[82:83], 0, v[26:27]
	v_lshl_add_u64 v[26:27], v[70:71], 1, v[26:27]
	v_readlane_b32 s75, v166, 10
	v_readlane_b32 s76, v166, 11
	v_readlane_b32 s77, v166, 12
	v_readlane_b32 s78, v166, 13
	v_readlane_b32 s79, v166, 14
	v_readlane_b32 s80, v166, 15
	v_readlane_b32 s81, v166, 16
	v_readlane_b32 s84, v166, 19
	v_readlane_b32 s85, v166, 20
	v_readlane_b32 s86, v166, 21
	v_readlane_b32 s87, v166, 22
	v_pk_mul_f32 v[20:21], v[22:23], v[24:25] op_sel_hi:[1,0]
	v_pk_mul_f32 v[28:29], v[28:29], v[24:25] op_sel_hi:[1,0]
	v_and_b32_sdwa v24, v21, v87 dst_sel:DWORD dst_unused:UNUSED_PAD src0_sel:WORD_1 src1_sel:DWORD
	v_and_b32_sdwa v25, v20, v87 dst_sel:DWORD dst_unused:UNUSED_PAD src0_sel:WORD_1 src1_sel:DWORD
	v_and_b32_sdwa v22, v29, v87 dst_sel:DWORD dst_unused:UNUSED_PAD src0_sel:WORD_1 src1_sel:DWORD
	v_and_b32_sdwa v23, v28, v87 dst_sel:DWORD dst_unused:UNUSED_PAD src0_sel:WORD_1 src1_sel:DWORD
	v_add3_u32 v21, v21, v24, s2
	v_add3_u32 v20, v20, v25, s2
	v_add3_u32 v23, v28, v23, s2
	v_add3_u32 v22, v29, v22, s2
	v_and_b32_e32 v21, 0xffff0000, v21
	v_and_b32_e32 v20, 0xffff0000, v20
	v_or_b32_sdwa v21, v21, v22 dst_sel:DWORD dst_unused:UNUSED_PAD src0_sel:DWORD src1_sel:WORD_1
	v_or_b32_sdwa v20, v20, v23 dst_sel:DWORD dst_unused:UNUSED_PAD src0_sel:DWORD src1_sel:WORD_1
	global_store_dwordx2 v[26:27], v[20:21], off offset:64
	s_or_b64 exec, exec, s[16:17]
	s_and_saveexec_b64 s[16:17], s[8:9]
	s_cbranch_execz .LBB0_735
.LBB0_747:
	v_lshl_add_u64 v[20:21], v[72:73], 2, s[0:1]
	v_mov_b32_e32 v20, v129
	v_pk_add_f32 v[18:19], v[18:19], v[34:35]
	v_pk_add_f32 v[16:17], v[16:17], v[32:33]
	v_readlane_b32 s72, v166, 7
	v_lshlrev_b64 v[22:23], 11, v[52:53]
	v_readlane_b32 s82, v166, 17
	v_readlane_b32 s83, v166, 18
	v_mov_b32_e32 v25, v18
	v_mov_b32_e32 v18, v17
	v_lshl_add_u64 v[22:23], s[82:83], 0, v[22:23]
	v_mov_b32_e32 v24, v16
	v_lshl_add_u64 v[16:17], v[70:71], 1, v[22:23]
	v_readlane_b32 s73, v166, 8
	v_readlane_b32 s74, v166, 9
	v_readlane_b32 s75, v166, 10
	v_readlane_b32 s76, v166, 11
	v_readlane_b32 s77, v166, 12
	v_readlane_b32 s78, v166, 13
	v_readlane_b32 s79, v166, 14
	v_readlane_b32 s80, v166, 15
	v_readlane_b32 s81, v166, 16
	v_readlane_b32 s84, v166, 19
	v_readlane_b32 s85, v166, 20
	v_readlane_b32 s86, v166, 21
	v_readlane_b32 s87, v166, 22
	v_pk_mul_f32 v[18:19], v[18:19], v[20:21] op_sel_hi:[1,0]
	v_pk_mul_f32 v[22:23], v[24:25], v[20:21] op_sel_hi:[1,0]
	v_and_b32_sdwa v24, v19, v87 dst_sel:DWORD dst_unused:UNUSED_PAD src0_sel:WORD_1 src1_sel:DWORD
	v_and_b32_sdwa v25, v18, v87 dst_sel:DWORD dst_unused:UNUSED_PAD src0_sel:WORD_1 src1_sel:DWORD
	v_and_b32_sdwa v20, v23, v87 dst_sel:DWORD dst_unused:UNUSED_PAD src0_sel:WORD_1 src1_sel:DWORD
	v_and_b32_sdwa v21, v22, v87 dst_sel:DWORD dst_unused:UNUSED_PAD src0_sel:WORD_1 src1_sel:DWORD
	v_add3_u32 v19, v19, v24, s2
	v_add3_u32 v18, v18, v25, s2
	v_add3_u32 v21, v22, v21, s2
	v_add3_u32 v20, v23, v20, s2
	v_and_b32_e32 v19, 0xffff0000, v19
	v_and_b32_e32 v18, 0xffff0000, v18
	v_or_b32_sdwa v19, v19, v20 dst_sel:DWORD dst_unused:UNUSED_PAD src0_sel:DWORD src1_sel:WORD_1
	v_or_b32_sdwa v18, v18, v21 dst_sel:DWORD dst_unused:UNUSED_PAD src0_sel:DWORD src1_sel:WORD_1
	global_store_dwordx2 v[16:17], v[18:19], off offset:64
	s_or_b64 exec, exec, s[16:17]
	v_mov_b64_e32 v[16:17], v[138:139]
	v_mov_b64_e32 v[18:19], v[140:141]
	s_and_saveexec_b64 s[16:17], vcc
	s_cbranch_execz .LBB0_736
; DEV unsigned pack2(float a, float b) { return (unsigned)f2bf(a) | ((unsigned)f2bf(b) << 16); }
; DEV void phase_moe2(const Params& p, int l, unsigned char* smem) {
;     ...
;           for (int m = 0; m < 4; ++m) {
;             const int i = mt * 128 + wr * 64 + m * 16 + fr;
;             if (i < cnt) {
;               const float g = gl[i];
;               *reinterpret_cast<uint2*>(p.out2 + (size_t)(rowoff + i) * 1024 + col) =
;                   make_uint2(pack2((acc[m][n][0] + b4.x) * g, (acc[m][n][1] + b4.y) * g), pack2((acc[m][n][2] + b4.z) * g, (acc[m][n][3] + b4.w) * g));
;             }
.LBB0_748:
	v_lshl_add_u64 v[20:21], v[72:73], 2, s[0:1]
	v_mov_b32_e32 v20, v126
	v_pk_add_f32 v[14:15], v[14:15], v[18:19]
	v_pk_add_f32 v[12:13], v[12:13], v[16:17]
	v_mov_b32_e32 v25, v14
	v_mov_b32_e32 v14, v13
	v_mov_b32_e32 v24, v12
	v_readlane_b32 s72, v166, 7
	v_lshlrev_b64 v[22:23], 11, v[78:79]
	v_readlane_b32 s82, v166, 17
	v_readlane_b32 s83, v166, 18
	v_readlane_b32 s73, v166, 8
	v_readlane_b32 s74, v166, 9
	v_lshl_add_u64 v[22:23], s[82:83], 0, v[22:23]
	v_lshl_add_u64 v[22:23], v[70:71], 1, v[22:23]
	v_readlane_b32 s75, v166, 10
	v_readlane_b32 s76, v166, 11
	v_readlane_b32 s77, v166, 12
	v_readlane_b32 s78, v166, 13
	v_readlane_b32 s79, v166, 14
	v_readlane_b32 s80, v166, 15
	v_readlane_b32 s81, v166, 16
	v_readlane_b32 s84, v166, 19
	v_readlane_b32 s85, v166, 20
	v_readlane_b32 s86, v166, 21
	v_readlane_b32 s87, v166, 22
	v_pk_mul_f32 v[12:13], v[14:15], v[20:21] op_sel_hi:[1,0]
	v_pk_mul_f32 v[24:25], v[24:25], v[20:21] op_sel_hi:[1,0]
	v_and_b32_sdwa v20, v13, v87 dst_sel:DWORD dst_unused:UNUSED_PAD src0_sel:WORD_1 src1_sel:DWORD
	v_and_b32_sdwa v21, v12, v87 dst_sel:DWORD dst_unused:UNUSED_PAD src0_sel:WORD_1 src1_sel:DWORD
	v_and_b32_sdwa v14, v25, v87 dst_sel:DWORD dst_unused:UNUSED_PAD src0_sel:WORD_1 src1_sel:DWORD
	v_and_b32_sdwa v15, v24, v87 dst_sel:DWORD dst_unused:UNUSED_PAD src0_sel:WORD_1 src1_sel:DWORD
	v_add3_u32 v13, v13, v20, s2
	v_add3_u32 v12, v12, v21, s2
	v_add3_u32 v15, v24, v15, s2
	v_add3_u32 v14, v25, v14, s2
	v_and_b32_e32 v13, 0xffff0000, v13
	v_and_b32_e32 v12, 0xffff0000, v12
	v_or_b32_sdwa v13, v13, v14 dst_sel:DWORD dst_unused:UNUSED_PAD src0_sel:DWORD src1_sel:WORD_1
	v_or_b32_sdwa v12, v12, v15 dst_sel:DWORD dst_unused:UNUSED_PAD src0_sel:DWORD src1_sel:WORD_1
	global_store_dwordx2 v[22:23], v[12:13], off offset:96
	s_or_b64 exec, exec, s[16:17]
	s_and_saveexec_b64 s[16:17], s[4:5]
	s_cbranch_execz .LBB0_737
.LBB0_749:
	v_lshl_add_u64 v[12:13], v[72:73], 2, s[0:1]
	v_mov_b32_e32 v12, v127
	v_pk_add_f32 v[10:11], v[10:11], v[18:19]
	v_pk_add_f32 v[8:9], v[8:9], v[16:17]
	v_mov_b32_e32 v21, v10
	v_mov_b32_e32 v10, v9
	v_mov_b32_e32 v20, v8
	v_readlane_b32 s72, v166, 7
	v_lshlrev_b64 v[14:15], 11, v[64:65]
	v_readlane_b32 s82, v166, 17
	v_readlane_b32 s83, v166, 18
	v_readlane_b32 s73, v166, 8
	v_readlane_b32 s74, v166, 9
	v_lshl_add_u64 v[14:15], s[82:83], 0, v[14:15]
	v_lshl_add_u64 v[14:15], v[70:71], 1, v[14:15]
	v_readlane_b32 s75, v166, 10
	v_readlane_b32 s76, v166, 11
	v_readlane_b32 s77, v166, 12
	v_readlane_b32 s78, v166, 13
	v_readlane_b32 s79, v166, 14
	v_readlane_b32 s80, v166, 15
	v_readlane_b32 s81, v166, 16
	v_readlane_b32 s84, v166, 19
	v_readlane_b32 s85, v166, 20
	v_readlane_b32 s86, v166, 21
	v_readlane_b32 s87, v166, 22
	v_pk_mul_f32 v[8:9], v[10:11], v[12:13] op_sel_hi:[1,0]
	v_pk_mul_f32 v[20:21], v[20:21], v[12:13] op_sel_hi:[1,0]
	v_and_b32_sdwa v12, v9, v87 dst_sel:DWORD dst_unused:UNUSED_PAD src0_sel:WORD_1 src1_sel:DWORD
	v_and_b32_sdwa v13, v8, v87 dst_sel:DWORD dst_unused:UNUSED_PAD src0_sel:WORD_1 src1_sel:DWORD
	v_and_b32_sdwa v10, v21, v87 dst_sel:DWORD dst_unused:UNUSED_PAD src0_sel:WORD_1 src1_sel:DWORD
	v_and_b32_sdwa v11, v20, v87 dst_sel:DWORD dst_unused:UNUSED_PAD src0_sel:WORD_1 src1_sel:DWORD
	v_add3_u32 v9, v9, v12, s2
	v_add3_u32 v8, v8, v13, s2
	v_add3_u32 v11, v20, v11, s2
	v_add3_u32 v10, v21, v10, s2
	v_and_b32_e32 v9, 0xffff0000, v9
	v_and_b32_e32 v8, 0xffff0000, v8
	v_or_b32_sdwa v9, v9, v10 dst_sel:DWORD dst_unused:UNUSED_PAD src0_sel:DWORD src1_sel:WORD_1
	v_or_b32_sdwa v8, v8, v11 dst_sel:DWORD dst_unused:UNUSED_PAD src0_sel:DWORD src1_sel:WORD_1
	global_store_dwordx2 v[14:15], v[8:9], off offset:96
	s_or_b64 exec, exec, s[16:17]
	s_and_saveexec_b64 s[4:5], s[6:7]
	s_cbranch_execz .LBB0_738
; DEV unsigned pack2(float a, float b) { return (unsigned)f2bf(a) | ((unsigned)f2bf(b) << 16); }
; DEV void phase_moe2(const Params& p, int l, unsigned char* smem) {
;     ...
;           for (int m = 0; m < 4; ++m) {
;             const int i = mt * 128 + wr * 64 + m * 16 + fr;
;             if (i < cnt) {
;               const float g = gl[i];
;               *reinterpret_cast<uint2*>(p.out2 + (size_t)(rowoff + i) * 1024 + col) =
;                   make_uint2(pack2((acc[m][n][0] + b4.x) * g, (acc[m][n][1] + b4.y) * g), pack2((acc[m][n][2] + b4.z) * g, (acc[m][n][3] + b4.w) * g));
;             }
.LBB0_750:
	v_lshl_add_u64 v[8:9], v[72:73], 2, s[0:1]
	v_mov_b32_e32 v8, v128
	v_pk_add_f32 v[6:7], v[6:7], v[18:19]
	v_pk_add_f32 v[4:5], v[4:5], v[16:17]
	v_mov_b32_e32 v13, v6
	v_mov_b32_e32 v6, v5
	v_mov_b32_e32 v12, v4
	v_readlane_b32 s72, v166, 7
	v_lshlrev_b64 v[10:11], 11, v[60:61]
	v_readlane_b32 s82, v166, 17
	v_readlane_b32 s83, v166, 18
	v_readlane_b32 s73, v166, 8
	v_readlane_b32 s74, v166, 9
	v_lshl_add_u64 v[10:11], s[82:83], 0, v[10:11]
	v_lshl_add_u64 v[10:11], v[70:71], 1, v[10:11]
	v_readlane_b32 s75, v166, 10
	v_readlane_b32 s76, v166, 11
	v_readlane_b32 s77, v166, 12
	v_readlane_b32 s78, v166, 13
	v_readlane_b32 s79, v166, 14
	v_readlane_b32 s80, v166, 15
	v_readlane_b32 s81, v166, 16
	v_readlane_b32 s84, v166, 19
	v_readlane_b32 s85, v166, 20
	v_readlane_b32 s86, v166, 21
	v_readlane_b32 s87, v166, 22
	v_pk_mul_f32 v[4:5], v[6:7], v[8:9] op_sel_hi:[1,0]
	v_pk_mul_f32 v[12:13], v[12:13], v[8:9] op_sel_hi:[1,0]
	v_and_b32_sdwa v8, v5, v87 dst_sel:DWORD dst_unused:UNUSED_PAD src0_sel:WORD_1 src1_sel:DWORD
	v_and_b32_sdwa v9, v4, v87 dst_sel:DWORD dst_unused:UNUSED_PAD src0_sel:WORD_1 src1_sel:DWORD
	v_and_b32_sdwa v6, v13, v87 dst_sel:DWORD dst_unused:UNUSED_PAD src0_sel:WORD_1 src1_sel:DWORD
	v_and_b32_sdwa v7, v12, v87 dst_sel:DWORD dst_unused:UNUSED_PAD src0_sel:WORD_1 src1_sel:DWORD
	v_add3_u32 v5, v5, v8, s2
	v_add3_u32 v4, v4, v9, s2
	v_add3_u32 v7, v12, v7, s2
	v_add3_u32 v6, v13, v6, s2
	v_and_b32_e32 v5, 0xffff0000, v5
	v_and_b32_e32 v4, 0xffff0000, v4
	v_or_b32_sdwa v5, v5, v6 dst_sel:DWORD dst_unused:UNUSED_PAD src0_sel:DWORD src1_sel:WORD_1
	v_or_b32_sdwa v4, v4, v7 dst_sel:DWORD dst_unused:UNUSED_PAD src0_sel:DWORD src1_sel:WORD_1
	global_store_dwordx2 v[10:11], v[4:5], off offset:96
	s_or_b64 exec, exec, s[4:5]
	s_and_saveexec_b64 s[4:5], s[8:9]
	s_cbranch_execz .LBB0_715
.LBB0_751:
	v_lshl_add_u64 v[4:5], v[72:73], 2, s[0:1]
	v_mov_b32_e32 v4, v129
	v_pk_add_f32 v[2:3], v[2:3], v[18:19]
	v_pk_add_f32 v[0:1], v[0:1], v[16:17]
	v_mov_b32_e32 v9, v2
	v_mov_b32_e32 v2, v1
	v_mov_b32_e32 v8, v0
	v_readlane_b32 s72, v166, 7
	v_lshlrev_b64 v[6:7], 11, v[52:53]
	v_readlane_b32 s82, v166, 17
	v_readlane_b32 s83, v166, 18
	v_readlane_b32 s73, v166, 8
	v_readlane_b32 s74, v166, 9
	v_lshl_add_u64 v[6:7], s[82:83], 0, v[6:7]
	v_lshl_add_u64 v[6:7], v[70:71], 1, v[6:7]
	v_readlane_b32 s75, v166, 10
	v_readlane_b32 s76, v166, 11
	v_readlane_b32 s77, v166, 12
	v_readlane_b32 s78, v166, 13
	v_readlane_b32 s79, v166, 14
	v_readlane_b32 s80, v166, 15
	v_readlane_b32 s81, v166, 16
	v_readlane_b32 s84, v166, 19
	v_readlane_b32 s85, v166, 20
	v_readlane_b32 s86, v166, 21
	v_readlane_b32 s87, v166, 22
	v_pk_mul_f32 v[0:1], v[2:3], v[4:5] op_sel_hi:[1,0]
	v_pk_mul_f32 v[8:9], v[8:9], v[4:5] op_sel_hi:[1,0]
	v_and_b32_sdwa v4, v1, v87 dst_sel:DWORD dst_unused:UNUSED_PAD src0_sel:WORD_1 src1_sel:DWORD
	v_and_b32_sdwa v5, v0, v87 dst_sel:DWORD dst_unused:UNUSED_PAD src0_sel:WORD_1 src1_sel:DWORD
	v_and_b32_sdwa v2, v9, v87 dst_sel:DWORD dst_unused:UNUSED_PAD src0_sel:WORD_1 src1_sel:DWORD
	v_and_b32_sdwa v3, v8, v87 dst_sel:DWORD dst_unused:UNUSED_PAD src0_sel:WORD_1 src1_sel:DWORD
	v_add3_u32 v1, v1, v4, s2
	v_add3_u32 v0, v0, v5, s2
	v_add3_u32 v3, v8, v3, s2
	v_add3_u32 v2, v9, v2, s2
	v_and_b32_e32 v1, 0xffff0000, v1
	v_and_b32_e32 v0, 0xffff0000, v0
	v_or_b32_sdwa v1, v1, v2 dst_sel:DWORD dst_unused:UNUSED_PAD src0_sel:DWORD src1_sel:WORD_1
	v_or_b32_sdwa v0, v0, v3 dst_sel:DWORD dst_unused:UNUSED_PAD src0_sel:DWORD src1_sel:WORD_1
	global_store_dwordx2 v[6:7], v[0:1], off offset:96
	s_branch .LBB0_715

; DEV float bf2f(unsigned short h) { return __uint_as_float(((unsigned)h) << 16); }
; DEV void phase_ml_conv(const Params& p, unsigned char* smem) {
;     ...
;     const int which = it & 1, h = (it >> 1) & 7, rest = it >> 4, ch = rest % NCH, b = rest / NCH;
;     const int segbase = ch < 4 ? NLAT + b * CTX : b * SEQ;
;     const int seglen = ch < 4 ? CTX : SEQ;
;     const int t0 = ch < 4 ? ch * 64 : (ch - 4) * 64;
;     const int tau0 = ch * 64;
;     const int chbase = which * 512 + h * 64;
;     const int tr = tid >> 3, cg8 = (tid & 7) * 8;
;     float cw[5][8], cb[8];
; #pragma unroll
;     for (int w = 0; w < 5; ++w)
; #pragma unroll
;       for (int i = 0; i < 8; ++i) cw[w][i] = p.conv_w[w * 1024 + chbase + cg8 + i];
; #pragma unroll
;     for (int i = 0; i < 8; ++i) cb[i] = p.conv_b[chbase + cg8 + i];
; #pragma unroll
;     for (int rr = 0; rr < 2; ++rr) {
;       const int tl = tr + rr * 32, tt = t0 + tl;
;       float a[8];
; #pragma unroll
;       for (int i = 0; i < 8; ++i) a[i] = cb[i];
; #pragma unroll
;       for (int w = 0; w < 5; ++w) {
;         int ts = tt + w - 2;
;         if (ts >= 0 && ts < seglen) {
;           uint4 v = *reinterpret_cast<const uint4*>(p.qb + (size_t)(segbase + ts) * 1024 + chbase + cg8);
;           a[0] += cw[w][0] * bf2f(v.x & 0xffff); a[1] += cw[w][1] * bf2f(v.x >> 16);
;           a[2] += cw[w][2] * bf2f(v.y & 0xffff); a[3] += cw[w][3] * bf2f(v.y >> 16);
;           a[4] += cw[w][4] * bf2f(v.z & 0xffff); a[5] += cw[w][5] * bf2f(v.z >> 16);
;           a[6] += cw[w][6] * bf2f(v.w & 0xffff); a[7] += cw[w][7] * bf2f(v.w >> 16);
.LBB0_1685:
	s_and_b32 s5, s18, 1
	s_bfe_u32 s4, s18, 0x30001
	s_lshl_b32 s0, s5, 9
	s_lshl_b32 s15, s4, 6
	s_or_b32 s10, s15, s0
	v_readlane_b32 s52, v166, 39
	v_or_b32_e32 v0, s10, v58
	v_readlane_b32 s66, v166, 53
	v_readlane_b32 s67, v166, 54
	v_lshlrev_b32_e32 v56, 2, v0
	s_mov_b64 s[22:23], s[66:67]
	v_lshl_add_u64 v[0:1], s[22:23], 0, v[56:57]
	s_mov_b64 s[0:1], 0x1000
	v_lshl_add_u64 v[2:3], v[0:1], 0, s[0:1]
	s_movk_i32 s0, 0x2000
	v_add_co_u32_e32 v4, vcc, s0, v0
	s_mov_b64 s[0:1], 0x2000
	s_nop 0
	v_addc_co_u32_e32 v5, vcc, 0, v1, vcc
	v_lshl_add_u64 v[6:7], v[0:1], 0, s[0:1]
	s_mov_b64 s[0:1], 0x3000
	global_load_dwordx4 v[40:43], v[4:5], off offset:-4096
	global_load_dwordx4 v[32:35], v[4:5], off
	global_load_dwordx4 v[44:47], v[2:3], off offset:16
	global_load_dwordx4 v[36:39], v[6:7], off offset:16
	v_lshl_add_u64 v[2:3], v[0:1], 0, s[0:1]
	s_movk_i32 s0, 0x4000
	v_readlane_b32 s53, v166, 40
	v_readlane_b32 s54, v166, 41
	v_readlane_b32 s55, v166, 42
	v_readlane_b32 s56, v166, 43
	v_readlane_b32 s57, v166, 44
	v_readlane_b32 s58, v166, 45
	v_readlane_b32 s59, v166, 46
	v_readlane_b32 s60, v166, 47
	v_readlane_b32 s61, v166, 48
	v_readlane_b32 s62, v166, 49
	v_readlane_b32 s63, v166, 50
	v_readlane_b32 s64, v166, 51
	v_readlane_b32 s65, v166, 52
	v_add_co_u32_e32 v4, vcc, s0, v0
	s_mov_b64 s[0:1], 0x4000
	s_nop 0
	v_addc_co_u32_e32 v5, vcc, 0, v1, vcc
	v_readlane_b32 s52, v166, 55
	v_lshl_add_u64 v[0:1], v[0:1], 0, s[0:1]
	global_load_dwordx4 v[24:27], v[4:5], off offset:-4096
	global_load_dwordx4 v[16:19], v[4:5], off
	global_load_dwordx4 v[28:31], v[2:3], off offset:16
	global_load_dwordx4 v[20:23], v[0:1], off offset:16
	v_readlane_b32 s53, v166, 56
	v_readlane_b32 s54, v166, 57
	v_readlane_b32 s55, v166, 58
	s_mov_b64 s[44:45], s[52:53]
	global_load_dwordx4 v[4:7], v56, s[44:45] offset:16
	global_load_dwordx4 v[0:3], v56, s[44:45]
	global_load_dwordx4 v[52:55], v56, s[22:23] offset:16
	global_load_dwordx4 v[48:51], v56, s[22:23]
	s_ashr_i32 s0, s18, 4
	s_mul_hi_i32 s1, s0, 0x3e0f83e1
	s_lshr_b32 s11, s1, 31
	s_ashr_i32 s19, s1, 5
	s_add_i32 s19, s19, s11
	s_mul_i32 s1, s19, 0x84
	s_sub_i32 s0, s0, s1
	s_lshl_b32 s1, s19, 8
	s_lshl_b32 s14, s0, 6
	s_addk_i32 s1, 0x4000
	s_add_i32 s11, s14, 0xffffff00
	s_lshl_b32 s12, s19, 13
	s_cmp_lt_i32 s0, 4
	s_cselect_b32 s22, s14, s11
	s_movk_i32 s0, 0x100
	v_add_u32_e32 v56, s22, v73
	s_cselect_b32 s21, s0, 0x2000
	v_add_u32_e32 v63, -2, v56
	s_cselect_b32 s20, s1, s12
	s_lshl_b32 s12, s10, 1
	v_cmp_lt_i32_e32 vcc, 1, v56
	v_cmp_gt_i32_e64 s[0:1], s21, v63
	v_lshl_add_u64 v[66:67], v[60:61], 0, s[12:13]
	s_and_b64 s[10:11], vcc, s[0:1]
	v_readlane_b32 s56, v166, 59
	v_readlane_b32 s57, v166, 60
	v_readlane_b32 s58, v166, 61
	v_readlane_b32 s59, v166, 62
	v_readlane_b32 s60, v166, 63
	v_readlane_b32 s61, v165, 0
	v_readlane_b32 s62, v165, 1
	v_readlane_b32 s63, v165, 2
	v_readlane_b32 s64, v165, 3
	v_readlane_b32 s65, v165, 4
	v_readlane_b32 s66, v165, 5
	v_readlane_b32 s67, v165, 6
	s_mov_b64 s[46:47], s[54:55]
	s_waitcnt vmcnt(2)
	v_mov_b64_e32 v[14:15], v[6:7]
	v_mov_b64_e32 v[12:13], v[4:5]
	v_mov_b64_e32 v[10:11], v[2:3]
	v_mov_b64_e32 v[8:9], v[0:1]
	v_add_u32_e32 v112, s20, v56
	v_ashrrev_i32_e32 v113, 31, v112
	v_lshlrev_b64 v[112:113], 11, v[112:113]
	v_lshl_add_u64 v[112:113], v[66:67], 0, v[112:113]
	v_add_co_u32_e32 v114, vcc, 0x1000, v112
	s_nop 1
	v_addc_co_u32_e32 v115, vcc, 0, v113, vcc
	global_load_dwordx4 v[124:127], v[112:113], off offset:-4096
	global_load_dwordx4 v[128:131], v[112:113], off offset:-2048
	global_load_dwordx4 v[132:135], v[112:113], off
	global_load_dwordx4 v[136:139], v[112:113], off offset:2048
	global_load_dwordx4 v[140:143], v[114:115], off
	s_and_saveexec_b64 s[0:1], s[10:11]
	s_cbranch_execz .LBB0_1687
	v_add_u32_e32 v8, s20, v63
	v_ashrrev_i32_e32 v9, 31, v8
	v_lshlrev_b64 v[8:9], 11, v[8:9]
	v_lshl_add_u64 v[8:9], v[66:67], 0, v[8:9]
	s_waitcnt vmcnt(4)
	v_mov_b64_e32 v[8:9], v[124:125]
	v_mov_b64_e32 v[10:11], v[126:127]
	v_lshlrev_b32_e32 v64, 16, v8
	v_and_b32_e32 v65, 0xffff0000, v8
	v_lshlrev_b32_e32 v8, 16, v9
	v_and_b32_e32 v9, 0xffff0000, v9
	v_lshlrev_b32_e32 v12, 16, v10
	v_and_b32_e32 v13, 0xffff0000, v10
	v_lshlrev_b32_e32 v10, 16, v11
	v_and_b32_e32 v11, 0xffff0000, v11
	v_pk_fma_f32 v[14:15], v[54:55], v[10:11], v[6:7]
	v_pk_fma_f32 v[12:13], v[52:53], v[12:13], v[4:5]
	v_pk_fma_f32 v[10:11], v[50:51], v[8:9], v[2:3]
	v_pk_fma_f32 v[8:9], v[48:49], v[64:65], v[0:1]
; DEV float bf2f(unsigned short h) { return __uint_as_float(((unsigned)h) << 16); }
; DEV void phase_ml_conv(const Params& p, unsigned char* smem) {
;     ...
;       for (int w = 0; w < 5; ++w) {
;         int ts = tt + w - 2;
;         if (ts >= 0 && ts < seglen) {
;           uint4 v = *reinterpret_cast<const uint4*>(p.qb + (size_t)(segbase + ts) * 1024 + chbase + cg8);
;           a[0] += cw[w][0] * bf2f(v.x & 0xffff); a[1] += cw[w][1] * bf2f(v.x >> 16);
;           a[2] += cw[w][2] * bf2f(v.y & 0xffff); a[3] += cw[w][3] * bf2f(v.y >> 16);
;           a[4] += cw[w][4] * bf2f(v.z & 0xffff); a[5] += cw[w][5] * bf2f(v.z >> 16);
;           a[6] += cw[w][6] * bf2f(v.w & 0xffff); a[7] += cw[w][7] * bf2f(v.w >> 16);
;         }
.LBB0_1687:
	s_or_b64 exec, exec, s[0:1]
	v_cmp_lt_i32_e32 vcc, 0, v56
	v_cmp_ge_i32_e64 s[0:1], s21, v56
	s_and_b64 s[10:11], vcc, s[0:1]
	s_and_saveexec_b64 s[0:1], s[10:11]
	s_cbranch_execz .LBB0_1689
	v_add3_u32 v64, s20, -1, v56
	v_ashrrev_i32_e32 v65, 31, v64
	v_lshlrev_b64 v[64:65], 11, v[64:65]
	v_lshl_add_u64 v[64:65], v[66:67], 0, v[64:65]
	s_waitcnt vmcnt(3)
	v_mov_b64_e32 v[68:69], v[128:129]
	v_mov_b64_e32 v[70:71], v[130:131]
	v_lshlrev_b32_e32 v64, 16, v68
	v_and_b32_e32 v65, 0xffff0000, v68
	v_lshlrev_b32_e32 v68, 16, v69
	v_and_b32_e32 v69, 0xffff0000, v69
	v_lshlrev_b32_e32 v78, 16, v70
	v_and_b32_e32 v79, 0xffff0000, v70
	v_lshlrev_b32_e32 v70, 16, v71
	v_and_b32_e32 v71, 0xffff0000, v71
	v_pk_fma_f32 v[14:15], v[46:47], v[70:71], v[14:15]
	v_pk_fma_f32 v[12:13], v[44:45], v[78:79], v[12:13]
	v_pk_fma_f32 v[10:11], v[42:43], v[68:69], v[10:11]
	v_pk_fma_f32 v[8:9], v[40:41], v[64:65], v[8:9]
.LBB0_1689:
	s_or_b64 exec, exec, s[0:1]
	v_cmp_gt_u32_e32 vcc, s21, v56
	s_and_saveexec_b64 s[0:1], vcc
	s_cbranch_execz .LBB0_1691
	v_add_u32_e32 v64, s20, v56
	v_ashrrev_i32_e32 v65, 31, v64
	v_lshlrev_b64 v[64:65], 11, v[64:65]
	v_lshl_add_u64 v[64:65], v[66:67], 0, v[64:65]
	s_waitcnt vmcnt(2)
	v_mov_b64_e32 v[68:69], v[132:133]
	v_mov_b64_e32 v[70:71], v[134:135]
	v_lshlrev_b32_e32 v64, 16, v68
	v_and_b32_e32 v65, 0xffff0000, v68
	v_lshlrev_b32_e32 v68, 16, v69
	v_and_b32_e32 v69, 0xffff0000, v69
	v_lshlrev_b32_e32 v78, 16, v70
	v_and_b32_e32 v79, 0xffff0000, v70
	v_lshlrev_b32_e32 v70, 16, v71
	v_and_b32_e32 v71, 0xffff0000, v71
	v_pk_fma_f32 v[14:15], v[38:39], v[70:71], v[14:15]
	v_pk_fma_f32 v[12:13], v[36:37], v[78:79], v[12:13]
	v_pk_fma_f32 v[10:11], v[34:35], v[68:69], v[10:11]
	v_pk_fma_f32 v[8:9], v[32:33], v[64:65], v[8:9]
.LBB0_1691:
	s_or_b64 exec, exec, s[0:1]
	v_add_u32_e32 v63, 1, v56
	v_cmp_lt_i32_e32 vcc, -2, v56
	v_cmp_gt_i32_e64 s[0:1], s21, v63
	s_and_b64 s[10:11], vcc, s[0:1]
	s_and_saveexec_b64 s[0:1], s[10:11]
	s_cbranch_execz .LBB0_1693
	v_add_u32_e32 v64, s20, v63
	v_ashrrev_i32_e32 v65, 31, v64
	v_lshlrev_b64 v[64:65], 11, v[64:65]
	v_lshl_add_u64 v[64:65], v[66:67], 0, v[64:65]
	s_waitcnt vmcnt(1)
	v_mov_b64_e32 v[68:69], v[136:137]
	v_mov_b64_e32 v[70:71], v[138:139]
	v_lshlrev_b32_e32 v64, 16, v68
	v_and_b32_e32 v65, 0xffff0000, v68
	v_lshlrev_b32_e32 v68, 16, v69
	v_and_b32_e32 v69, 0xffff0000, v69
	v_lshlrev_b32_e32 v78, 16, v70
	v_and_b32_e32 v79, 0xffff0000, v70
	v_lshlrev_b32_e32 v70, 16, v71
	v_and_b32_e32 v71, 0xffff0000, v71
	v_pk_fma_f32 v[14:15], v[30:31], v[70:71], v[14:15]
	v_pk_fma_f32 v[12:13], v[28:29], v[78:79], v[12:13]
	v_pk_fma_f32 v[10:11], v[26:27], v[68:69], v[10:11]
	v_pk_fma_f32 v[8:9], v[24:25], v[64:65], v[8:9]
.LBB0_1693:
	s_or_b64 exec, exec, s[0:1]
	v_add_u32_e32 v63, 2, v56
	v_cmp_lt_i32_e32 vcc, -3, v56
	v_cmp_gt_i32_e64 s[0:1], s21, v63
	s_and_b64 s[10:11], vcc, s[0:1]
	s_and_saveexec_b64 s[0:1], s[10:11]
	s_cbranch_execz .LBB0_1695
	v_add_u32_e32 v64, s20, v63
	v_ashrrev_i32_e32 v65, 31, v64
	v_lshlrev_b64 v[64:65], 11, v[64:65]
	v_lshl_add_u64 v[64:65], v[66:67], 0, v[64:65]
	s_waitcnt vmcnt(0)
	v_mov_b64_e32 v[68:69], v[140:141]
	v_mov_b64_e32 v[70:71], v[142:143]
	v_lshlrev_b32_e32 v64, 16, v68
	v_and_b32_e32 v65, 0xffff0000, v68
	v_lshlrev_b32_e32 v68, 16, v69
	v_and_b32_e32 v69, 0xffff0000, v69
	v_lshlrev_b32_e32 v78, 16, v70
	v_and_b32_e32 v79, 0xffff0000, v70
	v_lshlrev_b32_e32 v70, 16, v71
	v_and_b32_e32 v71, 0xffff0000, v71
	v_pk_fma_f32 v[14:15], v[22:23], v[70:71], v[14:15]
	v_pk_fma_f32 v[12:13], v[20:21], v[78:79], v[12:13]
	v_pk_fma_f32 v[10:11], v[18:19], v[68:69], v[10:11]
	v_pk_fma_f32 v[8:9], v[16:17], v[64:65], v[8:9]

; DEV float bf2f(unsigned short h) { return __uint_as_float(((unsigned)h) << 16); }
; DEV void phase_ml_conv(const Params& p, unsigned char* smem) {
;     ...
;     for (int rr = 0; rr < 2; ++rr) {
;       const int tl = tr + rr * 32, tt = t0 + tl;
;       float a[8];
; #pragma unroll
;       for (int i = 0; i < 8; ++i) a[i] = cb[i];
; #pragma unroll
;       for (int w = 0; w < 5; ++w) {
;         int ts = tt + w - 2;
;         if (ts >= 0 && ts < seglen) {
;           uint4 v = *reinterpret_cast<const uint4*>(p.qb + (size_t)(segbase + ts) * 1024 + chbase + cg8);
;           a[0] += cw[w][0] * bf2f(v.x & 0xffff); a[1] += cw[w][1] * bf2f(v.x >> 16);
;           a[2] += cw[w][2] * bf2f(v.y & 0xffff); a[3] += cw[w][3] * bf2f(v.y >> 16);
;           a[4] += cw[w][4] * bf2f(v.z & 0xffff); a[5] += cw[w][5] * bf2f(v.z >> 16);
;           a[6] += cw[w][6] * bf2f(v.w & 0xffff); a[7] += cw[w][7] * bf2f(v.w >> 16);
;         }
.LBB0_1697:
	s_nop 0
	v_add_u32_e32 v8, s22, v75
	v_add_u32_e32 v9, -2, v8
	v_cmp_lt_i32_e32 vcc, 1, v8
	v_cmp_gt_i32_e64 s[0:1], s21, v9
	s_and_b64 s[10:11], vcc, s[0:1]
	v_add_u32_e32 v116, s20, v8
	v_ashrrev_i32_e32 v117, 31, v116
	v_lshlrev_b64 v[116:117], 11, v[116:117]
	v_lshl_add_u64 v[116:117], v[66:67], 0, v[116:117]
	v_add_co_u32_e32 v118, vcc, 0x1000, v116
	s_nop 1
	v_addc_co_u32_e32 v119, vcc, 0, v117, vcc
	global_load_dwordx4 v[144:147], v[116:117], off offset:-4096
	global_load_dwordx4 v[148:151], v[116:117], off offset:-2048
	global_load_dwordx4 v[152:155], v[116:117], off
	global_load_dwordx4 v[156:159], v[116:117], off offset:2048
	global_load_dwordx4 v[160:163], v[118:119], off
	s_and_saveexec_b64 s[0:1], s[10:11]
	s_cbranch_execz .LBB0_1699
	v_add_u32_e32 v10, s20, v9
	v_ashrrev_i32_e32 v11, 31, v10
	v_lshlrev_b64 v[10:11], 11, v[10:11]
	v_lshl_add_u64 v[10:11], v[66:67], 0, v[10:11]
	s_waitcnt vmcnt(4)
	v_mov_b64_e32 v[10:11], v[144:145]
	v_mov_b64_e32 v[12:13], v[146:147]
	v_lshlrev_b32_e32 v14, 16, v10
	v_and_b32_e32 v15, 0xffff0000, v10
	v_lshlrev_b32_e32 v10, 16, v11
	v_and_b32_e32 v11, 0xffff0000, v11
	v_lshlrev_b32_e32 v68, 16, v12
	v_and_b32_e32 v69, 0xffff0000, v12
	v_lshlrev_b32_e32 v12, 16, v13
	v_and_b32_e32 v13, 0xffff0000, v13
	v_pk_fma_f32 v[6:7], v[54:55], v[12:13], v[6:7]
	v_pk_fma_f32 v[4:5], v[52:53], v[68:69], v[4:5]
	v_pk_fma_f32 v[2:3], v[50:51], v[10:11], v[2:3]
	v_pk_fma_f32 v[0:1], v[48:49], v[14:15], v[0:1]
.LBB0_1699:
	s_or_b64 exec, exec, s[0:1]
	v_cmp_lt_i32_e32 vcc, 0, v8
	v_cmp_ge_i32_e64 s[0:1], s21, v8
	s_and_b64 s[10:11], vcc, s[0:1]
	s_and_saveexec_b64 s[0:1], s[10:11]
	s_cbranch_execz .LBB0_1701
	v_add3_u32 v10, s20, -1, v8
	v_ashrrev_i32_e32 v11, 31, v10
	v_lshlrev_b64 v[10:11], 11, v[10:11]
	v_lshl_add_u64 v[10:11], v[66:67], 0, v[10:11]
	s_waitcnt vmcnt(3)
	v_mov_b64_e32 v[10:11], v[148:149]
	v_mov_b64_e32 v[12:13], v[150:151]
	v_lshlrev_b32_e32 v14, 16, v10
	v_and_b32_e32 v15, 0xffff0000, v10
	v_lshlrev_b32_e32 v10, 16, v11
	v_and_b32_e32 v11, 0xffff0000, v11
	v_lshlrev_b32_e32 v48, 16, v12
	v_and_b32_e32 v49, 0xffff0000, v12
	v_lshlrev_b32_e32 v12, 16, v13
	v_and_b32_e32 v13, 0xffff0000, v13
	v_pk_fma_f32 v[6:7], v[46:47], v[12:13], v[6:7]
	v_pk_fma_f32 v[4:5], v[44:45], v[48:49], v[4:5]
	v_pk_fma_f32 v[2:3], v[42:43], v[10:11], v[2:3]
	v_pk_fma_f32 v[0:1], v[40:41], v[14:15], v[0:1]
.LBB0_1701:
	s_or_b64 exec, exec, s[0:1]
	v_cmp_gt_u32_e32 vcc, s21, v8
	s_and_saveexec_b64 s[0:1], vcc
	s_cbranch_execz .LBB0_1703
	v_add_u32_e32 v10, s20, v8
	v_ashrrev_i32_e32 v11, 31, v10
	v_lshlrev_b64 v[10:11], 11, v[10:11]
	v_lshl_add_u64 v[10:11], v[66:67], 0, v[10:11]
	s_waitcnt vmcnt(2)
	v_mov_b64_e32 v[10:11], v[152:153]
	v_mov_b64_e32 v[12:13], v[154:155]
	v_lshlrev_b32_e32 v14, 16, v10
	v_and_b32_e32 v15, 0xffff0000, v10
	v_lshlrev_b32_e32 v10, 16, v11
	v_and_b32_e32 v11, 0xffff0000, v11
	v_lshlrev_b32_e32 v40, 16, v12
	v_and_b32_e32 v41, 0xffff0000, v12
	v_lshlrev_b32_e32 v12, 16, v13
	v_and_b32_e32 v13, 0xffff0000, v13
	v_pk_fma_f32 v[6:7], v[38:39], v[12:13], v[6:7]
	v_pk_fma_f32 v[4:5], v[36:37], v[40:41], v[4:5]
	v_pk_fma_f32 v[2:3], v[34:35], v[10:11], v[2:3]
	v_pk_fma_f32 v[0:1], v[32:33], v[14:15], v[0:1]
.LBB0_1703:
	s_or_b64 exec, exec, s[0:1]
	v_add_u32_e32 v9, 1, v8
	v_cmp_lt_i32_e32 vcc, -2, v8
	v_cmp_gt_i32_e64 s[0:1], s21, v9
	s_and_b64 s[10:11], vcc, s[0:1]
	s_and_saveexec_b64 s[0:1], s[10:11]
	s_cbranch_execz .LBB0_1705
	v_add_u32_e32 v10, s20, v9
	v_ashrrev_i32_e32 v11, 31, v10
	v_lshlrev_b64 v[10:11], 11, v[10:11]
	v_lshl_add_u64 v[10:11], v[66:67], 0, v[10:11]
	s_waitcnt vmcnt(1)
	v_mov_b64_e32 v[10:11], v[156:157]
	v_mov_b64_e32 v[12:13], v[158:159]
	v_lshlrev_b32_e32 v14, 16, v10
	v_and_b32_e32 v15, 0xffff0000, v10
	v_lshlrev_b32_e32 v10, 16, v11
	v_and_b32_e32 v11, 0xffff0000, v11
	v_lshlrev_b32_e32 v32, 16, v12
	v_and_b32_e32 v33, 0xffff0000, v12
	v_lshlrev_b32_e32 v12, 16, v13
	v_and_b32_e32 v13, 0xffff0000, v13
	v_pk_fma_f32 v[6:7], v[30:31], v[12:13], v[6:7]
	v_pk_fma_f32 v[4:5], v[28:29], v[32:33], v[4:5]
	v_pk_fma_f32 v[2:3], v[26:27], v[10:11], v[2:3]
	v_pk_fma_f32 v[0:1], v[24:25], v[14:15], v[0:1]
.LBB0_1705:
	s_or_b64 exec, exec, s[0:1]
	v_add_u32_e32 v9, 2, v8
	v_cmp_lt_i32_e32 vcc, -3, v8
	v_cmp_gt_i32_e64 s[0:1], s21, v9
	s_and_b64 s[10:11], vcc, s[0:1]
	s_and_saveexec_b64 s[0:1], s[10:11]
	s_cbranch_execz .LBB0_1707
	v_add_u32_e32 v8, s20, v9
	v_ashrrev_i32_e32 v9, 31, v8
	v_lshlrev_b64 v[8:9], 11, v[8:9]
	v_lshl_add_u64 v[8:9], v[66:67], 0, v[8:9]
	s_waitcnt vmcnt(0)
	v_mov_b64_e32 v[8:9], v[160:161]
	v_mov_b64_e32 v[10:11], v[162:163]
	v_lshlrev_b32_e32 v12, 16, v8
	v_and_b32_e32 v13, 0xffff0000, v8
	v_lshlrev_b32_e32 v8, 16, v9
	v_and_b32_e32 v9, 0xffff0000, v9
	v_lshlrev_b32_e32 v14, 16, v10
	v_and_b32_e32 v15, 0xffff0000, v10
	v_lshlrev_b32_e32 v10, 16, v11
	v_and_b32_e32 v11, 0xffff0000, v11
	v_pk_fma_f32 v[6:7], v[22:23], v[10:11], v[6:7]
	v_pk_fma_f32 v[4:5], v[20:21], v[14:15], v[4:5]
	v_pk_fma_f32 v[2:3], v[18:19], v[8:9], v[2:3]
	v_pk_fma_f32 v[0:1], v[16:17], v[12:13], v[0:1]

; DEV void phase_ml_out(const Params& p, unsigned char* smem) {
;     ...
;     {
; #pragma unroll
;       for (int i = 0; i < 2; ++i) {
;         const int c = tid + i * 256, row = c >> 3, ch = c & 7;
;         *reinterpret_cast<uint4*>(sK + row * 144 + ch * 16) = *reinterpret_cast<const uint4*>(kp + (size_t)row * 64 + ch * 8);
;       }
; #pragma unroll
;       for (int i = 0; i < 4; ++i) {
;         const int c = tid + i * 256, row = c >> 3, ch = c & 7;
;         *reinterpret_cast<uint4*>(sV + row * 144 + ch * 16) = *reinterpret_cast<const uint4*>(vt + (size_t)row * TAU + ch * 8);
;       }
;     }
;     __syncthreads();
;     ...
;       const float den = __shfl(acc8[0], fr);
;       const float mt = sCum[dir * 64 + l] + mu;
;       const float inv = 1.f / fmaxf(fabsf(den), __expf(-mt));
; #pragma unroll
;       for (int ef = 0; ef < 8; ++ef) {
;         if ((ef & 3) == 0) asm volatile("" ::: "memory");
;         f32x4 a = f32x4{0.f, 0.f, 0.f, 0.f};
;         const unsigned char* vr = sV + (ef * 16 + fr) * 144;
; #pragma unroll
;         for (int ks2 = 0; ks2 < 2; ++ks2) {
;           bf16x8 Av = *reinterpret_cast<const bf16x8*>(vr + ks2 * 64 + fq * 16);
;           a = __builtin_amdgcn_mfma_f32_16x16x32_bf16(Av, bP[ks2], a, 0, 0, 0);
;         }
; #pragma unroll
;         for (int ks = 0; ks < 2; ++ks) {
;           bf16x8 As = *reinterpret_cast<const bf16x8*>(Sp + (size_t)(ef * 16 + fr) * 64 + ks * 32 + fq * 8);
;           a = __builtin_amdgcn_mfma_f32_16x16x32_bf16(As, qw[ks], a, 0, 0, 0);
;         }
;         hs[ef] += a * inv;
.LBB0_1948:
	s_or_b64 exec, exec, s[0:1]
	s_or_b32 s9, s9, s12
	s_lshl_b32 s0, s8, 6
	s_mul_i32 s1, s9, 0x2100
	s_add_i32 s0, s1, s0
	s_ashr_i32 s1, s0, 31
	s_lshl_b64 s[0:1], s[0:1], 7
	v_lshl_add_u64 v[8:9], v[50:51], 0, s[0:1]
	v_lshl_add_u64 v[4:5], v[8:9], 0, v[36:37]
	global_load_dwordx4 v[4:7], v[4:5], off
	s_mov_b64 vcc, s[40:41]
	v_readlane_b32 s36, v166, 7
	s_lshl_b32 s4, s9, 7
	s_mul_i32 s5, s9, 0x210000
	v_readlane_b32 s48, v166, 19
	s_mul_hi_i32 s4, s4, 0x4200
	v_readlane_b32 s49, v166, 20
	s_add_u32 s5, s48, s5
	s_addc_u32 s14, s49, s4
	s_lshl_b32 s4, s8, 7
	s_add_u32 s4, s5, s4
	s_addc_u32 s5, s14, 0
	v_mov_b32_e32 v63, v29
	v_readlane_b32 s40, v166, 11
	v_readlane_b32 s41, v166, 12
	v_mov_b32_e32 v106, 0
	v_lshl_add_u64 v[110:111], v[52:53], 0, s[0:1]
	s_mov_b32 s92, 0
	v_mov_b32_e32 v107, v106
	v_mov_b32_e32 v108, v106
	v_mov_b32_e32 v109, v106
	v_mov_b32_e32 v102, v106
	v_mov_b32_e32 v103, v106
	v_mov_b32_e32 v104, v106
	v_mov_b32_e32 v105, v106
	v_mov_b32_e32 v98, v106
	v_mov_b32_e32 v99, v106
	v_mov_b32_e32 v100, v106
	v_mov_b32_e32 v101, v106
	v_mov_b32_e32 v94, v106
	v_mov_b32_e32 v95, v106
	v_mov_b32_e32 v96, v106
	v_mov_b32_e32 v97, v106
	v_mov_b32_e32 v90, v106
	v_mov_b32_e32 v91, v106
	v_mov_b32_e32 v92, v106
	v_mov_b32_e32 v93, v106
	v_mov_b32_e32 v86, v106
	v_mov_b32_e32 v87, v106
	v_mov_b32_e32 v88, v106
	v_mov_b32_e32 v89, v106
	v_mov_b32_e32 v82, v106
	v_mov_b32_e32 v83, v106
	v_mov_b32_e32 v84, v106
	v_mov_b32_e32 v85, v106
	v_mov_b32_e32 v78, v106
	v_mov_b32_e32 v79, v106
	v_mov_b32_e32 v80, v106
	v_mov_b32_e32 v81, v106
	s_mov_b64 s[40:41], vcc
	v_readlane_b32 s37, v166, 8
	v_readlane_b32 s38, v166, 9
	v_readlane_b32 s39, v166, 10
	v_readlane_b32 s42, v166, 13
	v_readlane_b32 s43, v166, 14
	v_readlane_b32 s44, v166, 15
	v_readlane_b32 s45, v166, 16
	v_readlane_b32 s46, v166, 17
	v_readlane_b32 s47, v166, 18
	v_readlane_b32 s50, v166, 21
	v_readlane_b32 s51, v166, 22
	v_lshl_add_u64 v[12:13], v[8:9], 0, v[38:39]
	global_load_dwordx4 v[12:15], v[12:13], off
	v_lshl_add_u64 v[8:9], s[4:5], 0, v[62:63]
	s_mov_b64 s[4:5], -1
	v_lshl_add_u64 v[16:17], v[8:9], 0, v[40:41]
	global_load_dwordx4 v[16:19], v[16:17], off
	v_lshl_add_u64 v[20:21], v[8:9], 0, v[42:43]
	global_load_dwordx4 v[20:23], v[20:21], off
	v_lshl_add_u64 v[24:25], v[8:9], 0, v[44:45]
	global_load_dwordx4 v[24:27], v[24:25], off
	v_lshl_add_u64 v[150:151], v[8:9], 0, v[46:47]
	global_load_dwordx4 v[150:153], v[150:151], off
	s_waitcnt vmcnt(0)
	ds_write_b128 v33, v[4:7]
	ds_write_b128 v144, v[12:15]
	ds_write_b128 v145, v[16:19]
	ds_write_b128 v146, v[20:23]
	ds_write_b128 v147, v[24:27]
	ds_write_b128 v148, v[150:153]
	s_waitcnt lgkmcnt(0)
	s_barrier
	s_branch .LBB0_1950
.LBB0_1949:
	s_or_b64 exec, exec, s[0:1]
	v_mov_b32_e32 v115, v114
	v_and_b32_e32 v119, 0xffff0000, v13
	v_lshlrev_b32_e32 v118, 16, v13
	v_lshlrev_b64 v[24:25], 14, v[112:113]
	v_and_b32_e32 v113, 0xffff0000, v12
	v_lshlrev_b32_e32 v112, 16, v12
	v_pk_mul_f32 v[12:13], v[114:115], v[118:119]
	v_and_b32_e32 v119, 0xffff0000, v14
	v_lshlrev_b32_e32 v118, 16, v14
	v_and_b32_e32 v121, 0xffff0000, v15
	v_lshlrev_b32_e32 v120, 16, v15
	v_pk_mul_f32 v[112:113], v[114:115], v[112:113]
	v_pk_mul_f32 v[118:119], v[114:115], v[118:119]
	v_pk_mul_f32 v[14:15], v[114:115], v[120:121]
	v_bfe_u32 v115, v119, 16, 1
	v_bfe_u32 v114, v14, 16, 1
	v_bfe_u32 v150, v113, 16, 1
	v_bfe_u32 v151, v112, 16, 1
	v_add3_u32 v151, v112, v151, s7
	v_add3_u32 v150, v113, v150, s7
	v_add3_u32 v119, v119, v115, s7
	v_add3_u32 v14, v14, v114, s7
	v_perm_b32 v115, v27, v117, s6
	v_perm_b32 v114, v77, v75, s6
	v_perm_b32 v113, v73, v71, s6
	v_perm_b32 v112, v67, v69, s6
	v_bfe_u32 v26, v15, 16, 1
	v_bfe_u32 v120, v118, 16, 1
	v_bfe_u32 v121, v13, 16, 1
	v_bfe_u32 v149, v12, 16, 1
	v_add3_u32 v12, v12, v149, s7
	v_add3_u32 v13, v13, v121, s7
	v_add3_u32 v118, v118, v120, s7
	v_add3_u32 v15, v15, v26, s7
	v_perm_b32 v15, v15, v14, s2
	v_perm_b32 v14, v119, v118, s2
	v_perm_b32 v13, v13, v12, s2
	v_perm_b32 v12, v150, v151, s2
	s_xor_b64 s[0:1], s[4:5], -1
	v_mov_b32_e32 v67, v29
	v_mfma_f32_16x16x32_bf16 v[20:23], v[112:115], v[12:15], v[20:23]
	v_mov_b32_e32 v69, v29
	v_mov_b32_e32 v71, v29
	v_mov_b32_e32 v73, v29
	v_mov_b32_e32 v75, v29
	v_mov_b32_e32 v77, v29
	s_nop 2
	v_and_or_b32 v21, v126, 64, v142
	v_lshlrev_b32_e32 v21, 2, v21
	ds_bpermute_b32 v20, v21, v20
	ds_read_b32 v21, v63 offset:1024
	ds_read_b128 v[112:115], v31 offset:11328
	s_mov_b32 s92, 1
	s_waitcnt lgkmcnt(2)
	v_max_f32_e64 v20, |v20|, |v20|
	s_waitcnt lgkmcnt(1)
	v_add_f32_e32 v21, v65, v21
	v_mul_f32_e32 v21, 0xbfb8aa3b, v21
	v_exp_f32_e32 v21, v21
	v_mov_b32_e32 v65, v29
	v_max_f32_e32 v20, v20, v21
	v_div_scale_f32 v21, s[4:5], v20, v20, 1.0
	v_rcp_f32_e32 v22, v21
	s_mov_b64 s[4:5], 0
	v_fma_f32 v23, -v21, v22, 1.0
	v_fmac_f32_e32 v22, v23, v22
	v_div_scale_f32 v23, vcc, 1.0, v20, 1.0
	v_mul_f32_e32 v26, v23, v22
	v_fma_f32 v27, -v21, v26, v23
	v_fmac_f32_e32 v26, v27, v22
	v_fma_f32 v21, -v21, v26, v23
	v_div_fmas_f32 v21, v21, v22, v26
	v_lshl_add_u64 v[22:23], v[54:55], 0, v[24:25]
	v_lshl_add_u64 v[162:163], v[22:23], 0, v[28:29]
	global_load_dwordx4 v[150:153], v[162:163], off
	global_load_dwordx4 v[154:157], v[162:163], off offset:64
	v_lshl_add_u64 v[162:163], v[22:23], 0, v[64:65]
	global_load_dwordx4 v[158:161], v[162:163], off
	ds_read_b128 v[24:27], v31 offset:11264
	s_waitcnt lgkmcnt(0)
	v_mfma_f32_16x16x32_bf16 v[24:27], v[24:27], v[4:7], 0
	v_lshl_add_u64 v[118:119], v[22:23], 0, v[28:29]
	v_div_fixup_f32 v20, v21, v20, 1.0
	s_and_b64 vcc, exec, s[0:1]
	v_mfma_f32_16x16x32_bf16 v[24:27], v[112:115], v[8:11], v[24:27]
	s_waitcnt vmcnt(2)
; DEV void phase_ml_out(const Params& p, unsigned char* smem) {
;     ...
;       for (int ef = 0; ef < 8; ++ef) {
;         if ((ef & 3) == 0) asm volatile("" ::: "memory");
;         f32x4 a = f32x4{0.f, 0.f, 0.f, 0.f};
;         const unsigned char* vr = sV + (ef * 16 + fr) * 144;
; #pragma unroll
;         for (int ks2 = 0; ks2 < 2; ++ks2) {
;           bf16x8 Av = *reinterpret_cast<const bf16x8*>(vr + ks2 * 64 + fq * 16);
;           a = __builtin_amdgcn_mfma_f32_16x16x32_bf16(Av, bP[ks2], a, 0, 0, 0);
;         }
; #pragma unroll
;         for (int ks = 0; ks < 2; ++ks) {
;           bf16x8 As = *reinterpret_cast<const bf16x8*>(Sp + (size_t)(ef * 16 + fr) * 64 + ks * 32 + fq * 8);
;           a = __builtin_amdgcn_mfma_f32_16x16x32_bf16(As, qw[ks], a, 0, 0, 0);
;         }
;         hs[ef] += a * inv;
	v_mfma_f32_16x16x32_bf16 v[24:27], v[150:153], v[16:19], v[24:27]
	global_load_dwordx4 v[150:153], v[162:163], off offset:64
	v_lshl_add_u64 v[118:119], v[22:23], 0, v[64:65]
	s_waitcnt vmcnt(2)
	v_mfma_f32_16x16x32_bf16 v[24:27], v[154:157], v[12:15], v[24:27]
	v_lshl_add_u64 v[162:163], v[22:23], 0, v[66:67]
	global_load_dwordx4 v[154:157], v[162:163], off
	ds_read_b128 v[112:115], v31 offset:13632
	s_nop 6
	v_pk_fma_f32 v[108:109], v[20:21], v[26:27], v[108:109] op_sel_hi:[0,1,1]
	v_pk_fma_f32 v[106:107], v[20:21], v[24:25], v[106:107] op_sel_hi:[0,1,1]
	ds_read_b128 v[24:27], v31 offset:13568
	s_waitcnt lgkmcnt(0)
	v_mfma_f32_16x16x32_bf16 v[24:27], v[24:27], v[4:7], 0
	v_mfma_f32_16x16x32_bf16 v[24:27], v[112:115], v[8:11], v[24:27]
	s_waitcnt vmcnt(2)
	v_mfma_f32_16x16x32_bf16 v[24:27], v[158:161], v[16:19], v[24:27]
	global_load_dwordx4 v[158:161], v[162:163], off offset:64
	v_lshl_add_u64 v[118:119], v[22:23], 0, v[66:67]
	s_waitcnt vmcnt(2)
	v_mfma_f32_16x16x32_bf16 v[24:27], v[150:153], v[12:15], v[24:27]
	v_lshl_add_u64 v[162:163], v[22:23], 0, v[68:69]
	global_load_dwordx4 v[150:153], v[162:163], off
	ds_read_b128 v[112:115], v31 offset:15936
	s_nop 6
	v_pk_fma_f32 v[104:105], v[20:21], v[26:27], v[104:105] op_sel_hi:[0,1,1]
	v_pk_fma_f32 v[102:103], v[20:21], v[24:25], v[102:103] op_sel_hi:[0,1,1]
	ds_read_b128 v[24:27], v31 offset:15872
	s_waitcnt lgkmcnt(0)
	v_mfma_f32_16x16x32_bf16 v[24:27], v[24:27], v[4:7], 0
	v_mfma_f32_16x16x32_bf16 v[24:27], v[112:115], v[8:11], v[24:27]
	s_waitcnt vmcnt(2)
	v_mfma_f32_16x16x32_bf16 v[24:27], v[154:157], v[16:19], v[24:27]
	global_load_dwordx4 v[154:157], v[162:163], off offset:64
	v_lshl_add_u64 v[118:119], v[22:23], 0, v[68:69]
	s_waitcnt vmcnt(2)
	v_mfma_f32_16x16x32_bf16 v[24:27], v[158:161], v[12:15], v[24:27]
	v_lshl_add_u64 v[162:163], v[22:23], 0, v[70:71]
	global_load_dwordx4 v[158:161], v[162:163], off
	ds_read_b128 v[112:115], v31 offset:18240
	s_nop 6
	v_pk_fma_f32 v[100:101], v[20:21], v[26:27], v[100:101] op_sel_hi:[0,1,1]
	v_pk_fma_f32 v[98:99], v[20:21], v[24:25], v[98:99] op_sel_hi:[0,1,1]
	ds_read_b128 v[24:27], v31 offset:18176
	s_waitcnt lgkmcnt(0)
	v_mfma_f32_16x16x32_bf16 v[24:27], v[24:27], v[4:7], 0
	v_mfma_f32_16x16x32_bf16 v[24:27], v[112:115], v[8:11], v[24:27]
	s_waitcnt vmcnt(2)
	v_mfma_f32_16x16x32_bf16 v[24:27], v[150:153], v[16:19], v[24:27]
	global_load_dwordx4 v[150:153], v[162:163], off offset:64
	v_lshl_add_u64 v[118:119], v[22:23], 0, v[70:71]
	s_waitcnt vmcnt(2)
	v_mfma_f32_16x16x32_bf16 v[24:27], v[154:157], v[12:15], v[24:27]
	v_lshl_add_u64 v[162:163], v[22:23], 0, v[72:73]
	global_load_dwordx4 v[154:157], v[162:163], off
	ds_read_b128 v[112:115], v31 offset:20544
	s_nop 6
	v_pk_fma_f32 v[96:97], v[20:21], v[26:27], v[96:97] op_sel_hi:[0,1,1]
	v_pk_fma_f32 v[94:95], v[20:21], v[24:25], v[94:95] op_sel_hi:[0,1,1]
	ds_read_b128 v[24:27], v31 offset:20480
	s_waitcnt lgkmcnt(0)
	v_mfma_f32_16x16x32_bf16 v[24:27], v[24:27], v[4:7], 0
	v_mfma_f32_16x16x32_bf16 v[24:27], v[112:115], v[8:11], v[24:27]
	s_waitcnt vmcnt(2)
	v_mfma_f32_16x16x32_bf16 v[24:27], v[158:161], v[16:19], v[24:27]
	global_load_dwordx4 v[158:161], v[162:163], off offset:64
	v_lshl_add_u64 v[118:119], v[22:23], 0, v[72:73]
	s_waitcnt vmcnt(2)
	v_mfma_f32_16x16x32_bf16 v[24:27], v[150:153], v[12:15], v[24:27]
	v_lshl_add_u64 v[162:163], v[22:23], 0, v[74:75]
	global_load_dwordx4 v[150:153], v[162:163], off
	ds_read_b128 v[112:115], v31 offset:22848
	s_nop 6
	v_pk_fma_f32 v[92:93], v[20:21], v[26:27], v[92:93] op_sel_hi:[0,1,1]
	v_pk_fma_f32 v[90:91], v[20:21], v[24:25], v[90:91] op_sel_hi:[0,1,1]
	ds_read_b128 v[24:27], v31 offset:22784
	s_waitcnt lgkmcnt(0)
	v_mfma_f32_16x16x32_bf16 v[24:27], v[24:27], v[4:7], 0
	v_mfma_f32_16x16x32_bf16 v[24:27], v[112:115], v[8:11], v[24:27]
	s_waitcnt vmcnt(2)
	v_mfma_f32_16x16x32_bf16 v[24:27], v[154:157], v[16:19], v[24:27]
	global_load_dwordx4 v[154:157], v[162:163], off offset:64
	v_lshl_add_u64 v[118:119], v[22:23], 0, v[74:75]
	v_lshl_add_u64 v[22:23], v[22:23], 0, v[76:77]
	s_waitcnt vmcnt(2)
	v_mfma_f32_16x16x32_bf16 v[24:27], v[158:161], v[12:15], v[24:27]
	global_load_dwordx4 v[158:161], v[22:23], off
	ds_read_b128 v[112:115], v31 offset:25152
	s_nop 6
	v_pk_fma_f32 v[88:89], v[20:21], v[26:27], v[88:89] op_sel_hi:[0,1,1]
	v_pk_fma_f32 v[86:87], v[20:21], v[24:25], v[86:87] op_sel_hi:[0,1,1]
	ds_read_b128 v[24:27], v31 offset:25088
	s_waitcnt lgkmcnt(0)
	v_mfma_f32_16x16x32_bf16 v[24:27], v[24:27], v[4:7], 0
	v_mfma_f32_16x16x32_bf16 v[24:27], v[112:115], v[8:11], v[24:27]
	s_waitcnt vmcnt(2)
	v_mfma_f32_16x16x32_bf16 v[24:27], v[150:153], v[16:19], v[24:27]
	global_load_dwordx4 v[150:153], v[22:23], off offset:64
	s_waitcnt vmcnt(2)
	v_mfma_f32_16x16x32_bf16 v[24:27], v[154:157], v[12:15], v[24:27]
	s_nop 7
	v_pk_fma_f32 v[84:85], v[20:21], v[26:27], v[84:85] op_sel_hi:[0,1,1]
	v_pk_fma_f32 v[82:83], v[20:21], v[24:25], v[82:83] op_sel_hi:[0,1,1]
	ds_read_b128 v[24:27], v31 offset:27392
	s_waitcnt lgkmcnt(0)
	v_mfma_f32_16x16x32_bf16 v[4:7], v[24:27], v[4:7], 0
	ds_read_b128 v[24:27], v31 offset:27456
	s_waitcnt lgkmcnt(0)
	v_mfma_f32_16x16x32_bf16 v[4:7], v[24:27], v[8:11], v[4:7]
	s_waitcnt vmcnt(1)
	v_mfma_f32_16x16x32_bf16 v[4:7], v[158:161], v[16:19], v[4:7]
	s_waitcnt vmcnt(0)
	v_mfma_f32_16x16x32_bf16 v[4:7], v[150:153], v[12:15], v[4:7]
	s_nop 7
	v_pk_fma_f32 v[80:81], v[20:21], v[6:7], v[80:81] op_sel_hi:[0,1,1]
	v_pk_fma_f32 v[78:79], v[20:21], v[4:5], v[78:79] op_sel_hi:[0,1,1]
	s_cbranch_vccnz .LBB0_1895

; DEV void phase_ml_out(const Params& p, unsigned char* smem) {
;     ...
;       f32x4 acc8 = f32x4{0.f, 0.f, 0.f, 0.f};
;       {
;         bf16x8 a1;
; #pragma unroll
;         for (int i = 0; i < 8; ++i) a1[i] = fr == 0 ? (short)0x3F80 : (short)0;
;         acc8 = __builtin_amdgcn_mfma_f32_16x16x32_bf16(a1, bP[0], acc8, 0, 0, 0);
;         acc8 = __builtin_amdgcn_mfma_f32_16x16x32_bf16(a1, bP[1], acc8, 0, 0, 0);
; #pragma unroll
;         for (int ks = 0; ks < 2; ++ks) {
;           bf16x8 an;
; #pragma unroll
;           for (int i = 0; i < 8; ++i) an[i] = fr == 0 ? (short)f2bf(np[ks * 32 + fq * 8 + i]) : (short)0;
;           acc8 = __builtin_amdgcn_mfma_f32_16x16x32_bf16(an, qw[ks], acc8, 0, 0, 0);
;         }
.LBB0_1982:
	s_or_b64 exec, exec, s[0:1]
	v_mul_f32_e32 v20, v20, v120
	v_bfe_u32 v75, v20, 16, 1
	v_add3_u32 v75, v20, v75, s7
	v_mul_f32_e32 v20, v21, v149
	v_bfe_u32 v21, v20, 16, 1
	v_add3_u32 v120, v20, v21, s7
	v_mul_f32_e32 v20, v22, v121
	v_bfe_u32 v21, v20, 16, 1
	v_add3_u32 v121, v20, v21, s7
	v_mul_f32_e32 v20, v23, v151
	v_bfe_u32 v21, v20, 16, 1
	v_add3_u32 v149, v20, v21, s7
	v_mul_f32_e32 v20, v24, v150
	v_bfe_u32 v21, v20, 16, 1
	v_add3_u32 v150, v20, v21, s7
	v_mul_f32_e32 v20, v25, v153
	v_bfe_u32 v21, v20, 16, 1
	v_add3_u32 v151, v20, v21, s7
	v_mul_f32_e32 v20, v26, v152
	v_bfe_u32 v21, v20, 16, 1
	v_mul_f32_e32 v4, v4, v69
	v_add3_u32 v26, v20, v21, s7
	v_bfe_u32 v20, v4, 16, 1
	v_add3_u32 v20, v4, v20, s7
	v_mul_f32_e32 v4, v5, v73
	v_bfe_u32 v5, v4, 16, 1
	v_add3_u32 v21, v4, v5, s7
	v_mul_f32_e32 v4, v6, v71
	v_bfe_u32 v5, v4, 16, 1
	v_add3_u32 v22, v4, v5, s7
	v_mul_f32_e32 v4, v7, v114
	v_bfe_u32 v5, v4, 16, 1
	v_add3_u32 v23, v4, v5, s7
	v_mul_f32_e32 v4, v8, v77
	v_bfe_u32 v5, v4, 16, 1
	v_add3_u32 v6, v4, v5, s7
	v_mul_f32_e32 v4, v9, v118
	v_bfe_u32 v5, v4, 16, 1
	v_add3_u32 v8, v4, v5, s7
	v_mul_f32_e32 v4, v10, v115
	v_bfe_u32 v5, v4, 16, 1
	v_add3_u32 v7, v4, v5, s7
	v_mul_f32_e32 v4, v11, v119
	v_bfe_u32 v5, v4, 16, 1
	v_add3_u32 v9, v4, v5, s7
	v_mul_f32_e32 v4, v27, v154
	v_bfe_u32 v5, v4, 16, 1
	v_readlane_b32 s36, v166, 2
	v_add3_u32 v10, v4, v5, s7
	v_lshlrev_b64 v[4:5], 8, v[112:113]
	v_readlane_b32 s38, v166, 4
	v_readlane_b32 s39, v166, 5
	v_perm_b32 v7, v9, v7, s2
	v_perm_b32 v6, v8, v6, s2
	v_lshl_add_u64 v[24:25], s[38:39], 0, v[4:5]
	v_perm_b32 v5, v23, v22, s2
	v_perm_b32 v4, v21, v20, s2
	v_perm_b32 v11, v10, v26, s2
	v_perm_b32 v10, v151, v150, s2
	v_mfma_f32_16x16x32_bf16 v[20:23], v[0:3], v[4:7], 0
	v_perm_b32 v9, v149, v121, s2
	v_perm_b32 v8, v120, v75, s2
	v_lshlrev_b32_e32 v26, 2, v34
	v_readlane_b32 s37, v166, 3
	v_mfma_f32_16x16x32_bf16 v[20:23], v[0:3], v[8:11], v[20:23]
	s_and_saveexec_b64 s[0:1], s[24:25]
	s_cbranch_execz .LBB0_1984
	v_mov_b32_e32 v27, v29
	v_lshl_add_u64 v[114:115], v[24:25], 0, v[26:27]
	global_load_dword v117, v[114:115], off
.LBB0_1984:
	s_or_b64 exec, exec, s[0:1]
	v_mov_b32_e32 v73, 0
	v_mov_b32_e32 v71, 0
	s_and_saveexec_b64 s[0:1], s[24:25]
	s_cbranch_execz .LBB0_1986
	v_mov_b32_e32 v27, v29
	v_lshl_add_u64 v[114:115], v[24:25], 0, v[26:27]
	global_load_dword v71, v[114:115], off offset:4
.LBB0_1986:
	s_or_b64 exec, exec, s[0:1]
	s_and_saveexec_b64 s[0:1], s[24:25]
	s_cbranch_execz .LBB0_1988
	v_mov_b32_e32 v27, v29
	v_lshl_add_u64 v[114:115], v[24:25], 0, v[26:27]
	global_load_dword v73, v[114:115], off offset:8
.LBB0_1988:
	s_or_b64 exec, exec, s[0:1]
	v_mov_b32_e32 v77, 0
	v_mov_b32_e32 v75, 0
	s_and_saveexec_b64 s[0:1], s[24:25]
	s_cbranch_execz .LBB0_1990
	v_mov_b32_e32 v27, v29
	v_lshl_add_u64 v[114:115], v[24:25], 0, v[26:27]
	global_load_dword v75, v[114:115], off offset:12
.LBB0_1990:
	s_or_b64 exec, exec, s[0:1]
	s_and_saveexec_b64 s[0:1], s[24:25]
	s_cbranch_execz .LBB0_1992
	v_mov_b32_e32 v27, v29
	v_lshl_add_u64 v[114:115], v[24:25], 0, v[26:27]
	global_load_dword v77, v[114:115], off offset:16
.LBB0_1992:
	s_or_b64 exec, exec, s[0:1]
	v_mov_b32_e32 v118, 0
	v_mov_b32_e32 v115, 0
	s_and_saveexec_b64 s[0:1], s[24:25]
	s_cbranch_execz .LBB0_1994
	v_mov_b32_e32 v27, v29
	v_lshl_add_u64 v[114:115], v[24:25], 0, v[26:27]
	global_load_dword v115, v[114:115], off offset:20
.LBB0_1994:
	s_or_b64 exec, exec, s[0:1]
	s_and_saveexec_b64 s[0:1], s[24:25]
	s_cbranch_execz .LBB0_1996
	v_mov_b32_e32 v27, v29
	v_lshl_add_u64 v[118:119], v[24:25], 0, v[26:27]
	global_load_dword v118, v[118:119], off offset:24

; DEV float bf2f(unsigned short h) { return __uint_as_float(((unsigned)h) << 16); }
; DEV void phase_ml_out(const Params& p, unsigned char* smem) {
;     ...
;       const float winter = __expf(mprev - mu);
;       bf16x8 qw[2];
; #pragma unroll
;       for (int ks = 0; ks < 2; ++ks) {
;         bf16x8 o;
; #pragma unroll
;         for (int i = 0; i < 8; ++i) o[i] = (short)f2bf(bf2f((unsigned short)qf[ks][i]) * winter);
;         qw[ks] = o;
;     ...
;         for (int ks = 0; ks < 2; ++ks) {
;           bf16x8 an;
; #pragma unroll
;           for (int i = 0; i < 8; ++i) an[i] = fr == 0 ? (short)f2bf(np[ks * 32 + fq * 8 + i]) : (short)0;
;           acc8 = __builtin_amdgcn_mfma_f32_16x16x32_bf16(an, qw[ks], acc8, 0, 0, 0);
.LBB0_1998:
	s_or_b64 exec, exec, s[0:1]
	s_waitcnt vmcnt(0)
	s_and_saveexec_b64 s[0:1], s[24:25]
	v_bfe_u32 v69, v117, 16, 1
	v_add3_u32 v117, v117, v69, s7
	v_lshrrev_b32_e32 v117, 16, v117
	v_bfe_u32 v69, v71, 16, 1
	v_add3_u32 v71, v71, v69, s7
	v_lshrrev_b32_e32 v71, 16, v71
	v_bfe_u32 v69, v73, 16, 1
	v_add3_u32 v73, v73, v69, s7
	v_lshrrev_b32_e32 v73, 16, v73
	v_bfe_u32 v69, v75, 16, 1
	v_add3_u32 v75, v75, v69, s7
	v_lshrrev_b32_e32 v75, 16, v75
	v_bfe_u32 v69, v77, 16, 1
	v_add3_u32 v77, v77, v69, s7
	v_lshrrev_b32_e32 v77, 16, v77
	v_bfe_u32 v69, v115, 16, 1
	v_add3_u32 v115, v115, v69, s7
	v_lshrrev_b32_e32 v115, 16, v115
	v_bfe_u32 v69, v118, 16, 1
	v_add3_u32 v118, v118, v69, s7
	v_lshrrev_b32_e32 v118, 16, v118
	v_bfe_u32 v69, v27, 16, 1
	v_add3_u32 v27, v27, v69, s7
	v_lshrrev_b32_e32 v27, 16, v27
	s_or_b64 exec, exec, s[0:1]
	v_sub_f32_e32 v67, v67, v65
	v_mul_f32_e32 v67, 0x3fb8aa3b, v67
	v_exp_f32_e32 v114, v67
	v_and_b32_e32 v121, 0xffff0000, v16
	v_lshlrev_b32_e32 v120, 16, v16
	v_and_b32_e32 v151, 0xffff0000, v17
	v_lshlrev_b32_e32 v150, 16, v17
	v_and_b32_e32 v153, 0xffff0000, v19
	v_lshlrev_b32_e32 v152, 16, v19
	v_pk_mul_f32 v[120:121], v[114:115], v[120:121] op_sel_hi:[0,1]
	v_pk_mul_f32 v[16:17], v[114:115], v[150:151] op_sel_hi:[0,1]
	v_and_b32_e32 v151, 0xffff0000, v18
	v_lshlrev_b32_e32 v150, 16, v18
	v_pk_mul_f32 v[18:19], v[114:115], v[152:153] op_sel_hi:[0,1]
	v_bfe_u32 v119, v18, 16, 1
	v_bfe_u32 v155, v121, 16, 1
	v_bfe_u32 v156, v120, 16, 1
	v_add3_u32 v156, v120, v156, s7
	v_add3_u32 v155, v121, v155, s7
	v_add3_u32 v18, v18, v119, s7
	v_perm_b32 v121, v27, v118, s6
	v_perm_b32 v120, v115, v77, s6
	v_perm_b32 v119, v75, v73, s6
	v_perm_b32 v118, v71, v117, s6
	v_pk_mul_f32 v[150:151], v[114:115], v[150:151] op_sel_hi:[0,1]
	v_bfe_u32 v67, v19, 16, 1
	v_bfe_u32 v149, v151, 16, 1
	v_bfe_u32 v152, v150, 16, 1
	v_bfe_u32 v153, v17, 16, 1
	v_bfe_u32 v154, v16, 16, 1
	v_add3_u32 v16, v16, v154, s7
	v_add3_u32 v17, v17, v153, s7
	v_add3_u32 v150, v150, v152, s7
	v_add3_u32 v149, v151, v149, s7
	v_add3_u32 v19, v19, v67, s7
	v_perm_b32 v19, v19, v18, s2
	v_perm_b32 v18, v149, v150, s2
	v_perm_b32 v17, v17, v16, s2
	v_perm_b32 v16, v155, v156, s2
	s_nop 1
	v_mfma_f32_16x16x32_bf16 v[20:23], v[118:121], v[16:19], v[20:23]
	s_and_saveexec_b64 s[0:1], s[24:25]
	s_cbranch_execz .LBB0_2000
	v_mov_b32_e32 v27, v29
	v_lshl_add_u64 v[118:119], v[24:25], 0, v[26:27]
	global_load_dword v69, v[118:119], off offset:128
.LBB0_2000:
	s_or_b64 exec, exec, s[0:1]
	v_mov_b32_e32 v71, 0
	v_mov_b32_e32 v67, 0
	s_and_saveexec_b64 s[0:1], s[24:25]
	s_cbranch_execz .LBB0_2002
	v_mov_b32_e32 v27, v29
	v_lshl_add_u64 v[118:119], v[24:25], 0, v[26:27]
	global_load_dword v67, v[118:119], off offset:132
.LBB0_2002:
	s_or_b64 exec, exec, s[0:1]
	s_and_saveexec_b64 s[0:1], s[24:25]
	s_cbranch_execz .LBB0_2004
	v_mov_b32_e32 v27, v29
	v_lshl_add_u64 v[118:119], v[24:25], 0, v[26:27]
	global_load_dword v71, v[118:119], off offset:136
.LBB0_2004:
	s_or_b64 exec, exec, s[0:1]
	v_mov_b32_e32 v75, 0
	v_mov_b32_e32 v73, 0
	s_and_saveexec_b64 s[0:1], s[24:25]
	s_cbranch_execz .LBB0_2006
	v_mov_b32_e32 v27, v29
	v_lshl_add_u64 v[118:119], v[24:25], 0, v[26:27]
	global_load_dword v73, v[118:119], off offset:140
.LBB0_2006:
	s_or_b64 exec, exec, s[0:1]
	s_and_saveexec_b64 s[0:1], s[24:25]
	s_cbranch_execz .LBB0_2008
	v_mov_b32_e32 v27, v29
	v_lshl_add_u64 v[118:119], v[24:25], 0, v[26:27]
	global_load_dword v75, v[118:119], off offset:144
.LBB0_2008:
	s_or_b64 exec, exec, s[0:1]
	s_waitcnt vmcnt(0)
	s_and_saveexec_b64 s[0:1], s[24:25]
	v_bfe_u32 v27, v69, 16, 1
	v_add3_u32 v69, v69, v27, s7
	v_lshrrev_b32_e32 v69, 16, v69
	v_bfe_u32 v27, v67, 16, 1
	v_add3_u32 v67, v67, v27, s7
	v_lshrrev_b32_e32 v67, 16, v67
	v_bfe_u32 v27, v71, 16, 1
	v_add3_u32 v71, v71, v27, s7
	v_lshrrev_b32_e32 v71, 16, v71
	v_bfe_u32 v27, v73, 16, 1
	v_add3_u32 v73, v73, v27, s7
	v_lshrrev_b32_e32 v73, 16, v73
	v_bfe_u32 v27, v75, 16, 1
	v_add3_u32 v75, v75, v27, s7
	v_lshrrev_b32_e32 v75, 16, v75
	s_or_b64 exec, exec, s[0:1]
	v_mov_b32_e32 v117, 0
	v_mov_b32_e32 v77, 0
	s_and_saveexec_b64 s[0:1], s[24:25]
	s_cbranch_execnz .LBB0_2011
	s_or_b64 exec, exec, s[0:1]
	s_and_saveexec_b64 s[0:1], s[24:25]
	s_cbranch_execnz .LBB0_2012

; template <bool SWAP, class RowA, class Epi>
; DEV void gemm_tile(unsigned char* smem, RowA rowA, const bf16_t* Bt, int K, Epi epi) {
;     ...
;   for (int t = 0; t < nk; ++t) {
;     asm volatile("s_waitcnt vmcnt(0)" ::: "memory");
;     __syncthreads();
;     if (t + 1 < nk) stage(t + 1, (t + 1) & 1);
;     const unsigned char* SA = smem + (t & 1) * 16384;
;     const unsigned char* SB = SA + 8192;
;     bf16x8 At[4], Bl[4];
; #pragma unroll
;     for (int m = 0; m < 4; ++m) At[m] = *reinterpret_cast<const bf16x8*>(SA + (wr * 64 + m * 16) * 64 + rdoff);
; #pragma unroll
;     for (int n = 0; n < 4; ++n) Bl[n] = *reinterpret_cast<const bf16x8*>(SB + (wc * 64 + n * 16) * 64 + rdoff);
; #pragma unroll
;     for (int m = 0; m < 4; ++m)
; #pragma unroll
;       for (int n = 0; n < 4; ++n)
;         acc[m][n] = SWAP ? __builtin_amdgcn_mfma_f32_16x16x32_bf16(Bl[n], At[m], acc[m][n], 0, 0, 0)
;                          : __builtin_amdgcn_mfma_f32_16x16x32_bf16(At[m], Bl[n], acc[m][n], 0, 0, 0);
;   }
; DEV void phase_moe1(const Params& p, int l, unsigned char* smem) {
;     ...
; #pragma unroll
;         for (int n = 0; n < 2; ++n) {
;           const int acol = nt * 64 + wc * 32 + n * 16 + fq * 4;
;           const float4 bg4 = *reinterpret_cast<const float4*>(bgu + acol);
;           const float4 bl4 = *reinterpret_cast<const float4*>(bgu + 1024 + acol);
;           const float bgv[4] = {bg4.x, bg4.y, bg4.z, bg4.w}, blv[4] = {bl4.x, bl4.y, bl4.z, bl4.w};
; #pragma unroll
;           for (int m = 0; m < 4; ++m) {
;             const int i = mt * 128 + wr * 64 + m * 16 + fr;
;             if (i < cnt) {
.LBB0_2342:
	s_add_i32 s7, s6, 0x4000
	s_and_b32 s8, s7, 0x4000
	s_and_b32 s6, s6, 0x4000
	v_add_u32_e32 v100, s8, v70
	v_or_b32_e32 v72, s6, v71
	v_readfirstlane_b32 s6, v100
	v_add_u32_e32 v102, 0x1000, v100
	v_lshl_add_u64 v[92:93], v[64:65], 0, s[4:5]
	v_add_u32_e32 v101, 0x2000, v100
	v_readfirstlane_b32 s8, v102
	s_mov_b32 m0, s6
	s_waitcnt vmcnt(0)
	s_waitcnt vmcnt(0) lgkmcnt(0)
	s_barrier
	v_lshl_add_u64 v[94:95], v[66:67], 0, s[4:5]
	v_lshl_add_u64 v[96:97], v[68:69], 0, s[4:5]
	v_add_u32_e32 v100, 0x3000, v100
	v_readfirstlane_b32 s9, v101
	global_load_lds_dwordx4 v[92:93], off
	s_mov_b32 m0, s8
	v_lshl_add_u64 v[98:99], v[96:97], 0, s[18:19]
	v_readfirstlane_b32 s12, v100
	global_load_lds_dwordx4 v[94:95], off
	s_mov_b32 m0, s9
	v_lshl_add_u64 v[96:97], v[96:97], 0, s[20:21]
	global_load_lds_dwordx4 v[98:99], off
	s_mov_b32 m0, s12
	v_add_u32_e32 v116, v72, v80
	global_load_lds_dwordx4 v[96:97], off
	v_add_u32_e32 v72, v72, v81
	ds_read_b128 v[92:95], v72 offset:8192
	ds_read_b128 v[96:99], v72 offset:9216
	ds_read_b128 v[100:103], v116
	ds_read_b128 v[104:107], v116 offset:1024
	ds_read_b128 v[108:111], v72 offset:10240
	ds_read_b128 v[112:115], v72 offset:11264
	s_waitcnt lgkmcnt(0)
	v_mfma_f32_16x16x32_bf16 v[60:63], v[92:95], v[100:103], v[60:63]
	s_add_u32 s4, s4, 64
	s_addc_u32 s5, s5, 0
	s_cmpk_eq_i32 s4, 0x7c0
	v_mfma_f32_16x16x32_bf16 v[24:27], v[96:99], v[100:103], v[24:27]
	s_mov_b32 s6, s7
	v_mfma_f32_16x16x32_bf16 v[56:59], v[108:111], v[100:103], v[56:59]
	v_mfma_f32_16x16x32_bf16 v[28:31], v[112:115], v[100:103], v[28:31]
	v_mfma_f32_16x16x32_bf16 v[52:55], v[92:95], v[104:107], v[52:55]
	v_mfma_f32_16x16x32_bf16 v[16:19], v[96:99], v[104:107], v[16:19]
	v_mfma_f32_16x16x32_bf16 v[48:51], v[108:111], v[104:107], v[48:51]
	v_mfma_f32_16x16x32_bf16 v[20:23], v[112:115], v[104:107], v[20:23]
	ds_read_b128 v[100:103], v116 offset:2048
	ds_read_b128 v[104:107], v116 offset:3072
	s_waitcnt lgkmcnt(0)
	v_mfma_f32_16x16x32_bf16 v[44:47], v[92:95], v[100:103], v[44:47]
	v_mfma_f32_16x16x32_bf16 v[8:11], v[96:99], v[100:103], v[8:11]
	v_mfma_f32_16x16x32_bf16 v[36:39], v[108:111], v[100:103], v[36:39]
	v_mfma_f32_16x16x32_bf16 v[12:15], v[112:115], v[100:103], v[12:15]
	v_mfma_f32_16x16x32_bf16 v[32:35], v[92:95], v[104:107], v[32:35]
	v_mfma_f32_16x16x32_bf16 v[0:3], v[96:99], v[104:107], v[0:3]
	v_mfma_f32_16x16x32_bf16 v[40:43], v[108:111], v[104:107], v[40:43]
	v_mfma_f32_16x16x32_bf16 v[4:7], v[112:115], v[104:107], v[4:7]
	s_cbranch_scc0 .LBB0_2342
	v_add_u32_e32 v72, v71, v81
	s_waitcnt vmcnt(0)
	s_waitcnt vmcnt(0)
	s_barrier
	ds_read_b128 v[92:95], v72 offset:24576
	ds_read_b128 v[100:103], v72 offset:25600
	ds_read_b128 v[104:107], v72 offset:26624
	ds_read_b128 v[108:111], v72 offset:27648
	v_add_u32_e32 v80, v71, v80
	ds_read_b128 v[96:99], v80 offset:16384
	ds_read_b128 v[112:115], v80 offset:19456
	s_waitcnt lgkmcnt(1)
	v_mfma_f32_16x16x32_bf16 v[64:67], v[92:95], v[96:99], v[60:63]
	v_readlane_b32 s48, v166, 55
	v_readlane_b32 s60, v165, 3
	v_readlane_b32 s61, v165, 4
	v_mfma_f32_16x16x32_bf16 v[24:27], v[100:103], v[96:99], v[24:27]
	s_lshl_b64 s[0:1], s[0:1], 2
	s_mov_b64 s[12:13], s[60:61]
	s_add_u32 s0, s12, s0
	v_mfma_f32_16x16x32_bf16 v[68:71], v[104:107], v[96:99], v[56:59]
	s_addc_u32 s1, s13, s1
	s_lshl_b32 s4, s10, 6
	v_lshl_add_u32 v72, v78, 6, s11
	v_mfma_f32_16x16x32_bf16 v[28:31], v[108:111], v[96:99], v[28:31]
	ds_read_b128 v[96:99], v80 offset:17408
	v_or_b32_e32 v72, v72, v79
	v_add_u32_e32 v78, v72, v75
	s_waitcnt lgkmcnt(0)
	v_mfma_f32_16x16x32_bf16 v[56:59], v[92:95], v[96:99], v[52:55]
	v_cmp_lt_i32_e64 s[6:7], v72, v74
	v_ashrrev_i32_e32 v79, 31, v78
	v_readlane_b32 s49, v166, 56
	v_mfma_f32_16x16x32_bf16 v[16:19], v[100:103], v[96:99], v[16:19]
	v_readlane_b32 s50, v166, 57
	v_readlane_b32 s51, v166, 58
	v_readlane_b32 s52, v166, 59
	v_mfma_f32_16x16x32_bf16 v[60:63], v[104:107], v[96:99], v[48:51]
	v_readlane_b32 s53, v166, 60
	v_readlane_b32 s54, v166, 61
	v_readlane_b32 s55, v166, 62
	v_mfma_f32_16x16x32_bf16 v[20:23], v[108:111], v[96:99], v[20:23]
	ds_read_b128 v[96:99], v80 offset:18432
	v_readlane_b32 s56, v166, 63
	v_readlane_b32 s57, v165, 0
	s_waitcnt lgkmcnt(0)
	v_mfma_f32_16x16x32_bf16 v[48:51], v[92:95], v[96:99], v[44:47]
	v_readlane_b32 s58, v165, 1
	s_nop 1
	v_lshlrev_b32_e32 v44, 5, v76
	v_readlane_b32 s59, v165, 2
	v_mfma_f32_16x16x32_bf16 v[52:55], v[104:107], v[96:99], v[36:39]
	v_readlane_b32 s62, v165, 5
	v_readlane_b32 s63, v165, 6
	s_nop 0
	v_lshlrev_b32_e32 v36, 2, v77
	v_or3_b32 v76, v44, s4, v36
	v_ashrrev_i32_e32 v77, 31, v76
	v_lshlrev_b64 v[44:45], 2, v[76:77]
	v_lshl_add_u64 v[80:81], s[0:1], 0, v[44:45]
	s_add_u32 s0, s0, 0x1000
	s_addc_u32 s1, s1, 0
	v_lshl_add_u64 v[44:45], s[0:1], 0, v[44:45]
	global_load_dwordx4 v[36:39], v[80:81], off
	v_mfma_f32_16x16x32_bf16 v[8:11], v[100:103], v[96:99], v[8:11]
	global_load_dwordx4 v[44:47], v[44:45], off
	v_mfma_f32_16x16x32_bf16 v[12:15], v[108:111], v[96:99], v[12:15]
	v_mfma_f32_16x16x32_bf16 v[32:35], v[92:95], v[112:115], v[32:35]
	v_mfma_f32_16x16x32_bf16 v[0:3], v[100:103], v[112:115], v[0:3]
	v_mfma_f32_16x16x32_bf16 v[40:43], v[104:107], v[112:115], v[40:43]
	v_mfma_f32_16x16x32_bf16 v[4:7], v[108:111], v[112:115], v[4:7]
	s_waitcnt vmcnt(0)
	s_and_saveexec_b64 s[4:5], s[6:7]
	s_cbranch_execz .LBB0_2345
; DEV unsigned pack2(float a, float b) { return (unsigned)f2bf(a) | ((unsigned)f2bf(b) << 16); }
; DEV float sigmoidf_(float x) { return 1.f / (1.f + __expf(-x)); }
; DEV void phase_moe1(const Params& p, int l, unsigned char* smem) {
;     ...
;         for (int n = 0; n < 2; ++n) {
;           const int acol = nt * 64 + wc * 32 + n * 16 + fq * 4;
;           const float4 bg4 = *reinterpret_cast<const float4*>(bgu + acol);
;           const float4 bl4 = *reinterpret_cast<const float4*>(bgu + 1024 + acol);
;           const float bgv[4] = {bg4.x, bg4.y, bg4.z, bg4.w}, blv[4] = {bl4.x, bl4.y, bl4.z, bl4.w};
; #pragma unroll
;           for (int m = 0; m < 4; ++m) {
;             const int i = mt * 128 + wr * 64 + m * 16 + fr;
;             if (i < cnt) {
;               float a[4];
; #pragma unroll
;               for (int j = 0; j < 4; ++j) {
;                 float gl = fminf(acc[m][n][j] + bgv[j], 7.f);
;                 float li = fminf(fmaxf(acc[m][n + 2][j] + blv[j], -7.f), 7.f);
;                 a[j] = gl * sigmoidf_(1.702f * gl) * (li + 1.f);
;               }
;               *reinterpret_cast<uint2*>(p.act + (size_t)(rowoff + i) * 1024 + acol) = make_uint2(pack2(a[0], a[1]), pack2(a[2], a[3]));
;             }
;           }
	v_add_f32_e32 v65, v65, v37
	v_min_f32_e32 v94, 0x40e00000, v65
	v_add_f32_e32 v65, v69, v45
	v_med3_f32 v96, v65, s2, v89
	v_mul_f32_e32 v65, 0x3fd9db23, v94
	v_mul_f32_e32 v65, 0xbfb8aa3b, v65
	v_add_f32_e32 v64, v64, v36
	v_exp_f32_e32 v98, v65
	v_add_f32_e32 v65, v66, v38
	v_min_f32_e32 v64, 0x40e00000, v64
	v_min_f32_e32 v65, 0x40e00000, v65
	v_add_f32_e32 v66, v70, v46
	v_mul_f32_e32 v92, 0x3fd9db23, v64
	v_med3_f32 v69, v66, s2, v89
	v_mul_f32_e32 v66, 0x3fd9db23, v65
	v_mul_f32_e32 v92, 0xbfb8aa3b, v92
	v_mul_f32_e32 v66, 0xbfb8aa3b, v66
	v_exp_f32_e32 v92, v92
	v_exp_f32_e32 v93, v66
	v_add_f32_e32 v66, v67, v39
	v_min_f32_e32 v95, 0x40e00000, v66
	v_add_f32_e32 v66, v71, v47
	v_med3_f32 v97, v66, s2, v89
	v_mul_f32_e32 v66, 0x3fd9db23, v95
	v_mul_f32_e32 v66, 0xbfb8aa3b, v66
	v_exp_f32_e32 v99, v66
	v_pk_add_f32 v[66:67], v[92:93], 1.0 op_sel_hi:[1,0]
	v_add_f32_e32 v68, v68, v44
	v_div_scale_f32 v92, s[8:9], v67, v67, 1.0
	v_rcp_f32_e32 v93, v92
	v_med3_f32 v68, v68, s2, v89
	v_lshlrev_b64 v[70:71], 11, v[78:79]
	v_lshl_add_u64 v[70:71], s[80:81], 0, v[70:71]
	v_fma_f32 v100, -v92, v93, 1.0
	v_fmac_f32_e32 v93, v100, v93
	v_div_scale_f32 v100, vcc, 1.0, v67, 1.0
	v_mul_f32_e32 v101, v100, v93
	v_fma_f32 v102, -v92, v101, v100
	v_fmac_f32_e32 v101, v102, v93
	v_fma_f32 v92, -v92, v101, v100
	v_div_scale_f32 v100, s[8:9], v66, v66, 1.0
	v_rcp_f32_e32 v102, v100
	v_div_fmas_f32 v92, v92, v93, v101
	v_div_fixup_f32 v67, v92, v67, 1.0
	v_lshl_add_u64 v[70:71], v[76:77], 1, v[70:71]
	v_fma_f32 v92, -v100, v102, 1.0
	v_fmac_f32_e32 v102, v92, v102
	v_div_scale_f32 v92, vcc, 1.0, v66, 1.0
	v_mul_f32_e32 v93, v92, v102
	v_fma_f32 v101, -v100, v93, v92
	v_fmac_f32_e32 v93, v101, v102
	v_fma_f32 v92, -v100, v93, v92
	v_div_fmas_f32 v92, v92, v102, v93
	v_div_fixup_f32 v66, v92, v66, 1.0
	v_pk_add_f32 v[92:93], v[98:99], 1.0 op_sel_hi:[1,0]
	v_pk_mul_f32 v[64:65], v[64:65], v[66:67]
	v_div_scale_f32 v98, s[8:9], v93, v93, 1.0
	v_rcp_f32_e32 v99, v98
	v_pk_add_f32 v[66:67], v[68:69], 1.0 op_sel_hi:[1,0]
	s_nop 0
	v_pk_mul_f32 v[64:65], v[66:67], v[64:65]
	v_fma_f32 v66, -v98, v99, 1.0
	v_fmac_f32_e32 v99, v66, v99
	v_div_scale_f32 v66, vcc, 1.0, v93, 1.0
	v_mul_f32_e32 v67, v66, v99
	v_fma_f32 v68, -v98, v67, v66
	v_fmac_f32_e32 v67, v68, v99
	v_div_scale_f32 v68, s[8:9], v92, v92, 1.0
	v_rcp_f32_e32 v69, v68
	v_fma_f32 v66, -v98, v67, v66
	v_div_fmas_f32 v66, v66, v99, v67
	v_div_fixup_f32 v67, v66, v93, 1.0
	v_fma_f32 v66, -v68, v69, 1.0
	v_fmac_f32_e32 v69, v66, v69
	v_div_scale_f32 v66, vcc, 1.0, v92, 1.0
	v_mul_f32_e32 v93, v66, v69
	v_fma_f32 v98, -v68, v93, v66
	v_fmac_f32_e32 v93, v98, v69
	v_fma_f32 v66, -v68, v93, v66
	v_div_fmas_f32 v66, v66, v69, v93
	v_div_fixup_f32 v66, v66, v92, 1.0
	v_pk_mul_f32 v[66:67], v[94:95], v[66:67]
	v_pk_add_f32 v[68:69], v[96:97], 1.0 op_sel_hi:[1,0]
	s_nop 0
	v_pk_mul_f32 v[66:67], v[68:69], v[66:67]
	v_and_b32_sdwa v68, v65, v90 dst_sel:DWORD dst_unused:UNUSED_PAD src0_sel:WORD_1 src1_sel:DWORD
	v_and_b32_sdwa v69, v64, v90 dst_sel:DWORD dst_unused:UNUSED_PAD src0_sel:WORD_1 src1_sel:DWORD
	v_add3_u32 v64, v64, v69, s3
	v_add3_u32 v65, v65, v68, s3
	v_and_b32_sdwa v68, v67, v90 dst_sel:DWORD dst_unused:UNUSED_PAD src0_sel:WORD_1 src1_sel:DWORD
	v_and_b32_sdwa v69, v66, v90 dst_sel:DWORD dst_unused:UNUSED_PAD src0_sel:WORD_1 src1_sel:DWORD
	v_add3_u32 v67, v67, v68, s3
	v_add3_u32 v66, v66, v69, s3
	v_and_b32_e32 v67, 0xffff0000, v67
	v_and_b32_e32 v66, 0xffff0000, v66
	v_or_b32_sdwa v65, v67, v65 dst_sel:DWORD dst_unused:UNUSED_PAD src0_sel:DWORD src1_sel:WORD_1
	v_or_b32_sdwa v64, v66, v64 dst_sel:DWORD dst_unused:UNUSED_PAD src0_sel:DWORD src1_sel:WORD_1
	global_store_dwordx2 v[70:71], v[64:65], off
.LBB0_2345:
	s_or_b64 exec, exec, s[4:5]
	v_or_b32_e32 v64, 16, v72
	v_cmp_lt_i32_e64 s[8:9], v64, v74
	v_add_u32_e32 v64, v64, v75
	v_ashrrev_i32_e32 v65, 31, v64
	s_and_saveexec_b64 s[4:5], s[8:9]
	s_cbranch_execz .LBB0_2347
	v_add_f32_e32 v57, v57, v37
	v_min_f32_e32 v68, 0x40e00000, v57
	v_add_f32_e32 v57, v61, v45
	v_med3_f32 v70, v57, s2, v89
	v_mul_f32_e32 v57, 0x3fd9db23, v68
	v_mul_f32_e32 v57, 0xbfb8aa3b, v57
	v_add_f32_e32 v56, v56, v36
	v_exp_f32_e32 v92, v57
	v_add_f32_e32 v57, v58, v38
	v_min_f32_e32 v56, 0x40e00000, v56
	v_min_f32_e32 v57, 0x40e00000, v57
	v_add_f32_e32 v58, v62, v46
	v_mul_f32_e32 v66, 0x3fd9db23, v56
	v_med3_f32 v61, v58, s2, v89
	v_mul_f32_e32 v58, 0x3fd9db23, v57
	v_mul_f32_e32 v66, 0xbfb8aa3b, v66
	v_mul_f32_e32 v58, 0xbfb8aa3b, v58
	v_exp_f32_e32 v66, v66
	v_exp_f32_e32 v67, v58
	v_add_f32_e32 v58, v59, v39
	v_min_f32_e32 v69, 0x40e00000, v58
	v_add_f32_e32 v58, v63, v47
	v_med3_f32 v71, v58, s2, v89
	v_mul_f32_e32 v58, 0x3fd9db23, v69
	v_mul_f32_e32 v58, 0xbfb8aa3b, v58
	v_exp_f32_e32 v93, v58
	v_pk_add_f32 v[58:59], v[66:67], 1.0 op_sel_hi:[1,0]
	v_add_f32_e32 v60, v60, v44
	v_div_scale_f32 v66, s[10:11], v59, v59, 1.0
	v_rcp_f32_e32 v67, v66
	v_med3_f32 v60, v60, s2, v89
	v_lshlrev_b64 v[62:63], 11, v[64:65]
	v_lshl_add_u64 v[62:63], s[80:81], 0, v[62:63]
	v_fma_f32 v94, -v66, v67, 1.0
	v_fmac_f32_e32 v67, v94, v67
	v_div_scale_f32 v94, vcc, 1.0, v59, 1.0
	v_mul_f32_e32 v95, v94, v67
	v_fma_f32 v96, -v66, v95, v94
	v_fmac_f32_e32 v95, v96, v67
	v_fma_f32 v66, -v66, v95, v94
	v_div_scale_f32 v94, s[10:11], v58, v58, 1.0
	v_rcp_f32_e32 v96, v94
	v_div_fmas_f32 v66, v66, v67, v95
	v_div_fixup_f32 v59, v66, v59, 1.0
	v_lshl_add_u64 v[62:63], v[76:77], 1, v[62:63]
	v_fma_f32 v66, -v94, v96, 1.0
	v_fmac_f32_e32 v96, v66, v96
	v_div_scale_f32 v66, vcc, 1.0, v58, 1.0
	v_mul_f32_e32 v67, v66, v96
	v_fma_f32 v95, -v94, v67, v66
	v_fmac_f32_e32 v67, v95, v96
; DEV unsigned pack2(float a, float b) { return (unsigned)f2bf(a) | ((unsigned)f2bf(b) << 16); }
; DEV float sigmoidf_(float x) { return 1.f / (1.f + __expf(-x)); }
; DEV void phase_moe1(const Params& p, int l, unsigned char* smem) {
;     ...
;         for (int n = 0; n < 2; ++n) {
;           const int acol = nt * 64 + wc * 32 + n * 16 + fq * 4;
;           const float4 bg4 = *reinterpret_cast<const float4*>(bgu + acol);
;           const float4 bl4 = *reinterpret_cast<const float4*>(bgu + 1024 + acol);
;           const float bgv[4] = {bg4.x, bg4.y, bg4.z, bg4.w}, blv[4] = {bl4.x, bl4.y, bl4.z, bl4.w};
; #pragma unroll
;           for (int m = 0; m < 4; ++m) {
;             const int i = mt * 128 + wr * 64 + m * 16 + fr;
;             if (i < cnt) {
;               float a[4];
; #pragma unroll
;               for (int j = 0; j < 4; ++j) {
;                 float gl = fminf(acc[m][n][j] + bgv[j], 7.f);
;                 float li = fminf(fmaxf(acc[m][n + 2][j] + blv[j], -7.f), 7.f);
;                 a[j] = gl * sigmoidf_(1.702f * gl) * (li + 1.f);
;               }
;               *reinterpret_cast<uint2*>(p.act + (size_t)(rowoff + i) * 1024 + acol) = make_uint2(pack2(a[0], a[1]), pack2(a[2], a[3]));
;             }
;           }
	v_fma_f32 v66, -v94, v67, v66
	v_div_fmas_f32 v66, v66, v96, v67
	v_div_fixup_f32 v58, v66, v58, 1.0
	v_pk_add_f32 v[66:67], v[92:93], 1.0 op_sel_hi:[1,0]
	v_pk_mul_f32 v[56:57], v[56:57], v[58:59]
	v_div_scale_f32 v92, s[10:11], v67, v67, 1.0
	v_rcp_f32_e32 v93, v92
	v_pk_add_f32 v[58:59], v[60:61], 1.0 op_sel_hi:[1,0]
	s_nop 0
	v_pk_mul_f32 v[56:57], v[58:59], v[56:57]
	v_fma_f32 v58, -v92, v93, 1.0
	v_fmac_f32_e32 v93, v58, v93
	v_div_scale_f32 v58, vcc, 1.0, v67, 1.0
	v_mul_f32_e32 v59, v58, v93
	v_fma_f32 v60, -v92, v59, v58
	v_fmac_f32_e32 v59, v60, v93
	v_div_scale_f32 v60, s[10:11], v66, v66, 1.0
	v_rcp_f32_e32 v61, v60
	v_fma_f32 v58, -v92, v59, v58
	v_div_fmas_f32 v58, v58, v93, v59
	v_div_fixup_f32 v59, v58, v67, 1.0
	v_fma_f32 v58, -v60, v61, 1.0
	v_fmac_f32_e32 v61, v58, v61
	v_div_scale_f32 v58, vcc, 1.0, v66, 1.0
	v_mul_f32_e32 v67, v58, v61
	v_fma_f32 v92, -v60, v67, v58
	v_fmac_f32_e32 v67, v92, v61
	v_fma_f32 v58, -v60, v67, v58
	v_div_fmas_f32 v58, v58, v61, v67
	v_div_fixup_f32 v58, v58, v66, 1.0
	v_pk_mul_f32 v[58:59], v[68:69], v[58:59]
	v_pk_add_f32 v[60:61], v[70:71], 1.0 op_sel_hi:[1,0]
	s_nop 0
	v_pk_mul_f32 v[58:59], v[60:61], v[58:59]
	v_and_b32_sdwa v60, v57, v90 dst_sel:DWORD dst_unused:UNUSED_PAD src0_sel:WORD_1 src1_sel:DWORD
	v_and_b32_sdwa v61, v56, v90 dst_sel:DWORD dst_unused:UNUSED_PAD src0_sel:WORD_1 src1_sel:DWORD
	v_add3_u32 v56, v56, v61, s3
	v_add3_u32 v57, v57, v60, s3
	v_and_b32_sdwa v60, v59, v90 dst_sel:DWORD dst_unused:UNUSED_PAD src0_sel:WORD_1 src1_sel:DWORD
	v_and_b32_sdwa v61, v58, v90 dst_sel:DWORD dst_unused:UNUSED_PAD src0_sel:WORD_1 src1_sel:DWORD
	v_add3_u32 v59, v59, v60, s3
	v_add3_u32 v58, v58, v61, s3
	v_and_b32_e32 v59, 0xffff0000, v59
	v_and_b32_e32 v58, 0xffff0000, v58
	v_or_b32_sdwa v57, v59, v57 dst_sel:DWORD dst_unused:UNUSED_PAD src0_sel:DWORD src1_sel:WORD_1
	v_or_b32_sdwa v56, v58, v56 dst_sel:DWORD dst_unused:UNUSED_PAD src0_sel:DWORD src1_sel:WORD_1
	global_store_dwordx2 v[62:63], v[56:57], off
.LBB0_2347:
	s_or_b64 exec, exec, s[4:5]
	v_or_b32_e32 v56, 32, v72
	v_cmp_lt_i32_e64 s[10:11], v56, v74
	v_add_u32_e32 v56, v56, v75
	v_ashrrev_i32_e32 v57, 31, v56
	s_and_saveexec_b64 s[4:5], s[10:11]
	s_cbranch_execz .LBB0_2349
	v_add_f32_e32 v49, v49, v37
	v_min_f32_e32 v60, 0x40e00000, v49
	v_add_f32_e32 v49, v53, v45
	v_med3_f32 v62, v49, s2, v89
	v_mul_f32_e32 v49, 0x3fd9db23, v60
	v_mul_f32_e32 v49, 0xbfb8aa3b, v49
	v_add_f32_e32 v48, v48, v36
	v_exp_f32_e32 v66, v49
	v_add_f32_e32 v49, v50, v38
	v_min_f32_e32 v48, 0x40e00000, v48
	v_min_f32_e32 v49, 0x40e00000, v49
	v_add_f32_e32 v50, v54, v46
	v_mul_f32_e32 v58, 0x3fd9db23, v48
	v_med3_f32 v53, v50, s2, v89
	v_mul_f32_e32 v50, 0x3fd9db23, v49
	v_mul_f32_e32 v58, 0xbfb8aa3b, v58
	v_mul_f32_e32 v50, 0xbfb8aa3b, v50
	v_exp_f32_e32 v58, v58
	v_exp_f32_e32 v59, v50
	v_add_f32_e32 v50, v51, v39
	v_min_f32_e32 v61, 0x40e00000, v50
	v_add_f32_e32 v50, v55, v47
	v_med3_f32 v63, v50, s2, v89
	v_mul_f32_e32 v50, 0x3fd9db23, v61
	v_mul_f32_e32 v50, 0xbfb8aa3b, v50
	v_exp_f32_e32 v67, v50
	v_pk_add_f32 v[50:51], v[58:59], 1.0 op_sel_hi:[1,0]
	v_add_f32_e32 v52, v52, v44
	v_div_scale_f32 v58, s[12:13], v51, v51, 1.0
	v_rcp_f32_e32 v59, v58
	v_med3_f32 v52, v52, s2, v89
	v_lshlrev_b64 v[54:55], 11, v[56:57]
	v_lshl_add_u64 v[54:55], s[80:81], 0, v[54:55]
	v_fma_f32 v68, -v58, v59, 1.0
	v_fmac_f32_e32 v59, v68, v59
	v_div_scale_f32 v68, vcc, 1.0, v51, 1.0
	v_mul_f32_e32 v69, v68, v59
	v_fma_f32 v70, -v58, v69, v68
	v_fmac_f32_e32 v69, v70, v59
	v_fma_f32 v58, -v58, v69, v68
	v_div_scale_f32 v68, s[12:13], v50, v50, 1.0
	v_rcp_f32_e32 v70, v68
	v_div_fmas_f32 v58, v58, v59, v69
	v_div_fixup_f32 v51, v58, v51, 1.0
	v_lshl_add_u64 v[54:55], v[76:77], 1, v[54:55]
	v_fma_f32 v58, -v68, v70, 1.0
	v_fmac_f32_e32 v70, v58, v70
	v_div_scale_f32 v58, vcc, 1.0, v50, 1.0
	v_mul_f32_e32 v59, v58, v70
	v_fma_f32 v69, -v68, v59, v58
	v_fmac_f32_e32 v59, v69, v70
	v_fma_f32 v58, -v68, v59, v58
	v_div_fmas_f32 v58, v58, v70, v59
	v_div_fixup_f32 v50, v58, v50, 1.0
	v_pk_add_f32 v[58:59], v[66:67], 1.0 op_sel_hi:[1,0]
	v_pk_mul_f32 v[48:49], v[48:49], v[50:51]
	v_div_scale_f32 v66, s[12:13], v59, v59, 1.0
	v_rcp_f32_e32 v67, v66
	v_pk_add_f32 v[50:51], v[52:53], 1.0 op_sel_hi:[1,0]
	s_nop 0
	v_pk_mul_f32 v[48:49], v[50:51], v[48:49]
	v_fma_f32 v50, -v66, v67, 1.0
	v_fmac_f32_e32 v67, v50, v67
	v_div_scale_f32 v50, vcc, 1.0, v59, 1.0
	v_mul_f32_e32 v51, v50, v67
	v_fma_f32 v52, -v66, v51, v50
	v_fmac_f32_e32 v51, v52, v67
	v_div_scale_f32 v52, s[12:13], v58, v58, 1.0
	v_rcp_f32_e32 v53, v52
	v_fma_f32 v50, -v66, v51, v50
	v_div_fmas_f32 v50, v50, v67, v51
	v_div_fixup_f32 v51, v50, v59, 1.0
	v_fma_f32 v50, -v52, v53, 1.0
	v_fmac_f32_e32 v53, v50, v53
	v_div_scale_f32 v50, vcc, 1.0, v58, 1.0
	v_mul_f32_e32 v59, v50, v53
	v_fma_f32 v66, -v52, v59, v50
	v_fmac_f32_e32 v59, v66, v53
	v_fma_f32 v50, -v52, v59, v50
	v_div_fmas_f32 v50, v50, v53, v59
	v_div_fixup_f32 v50, v50, v58, 1.0
	v_pk_mul_f32 v[50:51], v[60:61], v[50:51]
	v_pk_add_f32 v[52:53], v[62:63], 1.0 op_sel_hi:[1,0]
	s_nop 0
	v_pk_mul_f32 v[50:51], v[52:53], v[50:51]
	v_and_b32_sdwa v52, v49, v90 dst_sel:DWORD dst_unused:UNUSED_PAD src0_sel:WORD_1 src1_sel:DWORD
	v_and_b32_sdwa v53, v48, v90 dst_sel:DWORD dst_unused:UNUSED_PAD src0_sel:WORD_1 src1_sel:DWORD
	v_add3_u32 v48, v48, v53, s3
	v_add3_u32 v49, v49, v52, s3
	v_and_b32_sdwa v52, v51, v90 dst_sel:DWORD dst_unused:UNUSED_PAD src0_sel:WORD_1 src1_sel:DWORD
	v_and_b32_sdwa v53, v50, v90 dst_sel:DWORD dst_unused:UNUSED_PAD src0_sel:WORD_1 src1_sel:DWORD
	v_add3_u32 v51, v51, v52, s3
	v_add3_u32 v50, v50, v53, s3
	v_and_b32_e32 v51, 0xffff0000, v51
	v_and_b32_e32 v50, 0xffff0000, v50
	v_or_b32_sdwa v49, v51, v49 dst_sel:DWORD dst_unused:UNUSED_PAD src0_sel:DWORD src1_sel:WORD_1
	v_or_b32_sdwa v48, v50, v48 dst_sel:DWORD dst_unused:UNUSED_PAD src0_sel:DWORD src1_sel:WORD_1
	global_store_dwordx2 v[54:55], v[48:49], off
; DEV unsigned pack2(float a, float b) { return (unsigned)f2bf(a) | ((unsigned)f2bf(b) << 16); }
; DEV float sigmoidf_(float x) { return 1.f / (1.f + __expf(-x)); }
; DEV void phase_moe1(const Params& p, int l, unsigned char* smem) {
;     ...
;         for (int n = 0; n < 2; ++n) {
;           const int acol = nt * 64 + wc * 32 + n * 16 + fq * 4;
;           const float4 bg4 = *reinterpret_cast<const float4*>(bgu + acol);
;           const float4 bl4 = *reinterpret_cast<const float4*>(bgu + 1024 + acol);
;           const float bgv[4] = {bg4.x, bg4.y, bg4.z, bg4.w}, blv[4] = {bl4.x, bl4.y, bl4.z, bl4.w};
; #pragma unroll
;           for (int m = 0; m < 4; ++m) {
;             const int i = mt * 128 + wr * 64 + m * 16 + fr;
;             if (i < cnt) {
;               float a[4];
; #pragma unroll
;               for (int j = 0; j < 4; ++j) {
;                 float gl = fminf(acc[m][n][j] + bgv[j], 7.f);
;                 float li = fminf(fmaxf(acc[m][n + 2][j] + blv[j], -7.f), 7.f);
;                 a[j] = gl * sigmoidf_(1.702f * gl) * (li + 1.f);
;               }
;               *reinterpret_cast<uint2*>(p.act + (size_t)(rowoff + i) * 1024 + acol) = make_uint2(pack2(a[0], a[1]), pack2(a[2], a[3]));
;             }
;           }
.LBB0_2349:
	s_or_b64 exec, exec, s[4:5]
	v_or_b32_e32 v48, 48, v72
	v_cmp_lt_i32_e64 s[12:13], v48, v74
	v_add_u32_e32 v48, v48, v75
	v_ashrrev_i32_e32 v49, 31, v48
	s_and_saveexec_b64 s[4:5], s[12:13]
	s_cbranch_execz .LBB0_2351
	v_add_f32_e32 v33, v33, v37
	v_add_f32_e32 v32, v32, v36
	v_add_f32_e32 v36, v40, v44
	v_min_f32_e32 v44, 0x40e00000, v33
	v_add_f32_e32 v33, v41, v45
	v_med3_f32 v50, v33, s2, v89
	v_mul_f32_e32 v33, 0x3fd9db23, v44
	v_mul_f32_e32 v33, 0xbfb8aa3b, v33
	v_exp_f32_e32 v52, v33
	v_add_f32_e32 v33, v34, v38
	v_min_f32_e32 v32, 0x40e00000, v32
	v_min_f32_e32 v33, 0x40e00000, v33
	v_add_f32_e32 v34, v42, v46
	v_mul_f32_e32 v40, 0x3fd9db23, v32
	v_med3_f32 v37, v34, s2, v89
	v_mul_f32_e32 v34, 0x3fd9db23, v33
	v_mul_f32_e32 v40, 0xbfb8aa3b, v40
	v_mul_f32_e32 v34, 0xbfb8aa3b, v34
	v_exp_f32_e32 v40, v40
	v_exp_f32_e32 v41, v34
	v_add_f32_e32 v34, v35, v39
	v_min_f32_e32 v45, 0x40e00000, v34
	v_add_f32_e32 v34, v43, v47
	v_med3_f32 v51, v34, s2, v89
	v_mul_f32_e32 v34, 0x3fd9db23, v45
	v_mul_f32_e32 v34, 0xbfb8aa3b, v34
	v_exp_f32_e32 v53, v34
	v_pk_add_f32 v[34:35], v[40:41], 1.0 op_sel_hi:[1,0]
	v_med3_f32 v36, v36, s2, v89
	v_div_scale_f32 v40, s[24:25], v35, v35, 1.0
	v_rcp_f32_e32 v41, v40
	v_lshlrev_b64 v[38:39], 11, v[48:49]
	v_lshl_add_u64 v[38:39], s[80:81], 0, v[38:39]
	v_lshl_add_u64 v[38:39], v[76:77], 1, v[38:39]
	v_fma_f32 v42, -v40, v41, 1.0
	v_fmac_f32_e32 v41, v42, v41
	v_div_scale_f32 v42, vcc, 1.0, v35, 1.0
	v_mul_f32_e32 v43, v42, v41
	v_fma_f32 v46, -v40, v43, v42
	v_fmac_f32_e32 v43, v46, v41
	v_fma_f32 v40, -v40, v43, v42
	v_div_scale_f32 v42, s[24:25], v34, v34, 1.0
	v_rcp_f32_e32 v46, v42
	v_div_fmas_f32 v40, v40, v41, v43
	v_div_fixup_f32 v35, v40, v35, 1.0
	v_fma_f32 v40, -v42, v46, 1.0
	v_fmac_f32_e32 v46, v40, v46
	v_div_scale_f32 v40, vcc, 1.0, v34, 1.0
	v_mul_f32_e32 v41, v40, v46
	v_fma_f32 v43, -v42, v41, v40
	v_fmac_f32_e32 v41, v43, v46
	v_fma_f32 v40, -v42, v41, v40
	v_div_fmas_f32 v40, v40, v46, v41
	v_div_fixup_f32 v34, v40, v34, 1.0
	v_pk_add_f32 v[40:41], v[52:53], 1.0 op_sel_hi:[1,0]
	v_pk_mul_f32 v[32:33], v[32:33], v[34:35]
	v_div_scale_f32 v42, s[24:25], v41, v41, 1.0
	v_rcp_f32_e32 v43, v42
	v_pk_add_f32 v[34:35], v[36:37], 1.0 op_sel_hi:[1,0]
	s_nop 0
	v_pk_mul_f32 v[32:33], v[34:35], v[32:33]
	v_fma_f32 v34, -v42, v43, 1.0
	v_fmac_f32_e32 v43, v34, v43
	v_div_scale_f32 v34, vcc, 1.0, v41, 1.0
	v_mul_f32_e32 v35, v34, v43
	v_fma_f32 v36, -v42, v35, v34
	v_fmac_f32_e32 v35, v36, v43
	v_div_scale_f32 v36, s[24:25], v40, v40, 1.0
	v_rcp_f32_e32 v37, v36
	v_fma_f32 v34, -v42, v35, v34
	v_div_fmas_f32 v34, v34, v43, v35
	v_div_fixup_f32 v35, v34, v41, 1.0
	v_fma_f32 v34, -v36, v37, 1.0
	v_fmac_f32_e32 v37, v34, v37
	v_div_scale_f32 v34, vcc, 1.0, v40, 1.0
	v_mul_f32_e32 v41, v34, v37
	v_fma_f32 v42, -v36, v41, v34
	v_fmac_f32_e32 v41, v42, v37
	v_fma_f32 v34, -v36, v41, v34
	v_div_fmas_f32 v34, v34, v37, v41
	v_div_fixup_f32 v34, v34, v40, 1.0
	v_pk_mul_f32 v[34:35], v[44:45], v[34:35]
	v_pk_add_f32 v[36:37], v[50:51], 1.0 op_sel_hi:[1,0]
	s_nop 0
	v_pk_mul_f32 v[34:35], v[36:37], v[34:35]
	v_and_b32_sdwa v36, v33, v90 dst_sel:DWORD dst_unused:UNUSED_PAD src0_sel:WORD_1 src1_sel:DWORD
	v_and_b32_sdwa v37, v32, v90 dst_sel:DWORD dst_unused:UNUSED_PAD src0_sel:WORD_1 src1_sel:DWORD
	v_add3_u32 v32, v32, v37, s3
	v_add3_u32 v33, v33, v36, s3
	v_and_b32_sdwa v36, v35, v90 dst_sel:DWORD dst_unused:UNUSED_PAD src0_sel:WORD_1 src1_sel:DWORD
	v_and_b32_sdwa v37, v34, v90 dst_sel:DWORD dst_unused:UNUSED_PAD src0_sel:WORD_1 src1_sel:DWORD
	v_add3_u32 v35, v35, v36, s3
	v_add3_u32 v34, v34, v37, s3
	v_and_b32_e32 v35, 0xffff0000, v35
	v_and_b32_e32 v34, 0xffff0000, v34
	v_or_b32_sdwa v33, v35, v33 dst_sel:DWORD dst_unused:UNUSED_PAD src0_sel:DWORD src1_sel:WORD_1
	v_or_b32_sdwa v32, v34, v32 dst_sel:DWORD dst_unused:UNUSED_PAD src0_sel:DWORD src1_sel:WORD_1
	global_store_dwordx2 v[38:39], v[32:33], off
.LBB0_2351:
	s_or_b64 exec, exec, s[4:5]
	v_or_b32_e32 v32, 16, v76
	v_ashrrev_i32_e32 v33, 31, v32
	v_lshl_add_u64 v[32:33], v[32:33], 2, s[0:1]
	global_load_dwordx4 v[36:39], v[80:81], off offset:64
	s_nop 0
	global_load_dwordx4 v[32:35], v[32:33], off
	s_waitcnt vmcnt(0)
	s_and_saveexec_b64 s[0:1], s[6:7]
	s_cbranch_execnz .LBB0_2355
	s_or_b64 exec, exec, s[0:1]
	s_and_saveexec_b64 s[0:1], s[8:9]
	s_cbranch_execnz .LBB0_2356

; DEV unsigned pack2(float a, float b) { return (unsigned)f2bf(a) | ((unsigned)f2bf(b) << 16); }
; DEV float sigmoidf_(float x) { return 1.f / (1.f + __expf(-x)); }
; DEV void phase_moe1(const Params& p, int l, unsigned char* smem) {
;     ...
;         for (int n = 0; n < 2; ++n) {
;           const int acol = nt * 64 + wc * 32 + n * 16 + fq * 4;
;           const float4 bg4 = *reinterpret_cast<const float4*>(bgu + acol);
;           const float4 bl4 = *reinterpret_cast<const float4*>(bgu + 1024 + acol);
;           const float bgv[4] = {bg4.x, bg4.y, bg4.z, bg4.w}, blv[4] = {bl4.x, bl4.y, bl4.z, bl4.w};
; #pragma unroll
;           for (int m = 0; m < 4; ++m) {
;             const int i = mt * 128 + wr * 64 + m * 16 + fr;
;             if (i < cnt) {
;               float a[4];
; #pragma unroll
;               for (int j = 0; j < 4; ++j) {
;                 float gl = fminf(acc[m][n][j] + bgv[j], 7.f);
;                 float li = fminf(fmaxf(acc[m][n + 2][j] + blv[j], -7.f), 7.f);
;                 a[j] = gl * sigmoidf_(1.702f * gl) * (li + 1.f);
;               }
;               *reinterpret_cast<uint2*>(p.act + (size_t)(rowoff + i) * 1024 + acol) = make_uint2(pack2(a[0], a[1]), pack2(a[2], a[3]));
;             }
;           }
.LBB0_2355:
	v_add_f32_e32 v25, v25, v37
	v_min_f32_e32 v42, 0x40e00000, v25
	v_add_f32_e32 v25, v29, v33
	v_med3_f32 v44, v25, s2, v89
	v_mul_f32_e32 v25, 0x3fd9db23, v42
	v_mul_f32_e32 v25, 0xbfb8aa3b, v25
	v_add_f32_e32 v24, v24, v36
	v_exp_f32_e32 v46, v25
	v_add_f32_e32 v25, v26, v38
	v_min_f32_e32 v24, 0x40e00000, v24
	v_min_f32_e32 v25, 0x40e00000, v25
	v_add_f32_e32 v26, v30, v34
	v_mul_f32_e32 v40, 0x3fd9db23, v24
	v_med3_f32 v29, v26, s2, v89
	v_mul_f32_e32 v26, 0x3fd9db23, v25
	v_mul_f32_e32 v40, 0xbfb8aa3b, v40
	v_mul_f32_e32 v26, 0xbfb8aa3b, v26
	v_exp_f32_e32 v40, v40
	v_exp_f32_e32 v41, v26
	v_add_f32_e32 v26, v27, v39
	v_min_f32_e32 v43, 0x40e00000, v26
	v_add_f32_e32 v26, v31, v35
	v_med3_f32 v45, v26, s2, v89
	v_mul_f32_e32 v26, 0x3fd9db23, v43
	v_mul_f32_e32 v26, 0xbfb8aa3b, v26
	v_exp_f32_e32 v47, v26
	v_pk_add_f32 v[26:27], v[40:41], 1.0 op_sel_hi:[1,0]
	v_add_f32_e32 v28, v28, v32
	v_div_scale_f32 v40, s[4:5], v27, v27, 1.0
	v_rcp_f32_e32 v41, v40
	v_med3_f32 v28, v28, s2, v89
	v_lshlrev_b64 v[30:31], 11, v[78:79]
	v_lshl_add_u64 v[30:31], s[80:81], 0, v[30:31]
	v_fma_f32 v50, -v40, v41, 1.0
	v_fmac_f32_e32 v41, v50, v41
	v_div_scale_f32 v50, vcc, 1.0, v27, 1.0
	v_mul_f32_e32 v51, v50, v41
	v_fma_f32 v52, -v40, v51, v50
	v_fmac_f32_e32 v51, v52, v41
	v_fma_f32 v40, -v40, v51, v50
	v_div_scale_f32 v50, s[4:5], v26, v26, 1.0
	v_rcp_f32_e32 v52, v50
	v_div_fmas_f32 v40, v40, v41, v51
	v_div_fixup_f32 v27, v40, v27, 1.0
	v_lshl_add_u64 v[30:31], v[76:77], 1, v[30:31]
	v_fma_f32 v40, -v50, v52, 1.0
	v_fmac_f32_e32 v52, v40, v52
	v_div_scale_f32 v40, vcc, 1.0, v26, 1.0
	v_mul_f32_e32 v41, v40, v52
	v_fma_f32 v51, -v50, v41, v40
	v_fmac_f32_e32 v41, v51, v52
	v_fma_f32 v40, -v50, v41, v40
	v_div_fmas_f32 v40, v40, v52, v41
	v_div_fixup_f32 v26, v40, v26, 1.0
	v_pk_add_f32 v[40:41], v[46:47], 1.0 op_sel_hi:[1,0]
	v_pk_mul_f32 v[24:25], v[24:25], v[26:27]
	v_div_scale_f32 v46, s[4:5], v41, v41, 1.0
	v_rcp_f32_e32 v47, v46
	v_pk_add_f32 v[26:27], v[28:29], 1.0 op_sel_hi:[1,0]
	s_nop 0
	v_pk_mul_f32 v[24:25], v[26:27], v[24:25]
	v_fma_f32 v26, -v46, v47, 1.0
	v_fmac_f32_e32 v47, v26, v47
	v_div_scale_f32 v26, vcc, 1.0, v41, 1.0
	v_mul_f32_e32 v27, v26, v47
	v_fma_f32 v28, -v46, v27, v26
	v_fmac_f32_e32 v27, v28, v47
	v_div_scale_f32 v28, s[4:5], v40, v40, 1.0
	v_rcp_f32_e32 v29, v28
	v_fma_f32 v26, -v46, v27, v26
	v_div_fmas_f32 v26, v26, v47, v27
	v_div_fixup_f32 v27, v26, v41, 1.0
	v_fma_f32 v26, -v28, v29, 1.0
	v_fmac_f32_e32 v29, v26, v29
	v_div_scale_f32 v26, vcc, 1.0, v40, 1.0
	v_mul_f32_e32 v41, v26, v29
	v_fma_f32 v46, -v28, v41, v26
	v_fmac_f32_e32 v41, v46, v29
	v_fma_f32 v26, -v28, v41, v26
	v_div_fmas_f32 v26, v26, v29, v41
	v_div_fixup_f32 v26, v26, v40, 1.0
	v_pk_mul_f32 v[26:27], v[42:43], v[26:27]
	v_pk_add_f32 v[28:29], v[44:45], 1.0 op_sel_hi:[1,0]
	s_nop 0
	v_pk_mul_f32 v[26:27], v[28:29], v[26:27]
	v_and_b32_sdwa v28, v25, v90 dst_sel:DWORD dst_unused:UNUSED_PAD src0_sel:WORD_1 src1_sel:DWORD
	v_and_b32_sdwa v29, v24, v90 dst_sel:DWORD dst_unused:UNUSED_PAD src0_sel:WORD_1 src1_sel:DWORD
	v_add3_u32 v24, v24, v29, s3
	v_add3_u32 v25, v25, v28, s3
	v_and_b32_sdwa v28, v27, v90 dst_sel:DWORD dst_unused:UNUSED_PAD src0_sel:WORD_1 src1_sel:DWORD
	v_and_b32_sdwa v29, v26, v90 dst_sel:DWORD dst_unused:UNUSED_PAD src0_sel:WORD_1 src1_sel:DWORD
	v_add3_u32 v27, v27, v28, s3
	v_add3_u32 v26, v26, v29, s3
	v_and_b32_e32 v27, 0xffff0000, v27
	v_and_b32_e32 v26, 0xffff0000, v26
	v_or_b32_sdwa v25, v27, v25 dst_sel:DWORD dst_unused:UNUSED_PAD src0_sel:DWORD src1_sel:WORD_1
	v_or_b32_sdwa v24, v26, v24 dst_sel:DWORD dst_unused:UNUSED_PAD src0_sel:DWORD src1_sel:WORD_1
	global_store_dwordx2 v[30:31], v[24:25], off offset:32
	s_or_b64 exec, exec, s[0:1]
	s_and_saveexec_b64 s[0:1], s[8:9]
	s_cbranch_execz .LBB0_2353
.LBB0_2356:
	v_add_f32_e32 v17, v17, v37
	v_min_f32_e32 v26, 0x40e00000, v17
	v_add_f32_e32 v17, v21, v33
	v_med3_f32 v28, v17, s2, v89
	v_mul_f32_e32 v17, 0x3fd9db23, v26
	v_mul_f32_e32 v17, 0xbfb8aa3b, v17
	v_add_f32_e32 v16, v16, v36
	v_exp_f32_e32 v30, v17
	v_add_f32_e32 v17, v18, v38
	v_min_f32_e32 v16, 0x40e00000, v16
	v_min_f32_e32 v17, 0x40e00000, v17
	v_add_f32_e32 v18, v22, v34
	v_mul_f32_e32 v24, 0x3fd9db23, v16
	v_med3_f32 v21, v18, s2, v89
	v_mul_f32_e32 v18, 0x3fd9db23, v17
	v_mul_f32_e32 v24, 0xbfb8aa3b, v24
	v_mul_f32_e32 v18, 0xbfb8aa3b, v18
	v_exp_f32_e32 v24, v24
	v_exp_f32_e32 v25, v18
	v_add_f32_e32 v18, v19, v39
	v_min_f32_e32 v27, 0x40e00000, v18
	v_add_f32_e32 v18, v23, v35
	v_med3_f32 v29, v18, s2, v89
	v_mul_f32_e32 v18, 0x3fd9db23, v27
	v_mul_f32_e32 v18, 0xbfb8aa3b, v18
	v_exp_f32_e32 v31, v18
	v_pk_add_f32 v[18:19], v[24:25], 1.0 op_sel_hi:[1,0]
	v_add_f32_e32 v20, v20, v32
	v_div_scale_f32 v24, s[4:5], v19, v19, 1.0
	v_rcp_f32_e32 v25, v24
	v_med3_f32 v20, v20, s2, v89
	v_lshlrev_b64 v[22:23], 11, v[64:65]
	v_lshl_add_u64 v[22:23], s[80:81], 0, v[22:23]
	v_fma_f32 v40, -v24, v25, 1.0
	v_fmac_f32_e32 v25, v40, v25
	v_div_scale_f32 v40, vcc, 1.0, v19, 1.0
	v_mul_f32_e32 v41, v40, v25
	v_fma_f32 v42, -v24, v41, v40
	v_fmac_f32_e32 v41, v42, v25
	v_fma_f32 v24, -v24, v41, v40
	v_div_scale_f32 v40, s[4:5], v18, v18, 1.0
	v_rcp_f32_e32 v42, v40
	v_div_fmas_f32 v24, v24, v25, v41
	v_div_fixup_f32 v19, v24, v19, 1.0
	v_lshl_add_u64 v[22:23], v[76:77], 1, v[22:23]
	v_fma_f32 v24, -v40, v42, 1.0
	v_fmac_f32_e32 v42, v24, v42
	v_div_scale_f32 v24, vcc, 1.0, v18, 1.0
	v_mul_f32_e32 v25, v24, v42
	v_fma_f32 v41, -v40, v25, v24
	v_fmac_f32_e32 v25, v41, v42
	v_fma_f32 v24, -v40, v25, v24
	v_div_fmas_f32 v24, v24, v42, v25
	v_div_fixup_f32 v18, v24, v18, 1.0
	v_pk_add_f32 v[24:25], v[30:31], 1.0 op_sel_hi:[1,0]
; DEV unsigned pack2(float a, float b) { return (unsigned)f2bf(a) | ((unsigned)f2bf(b) << 16); }
; DEV float sigmoidf_(float x) { return 1.f / (1.f + __expf(-x)); }
; DEV void phase_moe1(const Params& p, int l, unsigned char* smem) {
;     ...
;         for (int n = 0; n < 2; ++n) {
;           const int acol = nt * 64 + wc * 32 + n * 16 + fq * 4;
;           const float4 bg4 = *reinterpret_cast<const float4*>(bgu + acol);
;           const float4 bl4 = *reinterpret_cast<const float4*>(bgu + 1024 + acol);
;           const float bgv[4] = {bg4.x, bg4.y, bg4.z, bg4.w}, blv[4] = {bl4.x, bl4.y, bl4.z, bl4.w};
; #pragma unroll
;           for (int m = 0; m < 4; ++m) {
;             const int i = mt * 128 + wr * 64 + m * 16 + fr;
;             if (i < cnt) {
;               float a[4];
; #pragma unroll
;               for (int j = 0; j < 4; ++j) {
;                 float gl = fminf(acc[m][n][j] + bgv[j], 7.f);
;                 float li = fminf(fmaxf(acc[m][n + 2][j] + blv[j], -7.f), 7.f);
;                 a[j] = gl * sigmoidf_(1.702f * gl) * (li + 1.f);
;               }
;               *reinterpret_cast<uint2*>(p.act + (size_t)(rowoff + i) * 1024 + acol) = make_uint2(pack2(a[0], a[1]), pack2(a[2], a[3]));
;             }
;           }
	v_pk_mul_f32 v[16:17], v[16:17], v[18:19]
	v_div_scale_f32 v30, s[4:5], v25, v25, 1.0
	v_rcp_f32_e32 v31, v30
	v_pk_add_f32 v[18:19], v[20:21], 1.0 op_sel_hi:[1,0]
	s_nop 0
	v_pk_mul_f32 v[16:17], v[18:19], v[16:17]
	v_fma_f32 v18, -v30, v31, 1.0
	v_fmac_f32_e32 v31, v18, v31
	v_div_scale_f32 v18, vcc, 1.0, v25, 1.0
	v_mul_f32_e32 v19, v18, v31
	v_fma_f32 v20, -v30, v19, v18
	v_fmac_f32_e32 v19, v20, v31
	v_div_scale_f32 v20, s[4:5], v24, v24, 1.0
	v_rcp_f32_e32 v21, v20
	v_fma_f32 v18, -v30, v19, v18
	v_div_fmas_f32 v18, v18, v31, v19
	v_div_fixup_f32 v19, v18, v25, 1.0
	v_fma_f32 v18, -v20, v21, 1.0
	v_fmac_f32_e32 v21, v18, v21
	v_div_scale_f32 v18, vcc, 1.0, v24, 1.0
	v_mul_f32_e32 v25, v18, v21
	v_fma_f32 v30, -v20, v25, v18
	v_fmac_f32_e32 v25, v30, v21
	v_fma_f32 v18, -v20, v25, v18
	v_div_fmas_f32 v18, v18, v21, v25
	v_div_fixup_f32 v18, v18, v24, 1.0
	v_pk_mul_f32 v[18:19], v[26:27], v[18:19]
	v_pk_add_f32 v[20:21], v[28:29], 1.0 op_sel_hi:[1,0]
	s_nop 0
	v_pk_mul_f32 v[18:19], v[20:21], v[18:19]
	v_and_b32_sdwa v20, v17, v90 dst_sel:DWORD dst_unused:UNUSED_PAD src0_sel:WORD_1 src1_sel:DWORD
	v_and_b32_sdwa v21, v16, v90 dst_sel:DWORD dst_unused:UNUSED_PAD src0_sel:WORD_1 src1_sel:DWORD
	v_add3_u32 v16, v16, v21, s3
	v_add3_u32 v17, v17, v20, s3
	v_and_b32_sdwa v20, v19, v90 dst_sel:DWORD dst_unused:UNUSED_PAD src0_sel:WORD_1 src1_sel:DWORD
	v_and_b32_sdwa v21, v18, v90 dst_sel:DWORD dst_unused:UNUSED_PAD src0_sel:WORD_1 src1_sel:DWORD
	v_add3_u32 v19, v19, v20, s3
	v_add3_u32 v18, v18, v21, s3
	v_and_b32_e32 v19, 0xffff0000, v19
	v_and_b32_e32 v18, 0xffff0000, v18
	v_or_b32_sdwa v17, v19, v17 dst_sel:DWORD dst_unused:UNUSED_PAD src0_sel:DWORD src1_sel:WORD_1
	v_or_b32_sdwa v16, v18, v16 dst_sel:DWORD dst_unused:UNUSED_PAD src0_sel:DWORD src1_sel:WORD_1
	global_store_dwordx2 v[22:23], v[16:17], off offset:32
	s_or_b64 exec, exec, s[0:1]
	s_and_saveexec_b64 s[0:1], s[10:11]
	s_cbranch_execz .LBB0_2354
.LBB0_2357:
	v_add_f32_e32 v9, v9, v37
	v_min_f32_e32 v18, 0x40e00000, v9
	v_add_f32_e32 v9, v13, v33
	v_med3_f32 v20, v9, s2, v89
	v_mul_f32_e32 v9, 0x3fd9db23, v18
	v_mul_f32_e32 v9, 0xbfb8aa3b, v9
	v_add_f32_e32 v8, v8, v36
	v_exp_f32_e32 v22, v9
	v_add_f32_e32 v9, v10, v38
	v_min_f32_e32 v8, 0x40e00000, v8
	v_min_f32_e32 v9, 0x40e00000, v9
	v_add_f32_e32 v10, v14, v34
	v_mul_f32_e32 v16, 0x3fd9db23, v8
	v_med3_f32 v13, v10, s2, v89
	v_mul_f32_e32 v10, 0x3fd9db23, v9
	v_mul_f32_e32 v16, 0xbfb8aa3b, v16
	v_mul_f32_e32 v10, 0xbfb8aa3b, v10
	v_exp_f32_e32 v16, v16
	v_exp_f32_e32 v17, v10
	v_add_f32_e32 v10, v11, v39
	v_min_f32_e32 v19, 0x40e00000, v10
	v_add_f32_e32 v10, v15, v35
	v_med3_f32 v21, v10, s2, v89
	v_mul_f32_e32 v10, 0x3fd9db23, v19
	v_mul_f32_e32 v10, 0xbfb8aa3b, v10
	v_exp_f32_e32 v23, v10
	v_pk_add_f32 v[10:11], v[16:17], 1.0 op_sel_hi:[1,0]
	v_add_f32_e32 v12, v12, v32
	v_div_scale_f32 v16, s[4:5], v11, v11, 1.0
	v_rcp_f32_e32 v17, v16
	v_med3_f32 v12, v12, s2, v89
	v_lshlrev_b64 v[14:15], 11, v[56:57]
	v_lshl_add_u64 v[14:15], s[80:81], 0, v[14:15]
	v_fma_f32 v24, -v16, v17, 1.0
	v_fmac_f32_e32 v17, v24, v17
	v_div_scale_f32 v24, vcc, 1.0, v11, 1.0
	v_mul_f32_e32 v25, v24, v17
	v_fma_f32 v26, -v16, v25, v24
	v_fmac_f32_e32 v25, v26, v17
	v_fma_f32 v16, -v16, v25, v24
	v_div_scale_f32 v24, s[4:5], v10, v10, 1.0
	v_rcp_f32_e32 v26, v24
	v_div_fmas_f32 v16, v16, v17, v25
	v_div_fixup_f32 v11, v16, v11, 1.0
	v_lshl_add_u64 v[14:15], v[76:77], 1, v[14:15]
	v_fma_f32 v16, -v24, v26, 1.0
	v_fmac_f32_e32 v26, v16, v26
	v_div_scale_f32 v16, vcc, 1.0, v10, 1.0
	v_mul_f32_e32 v17, v16, v26
	v_fma_f32 v25, -v24, v17, v16
	v_fmac_f32_e32 v17, v25, v26
	v_fma_f32 v16, -v24, v17, v16
	v_div_fmas_f32 v16, v16, v26, v17
	v_div_fixup_f32 v10, v16, v10, 1.0
	v_pk_add_f32 v[16:17], v[22:23], 1.0 op_sel_hi:[1,0]
	v_pk_mul_f32 v[8:9], v[8:9], v[10:11]
	v_div_scale_f32 v22, s[4:5], v17, v17, 1.0
	v_rcp_f32_e32 v23, v22
	v_pk_add_f32 v[10:11], v[12:13], 1.0 op_sel_hi:[1,0]
	s_nop 0
	v_pk_mul_f32 v[8:9], v[10:11], v[8:9]
	v_fma_f32 v10, -v22, v23, 1.0
	v_fmac_f32_e32 v23, v10, v23
	v_div_scale_f32 v10, vcc, 1.0, v17, 1.0
	v_mul_f32_e32 v11, v10, v23
	v_fma_f32 v12, -v22, v11, v10
	v_fmac_f32_e32 v11, v12, v23
	v_div_scale_f32 v12, s[4:5], v16, v16, 1.0
	v_rcp_f32_e32 v13, v12
	v_fma_f32 v10, -v22, v11, v10
	v_div_fmas_f32 v10, v10, v23, v11
	v_div_fixup_f32 v11, v10, v17, 1.0
	v_fma_f32 v10, -v12, v13, 1.0
	v_fmac_f32_e32 v13, v10, v13
	v_div_scale_f32 v10, vcc, 1.0, v16, 1.0
	v_mul_f32_e32 v17, v10, v13
	v_fma_f32 v22, -v12, v17, v10
	v_fmac_f32_e32 v17, v22, v13
	v_fma_f32 v10, -v12, v17, v10
	v_div_fmas_f32 v10, v10, v13, v17
	v_div_fixup_f32 v10, v10, v16, 1.0
	v_pk_mul_f32 v[10:11], v[18:19], v[10:11]
	v_pk_add_f32 v[12:13], v[20:21], 1.0 op_sel_hi:[1,0]
	s_nop 0
	v_pk_mul_f32 v[10:11], v[12:13], v[10:11]
	v_and_b32_sdwa v12, v9, v90 dst_sel:DWORD dst_unused:UNUSED_PAD src0_sel:WORD_1 src1_sel:DWORD
	v_and_b32_sdwa v13, v8, v90 dst_sel:DWORD dst_unused:UNUSED_PAD src0_sel:WORD_1 src1_sel:DWORD
	v_add3_u32 v8, v8, v13, s3
	v_add3_u32 v9, v9, v12, s3
	v_and_b32_sdwa v12, v11, v90 dst_sel:DWORD dst_unused:UNUSED_PAD src0_sel:WORD_1 src1_sel:DWORD
	v_and_b32_sdwa v13, v10, v90 dst_sel:DWORD dst_unused:UNUSED_PAD src0_sel:WORD_1 src1_sel:DWORD
	v_add3_u32 v11, v11, v12, s3
	v_add3_u32 v10, v10, v13, s3
	v_and_b32_e32 v11, 0xffff0000, v11
	v_and_b32_e32 v10, 0xffff0000, v10
	v_or_b32_sdwa v9, v11, v9 dst_sel:DWORD dst_unused:UNUSED_PAD src0_sel:DWORD src1_sel:WORD_1
	v_or_b32_sdwa v8, v10, v8 dst_sel:DWORD dst_unused:UNUSED_PAD src0_sel:DWORD src1_sel:WORD_1
	global_store_dwordx2 v[14:15], v[8:9], off offset:32
	s_or_b64 exec, exec, s[0:1]
	s_and_saveexec_b64 s[0:1], s[12:13]
	s_cbranch_execz .LBB0_2338
; DEV unsigned pack2(float a, float b) { return (unsigned)f2bf(a) | ((unsigned)f2bf(b) << 16); }
; DEV float sigmoidf_(float x) { return 1.f / (1.f + __expf(-x)); }
; DEV void phase_moe1(const Params& p, int l, unsigned char* smem) {
;     ...
;         for (int n = 0; n < 2; ++n) {
;           const int acol = nt * 64 + wc * 32 + n * 16 + fq * 4;
;           const float4 bg4 = *reinterpret_cast<const float4*>(bgu + acol);
;           const float4 bl4 = *reinterpret_cast<const float4*>(bgu + 1024 + acol);
;           const float bgv[4] = {bg4.x, bg4.y, bg4.z, bg4.w}, blv[4] = {bl4.x, bl4.y, bl4.z, bl4.w};
; #pragma unroll
;           for (int m = 0; m < 4; ++m) {
;             const int i = mt * 128 + wr * 64 + m * 16 + fr;
;             if (i < cnt) {
;               float a[4];
; #pragma unroll
;               for (int j = 0; j < 4; ++j) {
;                 float gl = fminf(acc[m][n][j] + bgv[j], 7.f);
;                 float li = fminf(fmaxf(acc[m][n + 2][j] + blv[j], -7.f), 7.f);
;                 a[j] = gl * sigmoidf_(1.702f * gl) * (li + 1.f);
;               }
;               *reinterpret_cast<uint2*>(p.act + (size_t)(rowoff + i) * 1024 + acol) = make_uint2(pack2(a[0], a[1]), pack2(a[2], a[3]));
;             }
;           }
.LBB0_2358:
	v_add_f32_e32 v1, v1, v37
	v_min_f32_e32 v10, 0x40e00000, v1
	v_add_f32_e32 v1, v5, v33
	v_med3_f32 v12, v1, s2, v89
	v_mul_f32_e32 v1, 0x3fd9db23, v10
	v_mul_f32_e32 v1, 0xbfb8aa3b, v1
	v_add_f32_e32 v0, v0, v36
	v_exp_f32_e32 v14, v1
	v_add_f32_e32 v1, v2, v38
	v_min_f32_e32 v0, 0x40e00000, v0
	v_min_f32_e32 v1, 0x40e00000, v1
	v_add_f32_e32 v2, v6, v34
	v_mul_f32_e32 v8, 0x3fd9db23, v0
	v_med3_f32 v5, v2, s2, v89
	v_mul_f32_e32 v2, 0x3fd9db23, v1
	v_mul_f32_e32 v8, 0xbfb8aa3b, v8
	v_mul_f32_e32 v2, 0xbfb8aa3b, v2
	v_exp_f32_e32 v8, v8
	v_exp_f32_e32 v9, v2
	v_add_f32_e32 v2, v3, v39
	v_min_f32_e32 v11, 0x40e00000, v2
	v_add_f32_e32 v2, v7, v35
	v_med3_f32 v13, v2, s2, v89
	v_mul_f32_e32 v2, 0x3fd9db23, v11
	v_mul_f32_e32 v2, 0xbfb8aa3b, v2
	v_exp_f32_e32 v15, v2
	v_pk_add_f32 v[2:3], v[8:9], 1.0 op_sel_hi:[1,0]
	v_add_f32_e32 v4, v4, v32
	v_div_scale_f32 v8, s[4:5], v3, v3, 1.0
	v_rcp_f32_e32 v9, v8
	v_med3_f32 v4, v4, s2, v89
	v_lshlrev_b64 v[6:7], 11, v[48:49]
	v_lshl_add_u64 v[6:7], s[80:81], 0, v[6:7]
	v_fma_f32 v16, -v8, v9, 1.0
	v_fmac_f32_e32 v9, v16, v9
	v_div_scale_f32 v16, vcc, 1.0, v3, 1.0
	v_mul_f32_e32 v17, v16, v9
	v_fma_f32 v18, -v8, v17, v16
	v_fmac_f32_e32 v17, v18, v9
	v_fma_f32 v8, -v8, v17, v16
	v_div_scale_f32 v16, s[4:5], v2, v2, 1.0
	v_rcp_f32_e32 v18, v16
	v_div_fmas_f32 v8, v8, v9, v17
	v_div_fixup_f32 v3, v8, v3, 1.0
	v_lshl_add_u64 v[6:7], v[76:77], 1, v[6:7]
	v_fma_f32 v8, -v16, v18, 1.0
	v_fmac_f32_e32 v18, v8, v18
	v_div_scale_f32 v8, vcc, 1.0, v2, 1.0
	v_mul_f32_e32 v9, v8, v18
	v_fma_f32 v17, -v16, v9, v8
	v_fmac_f32_e32 v9, v17, v18
	v_fma_f32 v8, -v16, v9, v8
	v_div_fmas_f32 v8, v8, v18, v9
	v_div_fixup_f32 v2, v8, v2, 1.0
	v_pk_add_f32 v[8:9], v[14:15], 1.0 op_sel_hi:[1,0]
	v_pk_mul_f32 v[0:1], v[0:1], v[2:3]
	v_div_scale_f32 v14, s[4:5], v9, v9, 1.0
	v_rcp_f32_e32 v15, v14
	v_pk_add_f32 v[2:3], v[4:5], 1.0 op_sel_hi:[1,0]
	s_nop 0
	v_pk_mul_f32 v[0:1], v[2:3], v[0:1]
	v_fma_f32 v2, -v14, v15, 1.0
	v_fmac_f32_e32 v15, v2, v15
	v_div_scale_f32 v2, vcc, 1.0, v9, 1.0
	v_mul_f32_e32 v3, v2, v15
	v_fma_f32 v4, -v14, v3, v2
	v_fmac_f32_e32 v3, v4, v15
	v_div_scale_f32 v4, s[4:5], v8, v8, 1.0
	v_rcp_f32_e32 v5, v4
	v_fma_f32 v2, -v14, v3, v2
	v_div_fmas_f32 v2, v2, v15, v3
	v_div_fixup_f32 v3, v2, v9, 1.0
	v_fma_f32 v2, -v4, v5, 1.0
	v_fmac_f32_e32 v5, v2, v5
	v_div_scale_f32 v2, vcc, 1.0, v8, 1.0
	v_mul_f32_e32 v9, v2, v5
	v_fma_f32 v14, -v4, v9, v2
	v_fmac_f32_e32 v9, v14, v5
	v_fma_f32 v2, -v4, v9, v2
	v_div_fmas_f32 v2, v2, v5, v9
	v_div_fixup_f32 v2, v2, v8, 1.0
	v_pk_mul_f32 v[2:3], v[10:11], v[2:3]
	v_pk_add_f32 v[4:5], v[12:13], 1.0 op_sel_hi:[1,0]
	s_nop 0
	v_pk_mul_f32 v[2:3], v[4:5], v[2:3]
	v_and_b32_sdwa v4, v1, v90 dst_sel:DWORD dst_unused:UNUSED_PAD src0_sel:WORD_1 src1_sel:DWORD
	v_and_b32_sdwa v5, v0, v90 dst_sel:DWORD dst_unused:UNUSED_PAD src0_sel:WORD_1 src1_sel:DWORD
	v_add3_u32 v0, v0, v5, s3
	v_add3_u32 v1, v1, v4, s3
	v_and_b32_sdwa v4, v3, v90 dst_sel:DWORD dst_unused:UNUSED_PAD src0_sel:WORD_1 src1_sel:DWORD
	v_and_b32_sdwa v5, v2, v90 dst_sel:DWORD dst_unused:UNUSED_PAD src0_sel:WORD_1 src1_sel:DWORD
	v_add3_u32 v3, v3, v4, s3
	v_add3_u32 v2, v2, v5, s3
	v_and_b32_e32 v3, 0xffff0000, v3
	v_and_b32_e32 v2, 0xffff0000, v2
	v_or_b32_sdwa v1, v3, v1 dst_sel:DWORD dst_unused:UNUSED_PAD src0_sel:DWORD src1_sel:WORD_1
	v_or_b32_sdwa v0, v2, v0 dst_sel:DWORD dst_unused:UNUSED_PAD src0_sel:DWORD src1_sel:WORD_1
	global_store_dwordx2 v[6:7], v[0:1], off offset:32
	s_branch .LBB0_2338

; DEV unsigned pack2(float a, float b) { return (unsigned)f2bf(a) | ((unsigned)f2bf(b) << 16); }
; template <bool SWAP, class RowA, class Epi>
; DEV void gemm_tile(unsigned char* smem, RowA rowA, const bf16_t* Bt, int K, Epi epi) {
;     ...
;   for (int t = 0; t < nk; ++t) {
;     asm volatile("s_waitcnt vmcnt(0)" ::: "memory");
;     __syncthreads();
;     if (t + 1 < nk) stage(t + 1, (t + 1) & 1);
;     const unsigned char* SA = smem + (t & 1) * 16384;
;     const unsigned char* SB = SA + 8192;
;     bf16x8 At[4], Bl[4];
; #pragma unroll
;     for (int m = 0; m < 4; ++m) At[m] = *reinterpret_cast<const bf16x8*>(SA + (wr * 64 + m * 16) * 64 + rdoff);
; #pragma unroll
;     for (int n = 0; n < 4; ++n) Bl[n] = *reinterpret_cast<const bf16x8*>(SB + (wc * 64 + n * 16) * 64 + rdoff);
; #pragma unroll
;     for (int m = 0; m < 4; ++m)
; #pragma unroll
;       for (int n = 0; n < 4; ++n)
;         acc[m][n] = SWAP ? __builtin_amdgcn_mfma_f32_16x16x32_bf16(Bl[n], At[m], acc[m][n], 0, 0, 0)
;                          : __builtin_amdgcn_mfma_f32_16x16x32_bf16(At[m], Bl[n], acc[m][n], 0, 0, 0);
;   }
; DEV void phase_moe2(const Params& p, int l, unsigned char* smem) {
;     ...
; #pragma unroll
;         for (int n = 0; n < 4; ++n) {
;           const int col = nt * 128 + wc * 64 + n * 16 + fq * 4;
;           const float4 b4 = *reinterpret_cast<const float4*>(bd + col);
; #pragma unroll
;           for (int m = 0; m < 4; ++m) {
;             const int i = mt * 128 + wr * 64 + m * 16 + fr;
;             if (i < cnt) {
;               const float g = gl[i];
;               *reinterpret_cast<uint2*>(p.out2 + (size_t)(rowoff + i) * 1024 + col) =
;                   make_uint2(pack2((acc[m][n][0] + b4.x) * g, (acc[m][n][1] + b4.y) * g), pack2((acc[m][n][2] + b4.z) * g, (acc[m][n][3] + b4.w) * g));
;             }
.LBB0_2411:
	s_add_i32 s10, s5, 0x4000
	s_and_b32 s20, s10, 0x4000
	s_and_b32 s5, s5, 0x4000
	v_add_u32_e32 v89, s20, v78
	v_lshl_add_u64 v[90:91], v[64:65], 0, s[6:7]
	v_or_b32_e32 v68, s5, v76
	v_readfirstlane_b32 s5, v89
	v_add_u32_e32 v99, 0x1000, v89
	v_lshl_add_u64 v[94:95], v[90:91], 0, 64
	v_add_u32_e32 v98, 0x2000, v89
	v_readfirstlane_b32 s20, v99
	s_mov_b32 m0, s5
	s_waitcnt vmcnt(0)
	s_waitcnt lgkmcnt(0)
	s_barrier
	v_lshl_add_u64 v[92:93], v[66:67], 0, s[6:7]
	v_lshl_add_u64 v[90:91], v[90:91], 0, s[14:15]
	v_add_u32_e32 v89, 0x3000, v89
	v_readfirstlane_b32 s21, v98
	global_load_lds_dwordx4 v[94:95], off
	s_mov_b32 m0, s20
	v_lshl_add_u64 v[96:97], v[92:93], 0, s[16:17]
	v_readfirstlane_b32 s23, v89
	global_load_lds_dwordx4 v[90:91], off
	s_mov_b32 m0, s21
	v_lshl_add_u64 v[92:93], v[92:93], 0, s[18:19]
	global_load_lds_dwordx4 v[96:97], off
	s_mov_b32 m0, s23
	v_add_u32_e32 v89, v68, v77
	global_load_lds_dwordx4 v[92:93], off
	v_add_u32_e32 v68, v68, v79
	ds_read_b128 v[90:93], v68 offset:8192
	ds_read_b128 v[94:97], v68 offset:9216
	ds_read_b128 v[98:101], v89
	ds_read_b128 v[102:105], v89 offset:1024
	ds_read_b128 v[106:109], v68 offset:10240
	ds_read_b128 v[110:113], v68 offset:11264
	s_waitcnt lgkmcnt(0)
	v_mfma_f32_16x16x32_bf16 v[60:63], v[90:93], v[98:101], v[60:63]
	s_add_u32 s6, s6, 64
	s_addc_u32 s7, s7, 0
	s_cmpk_eq_i32 s6, 0x7c0
	v_mfma_f32_16x16x32_bf16 v[56:59], v[94:97], v[98:101], v[56:59]
	s_mov_b32 s5, s10
	v_mfma_f32_16x16x32_bf16 v[28:31], v[106:109], v[98:101], v[28:31]
	v_mfma_f32_16x16x32_bf16 v[12:15], v[110:113], v[98:101], v[12:15]
	v_mfma_f32_16x16x32_bf16 v[52:55], v[90:93], v[102:105], v[52:55]
	v_mfma_f32_16x16x32_bf16 v[48:51], v[94:97], v[102:105], v[48:51]
	v_mfma_f32_16x16x32_bf16 v[24:27], v[106:109], v[102:105], v[24:27]
	v_mfma_f32_16x16x32_bf16 v[8:11], v[110:113], v[102:105], v[8:11]
	ds_read_b128 v[98:101], v89 offset:2048
	ds_read_b128 v[102:105], v89 offset:3072
	s_waitcnt lgkmcnt(0)
	v_mfma_f32_16x16x32_bf16 v[44:47], v[90:93], v[98:101], v[44:47]
	v_mfma_f32_16x16x32_bf16 v[40:43], v[94:97], v[98:101], v[40:43]
	v_mfma_f32_16x16x32_bf16 v[20:23], v[106:109], v[98:101], v[20:23]
	v_mfma_f32_16x16x32_bf16 v[4:7], v[110:113], v[98:101], v[4:7]
	v_mfma_f32_16x16x32_bf16 v[36:39], v[90:93], v[102:105], v[36:39]
	v_mfma_f32_16x16x32_bf16 v[32:35], v[94:97], v[102:105], v[32:35]
	v_mfma_f32_16x16x32_bf16 v[16:19], v[106:109], v[102:105], v[16:19]
	v_mfma_f32_16x16x32_bf16 v[0:3], v[110:113], v[102:105], v[0:3]
	s_cbranch_scc0 .LBB0_2411
	v_add_u32_e32 v68, v76, v79
	s_waitcnt vmcnt(0)
	s_waitcnt vmcnt(0)
	s_barrier
	ds_read_b128 v[90:93], v68 offset:24576
	ds_read_b128 v[94:97], v68 offset:25600
	ds_read_b128 v[98:101], v68 offset:26624
	ds_read_b128 v[102:105], v68 offset:27648
	v_add_u32_e32 v89, v76, v77
	ds_read_b128 v[76:79], v89 offset:16384
	ds_read_b128 v[106:109], v89 offset:18432
	s_waitcnt lgkmcnt(1)
	v_mfma_f32_16x16x32_bf16 v[64:67], v[90:93], v[76:79], v[60:63]
	s_lshl_b64 s[0:1], s[0:1], 2
	s_add_u32 s0, s44, s0
	s_addc_u32 s1, s45, s1
	v_mfma_f32_16x16x32_bf16 v[56:59], v[94:97], v[76:79], v[56:59]
	s_mul_i32 s10, s8, 0x4200
	v_lshl_add_u32 v68, v72, 6, s9
	v_or_b32_e32 v72, v68, v73
	v_mfma_f32_16x16x32_bf16 v[28:31], v[98:101], v[76:79], v[28:31]
	v_cmp_lt_i32_e32 vcc, v72, v74
	v_ashrrev_i32_e32 v73, 31, v72
	v_mfma_f32_16x16x32_bf16 v[12:15], v[102:105], v[76:79], v[12:15]
	ds_read_b128 v[76:79], v89 offset:17408
	s_waitcnt lgkmcnt(0)
	v_mfma_f32_16x16x32_bf16 v[60:63], v[90:93], v[76:79], v[52:55]
	v_mfma_f32_16x16x32_bf16 v[52:55], v[90:93], v[106:109], v[44:47]
	s_nop 2
	v_lshlrev_b32_e32 v44, 6, v70
	v_lshlrev_b32_e32 v45, 2, v71
	v_or3_b32 v70, v44, v45, s4
	v_ashrrev_i32_e32 v71, 31, v70
	v_mfma_f32_16x16x32_bf16 v[48:51], v[94:97], v[76:79], v[48:51]
	v_mfma_f32_16x16x32_bf16 v[24:27], v[98:101], v[76:79], v[24:27]
	v_mfma_f32_16x16x32_bf16 v[8:11], v[102:105], v[76:79], v[8:11]
	v_lshl_add_u64 v[76:77], v[70:71], 2, s[0:1]
	global_load_dwordx4 v[44:47], v[76:77], off
	s_lshl_b64 s[0:1], s[10:11], 2
	v_mfma_f32_16x16x32_bf16 v[40:43], v[94:97], v[106:109], v[40:43]
	s_add_u32 s4, s78, s0
	v_add_u32_e32 v78, v72, v75
	s_addc_u32 s5, s79, s1
	v_mfma_f32_16x16x32_bf16 v[20:23], v[98:101], v[106:109], v[20:23]
	v_ashrrev_i32_e32 v79, 31, v78
	v_mfma_f32_16x16x32_bf16 v[4:7], v[102:105], v[106:109], v[4:7]
	ds_read_b128 v[106:109], v89 offset:19456
	s_waitcnt lgkmcnt(0)
	v_mfma_f32_16x16x32_bf16 v[36:39], v[90:93], v[106:109], v[36:39]
	v_mfma_f32_16x16x32_bf16 v[32:35], v[94:97], v[106:109], v[32:35]
	v_mfma_f32_16x16x32_bf16 v[16:19], v[98:101], v[106:109], v[16:19]
	v_mfma_f32_16x16x32_bf16 v[0:3], v[102:105], v[106:109], v[0:3]
	v_lshl_add_u64 v[124:125], v[72:73], 2, s[4:5]
	global_load_dword v126, v[124:125], off
	global_load_dword v127, v[124:125], off offset:64
	global_load_dword v128, v[124:125], off offset:128
	global_load_dword v129, v[124:125], off offset:192
	global_load_dwordx4 v[130:133], v[76:77], off offset:64
	global_load_dwordx4 v[134:137], v[76:77], off offset:128
	global_load_dwordx4 v[138:141], v[76:77], off offset:192
	s_waitcnt vmcnt(0)
	s_and_saveexec_b64 s[0:1], vcc
	s_cbranch_execz .LBB0_2414
	v_lshl_add_u64 v[90:91], v[72:73], 2, s[4:5]
	v_mov_b32_e32 v68, v126
	v_pk_add_f32 v[66:67], v[66:67], v[46:47]
	v_pk_add_f32 v[64:65], v[64:65], v[44:45]
	v_lshlrev_b64 v[90:91], 11, v[78:79]
	v_mov_b32_e32 v93, v66
	v_mov_b32_e32 v66, v65
	v_lshl_add_u64 v[90:91], s[82:83], 0, v[90:91]
	v_mov_b32_e32 v92, v64
	v_lshl_add_u64 v[64:65], v[70:71], 1, v[90:91]
	v_pk_mul_f32 v[66:67], v[66:67], v[68:69] op_sel_hi:[1,0]
	v_pk_mul_f32 v[90:91], v[92:93], v[68:69] op_sel_hi:[1,0]
	v_and_b32_sdwa v92, v67, v87 dst_sel:DWORD dst_unused:UNUSED_PAD src0_sel:WORD_1 src1_sel:DWORD
	v_and_b32_sdwa v93, v66, v87 dst_sel:DWORD dst_unused:UNUSED_PAD src0_sel:WORD_1 src1_sel:DWORD
	v_and_b32_sdwa v68, v91, v87 dst_sel:DWORD dst_unused:UNUSED_PAD src0_sel:WORD_1 src1_sel:DWORD
	v_and_b32_sdwa v89, v90, v87 dst_sel:DWORD dst_unused:UNUSED_PAD src0_sel:WORD_1 src1_sel:DWORD
	v_add3_u32 v67, v67, v92, s2
	v_add3_u32 v66, v66, v93, s2
	v_add3_u32 v89, v90, v89, s2
	v_add3_u32 v68, v91, v68, s2
	v_and_b32_e32 v67, 0xffff0000, v67
	v_and_b32_e32 v66, 0xffff0000, v66
	v_or_b32_sdwa v67, v67, v68 dst_sel:DWORD dst_unused:UNUSED_PAD src0_sel:DWORD src1_sel:WORD_1
	v_or_b32_sdwa v66, v66, v89 dst_sel:DWORD dst_unused:UNUSED_PAD src0_sel:DWORD src1_sel:WORD_1
	global_store_dwordx2 v[64:65], v[66:67], off
; DEV unsigned pack2(float a, float b) { return (unsigned)f2bf(a) | ((unsigned)f2bf(b) << 16); }
; DEV void phase_moe2(const Params& p, int l, unsigned char* smem) {
;     ...
; #pragma unroll
;         for (int n = 0; n < 4; ++n) {
;           const int col = nt * 128 + wc * 64 + n * 16 + fq * 4;
;           const float4 b4 = *reinterpret_cast<const float4*>(bd + col);
; #pragma unroll
;           for (int m = 0; m < 4; ++m) {
;             const int i = mt * 128 + wr * 64 + m * 16 + fr;
;             if (i < cnt) {
;               const float g = gl[i];
;               *reinterpret_cast<uint2*>(p.out2 + (size_t)(rowoff + i) * 1024 + col) =
;                   make_uint2(pack2((acc[m][n][0] + b4.x) * g, (acc[m][n][1] + b4.y) * g), pack2((acc[m][n][2] + b4.z) * g, (acc[m][n][3] + b4.w) * g));
;             }
;           }
;         }
.LBB0_2414:
	s_or_b64 exec, exec, s[0:1]
	v_or_b32_e32 v64, 16, v72
	v_cmp_lt_i32_e64 s[0:1], v64, v74
	v_add_u32_e32 v64, v64, v75
	v_ashrrev_i32_e32 v65, 31, v64
	s_and_saveexec_b64 s[6:7], s[0:1]
	s_cbranch_execz .LBB0_2416
	v_lshl_add_u64 v[66:67], v[72:73], 2, s[4:5]
	v_mov_b32_e32 v66, v127
	v_pk_add_f32 v[62:63], v[62:63], v[46:47]
	v_pk_add_f32 v[60:61], v[60:61], v[44:45]
	v_lshlrev_b64 v[90:91], 11, v[64:65]
	v_mov_b32_e32 v93, v62
	v_mov_b32_e32 v62, v61
	v_lshl_add_u64 v[90:91], s[82:83], 0, v[90:91]
	v_mov_b32_e32 v92, v60
	v_lshl_add_u64 v[60:61], v[70:71], 1, v[90:91]
	v_pk_mul_f32 v[62:63], v[62:63], v[66:67] op_sel_hi:[1,0]
	v_pk_mul_f32 v[90:91], v[92:93], v[66:67] op_sel_hi:[1,0]
	v_and_b32_sdwa v68, v63, v87 dst_sel:DWORD dst_unused:UNUSED_PAD src0_sel:WORD_1 src1_sel:DWORD
	v_and_b32_sdwa v89, v62, v87 dst_sel:DWORD dst_unused:UNUSED_PAD src0_sel:WORD_1 src1_sel:DWORD
	v_and_b32_sdwa v66, v91, v87 dst_sel:DWORD dst_unused:UNUSED_PAD src0_sel:WORD_1 src1_sel:DWORD
	v_and_b32_sdwa v67, v90, v87 dst_sel:DWORD dst_unused:UNUSED_PAD src0_sel:WORD_1 src1_sel:DWORD
	v_add3_u32 v63, v63, v68, s2
	v_add3_u32 v62, v62, v89, s2
	v_add3_u32 v67, v90, v67, s2
	v_add3_u32 v66, v91, v66, s2
	v_and_b32_e32 v63, 0xffff0000, v63
	v_and_b32_e32 v62, 0xffff0000, v62
	v_or_b32_sdwa v63, v63, v66 dst_sel:DWORD dst_unused:UNUSED_PAD src0_sel:DWORD src1_sel:WORD_1
	v_or_b32_sdwa v62, v62, v67 dst_sel:DWORD dst_unused:UNUSED_PAD src0_sel:DWORD src1_sel:WORD_1
	global_store_dwordx2 v[60:61], v[62:63], off
.LBB0_2416:
	s_or_b64 exec, exec, s[6:7]
	v_or_b32_e32 v60, 32, v72
	v_cmp_lt_i32_e64 s[6:7], v60, v74
	v_add_u32_e32 v60, v60, v75
	v_ashrrev_i32_e32 v61, 31, v60
	s_and_saveexec_b64 s[8:9], s[6:7]
	s_cbranch_execz .LBB0_2418
	v_lshl_add_u64 v[62:63], v[72:73], 2, s[4:5]
	v_mov_b32_e32 v62, v128
	v_pk_add_f32 v[54:55], v[54:55], v[46:47]
	v_pk_add_f32 v[52:53], v[52:53], v[44:45]
	v_lshlrev_b64 v[66:67], 11, v[60:61]
	v_mov_b32_e32 v91, v54
	v_mov_b32_e32 v54, v53
	v_lshl_add_u64 v[66:67], s[82:83], 0, v[66:67]
	v_mov_b32_e32 v90, v52
	v_lshl_add_u64 v[52:53], v[70:71], 1, v[66:67]
	v_pk_mul_f32 v[54:55], v[54:55], v[62:63] op_sel_hi:[1,0]
	v_pk_mul_f32 v[66:67], v[90:91], v[62:63] op_sel_hi:[1,0]
	v_and_b32_sdwa v68, v55, v87 dst_sel:DWORD dst_unused:UNUSED_PAD src0_sel:WORD_1 src1_sel:DWORD
	v_and_b32_sdwa v89, v54, v87 dst_sel:DWORD dst_unused:UNUSED_PAD src0_sel:WORD_1 src1_sel:DWORD
	v_and_b32_sdwa v62, v67, v87 dst_sel:DWORD dst_unused:UNUSED_PAD src0_sel:WORD_1 src1_sel:DWORD
	v_and_b32_sdwa v63, v66, v87 dst_sel:DWORD dst_unused:UNUSED_PAD src0_sel:WORD_1 src1_sel:DWORD
	v_add3_u32 v55, v55, v68, s2
	v_add3_u32 v54, v54, v89, s2
	v_add3_u32 v63, v66, v63, s2
	v_add3_u32 v62, v67, v62, s2
	v_and_b32_e32 v55, 0xffff0000, v55
	v_and_b32_e32 v54, 0xffff0000, v54
	v_or_b32_sdwa v55, v55, v62 dst_sel:DWORD dst_unused:UNUSED_PAD src0_sel:DWORD src1_sel:WORD_1
	v_or_b32_sdwa v54, v54, v63 dst_sel:DWORD dst_unused:UNUSED_PAD src0_sel:DWORD src1_sel:WORD_1
	global_store_dwordx2 v[52:53], v[54:55], off
.LBB0_2418:
	s_or_b64 exec, exec, s[8:9]
	v_or_b32_e32 v52, 48, v72
	v_cmp_lt_i32_e64 s[8:9], v52, v74
	v_add_u32_e32 v52, v52, v75
	v_ashrrev_i32_e32 v53, 31, v52
	s_and_saveexec_b64 s[20:21], s[8:9]
	s_cbranch_execnz .LBB0_2431
	s_or_b64 exec, exec, s[20:21]
	v_mov_b64_e32 v[36:37], v[130:131]
	v_mov_b64_e32 v[38:39], v[132:133]
	s_and_saveexec_b64 s[20:21], vcc
	s_cbranch_execnz .LBB0_2432

; DEV unsigned pack2(float a, float b) { return (unsigned)f2bf(a) | ((unsigned)f2bf(b) << 16); }
; DEV void phase_moe2(const Params& p, int l, unsigned char* smem) {
;     ...
; #pragma unroll
;         for (int n = 0; n < 4; ++n) {
;           const int col = nt * 128 + wc * 64 + n * 16 + fq * 4;
;           const float4 b4 = *reinterpret_cast<const float4*>(bd + col);
; #pragma unroll
;           for (int m = 0; m < 4; ++m) {
;             const int i = mt * 128 + wr * 64 + m * 16 + fr;
;             if (i < cnt) {
;               const float g = gl[i];
;               *reinterpret_cast<uint2*>(p.out2 + (size_t)(rowoff + i) * 1024 + col) =
;                   make_uint2(pack2((acc[m][n][0] + b4.x) * g, (acc[m][n][1] + b4.y) * g), pack2((acc[m][n][2] + b4.z) * g, (acc[m][n][3] + b4.w) * g));
;             }
;           }
;         }
.LBB0_2423:
	s_or_b64 exec, exec, s[20:21]
	v_mov_b64_e32 v[32:33], v[134:135]
	v_mov_b64_e32 v[34:35], v[136:137]
	s_and_saveexec_b64 s[20:21], vcc
	s_cbranch_execnz .LBB0_2436

; DEV unsigned pack2(float a, float b) { return (unsigned)f2bf(a) | ((unsigned)f2bf(b) << 16); }
; DEV void phase_moe2(const Params& p, int l, unsigned char* smem) {
;     ...
; #pragma unroll
;         for (int n = 0; n < 4; ++n) {
;           const int col = nt * 128 + wc * 64 + n * 16 + fq * 4;
;           const float4 b4 = *reinterpret_cast<const float4*>(bd + col);
; #pragma unroll
;           for (int m = 0; m < 4; ++m) {
;             const int i = mt * 128 + wr * 64 + m * 16 + fr;
;             if (i < cnt) {
;               const float g = gl[i];
;               *reinterpret_cast<uint2*>(p.out2 + (size_t)(rowoff + i) * 1024 + col) =
;                   make_uint2(pack2((acc[m][n][0] + b4.x) * g, (acc[m][n][1] + b4.y) * g), pack2((acc[m][n][2] + b4.z) * g, (acc[m][n][3] + b4.w) * g));
;             }
;           }
;         }
.LBB0_2427:
	s_or_b64 exec, exec, s[20:21]
	v_mov_b64_e32 v[16:17], v[138:139]
	v_mov_b64_e32 v[18:19], v[140:141]
	s_and_saveexec_b64 s[20:21], vcc
	s_cbranch_execnz .LBB0_2440

; DEV unsigned pack2(float a, float b) { return (unsigned)f2bf(a) | ((unsigned)f2bf(b) << 16); }
; DEV void phase_moe2(const Params& p, int l, unsigned char* smem) {
;     ...
; #pragma unroll
;         for (int n = 0; n < 4; ++n) {
;           const int col = nt * 128 + wc * 64 + n * 16 + fq * 4;
;           const float4 b4 = *reinterpret_cast<const float4*>(bd + col);
; #pragma unroll
;           for (int m = 0; m < 4; ++m) {
;             const int i = mt * 128 + wr * 64 + m * 16 + fr;
;             if (i < cnt) {
;               const float g = gl[i];
;               *reinterpret_cast<uint2*>(p.out2 + (size_t)(rowoff + i) * 1024 + col) =
;                   make_uint2(pack2((acc[m][n][0] + b4.x) * g, (acc[m][n][1] + b4.y) * g), pack2((acc[m][n][2] + b4.z) * g, (acc[m][n][3] + b4.w) * g));
;             }
;           }
;         }
.LBB0_2431:
	v_lshl_add_u64 v[54:55], v[72:73], 2, s[4:5]
	v_mov_b32_e32 v54, v129
	v_pk_add_f32 v[38:39], v[38:39], v[46:47]
	v_pk_add_f32 v[36:37], v[36:37], v[44:45]
	v_lshlrev_b64 v[62:63], 11, v[52:53]
	v_mov_b32_e32 v47, v38
	v_mov_b32_e32 v38, v37
	v_lshl_add_u64 v[44:45], s[82:83], 0, v[62:63]
	v_mov_b32_e32 v46, v36
	v_lshl_add_u64 v[36:37], v[70:71], 1, v[44:45]
	v_pk_mul_f32 v[38:39], v[38:39], v[54:55] op_sel_hi:[1,0]
	v_pk_mul_f32 v[44:45], v[46:47], v[54:55] op_sel_hi:[1,0]
	v_and_b32_sdwa v54, v39, v87 dst_sel:DWORD dst_unused:UNUSED_PAD src0_sel:WORD_1 src1_sel:DWORD
	v_and_b32_sdwa v55, v38, v87 dst_sel:DWORD dst_unused:UNUSED_PAD src0_sel:WORD_1 src1_sel:DWORD
	v_and_b32_sdwa v46, v45, v87 dst_sel:DWORD dst_unused:UNUSED_PAD src0_sel:WORD_1 src1_sel:DWORD
	v_and_b32_sdwa v47, v44, v87 dst_sel:DWORD dst_unused:UNUSED_PAD src0_sel:WORD_1 src1_sel:DWORD
	v_add3_u32 v39, v39, v54, s2
	v_add3_u32 v38, v38, v55, s2
	v_add3_u32 v44, v44, v47, s2
	v_add3_u32 v45, v45, v46, s2
	v_and_b32_e32 v39, 0xffff0000, v39
	v_and_b32_e32 v38, 0xffff0000, v38
	v_or_b32_sdwa v39, v39, v45 dst_sel:DWORD dst_unused:UNUSED_PAD src0_sel:DWORD src1_sel:WORD_1
	v_or_b32_sdwa v38, v38, v44 dst_sel:DWORD dst_unused:UNUSED_PAD src0_sel:DWORD src1_sel:WORD_1
	global_store_dwordx2 v[36:37], v[38:39], off
	s_or_b64 exec, exec, s[20:21]
	v_mov_b64_e32 v[36:37], v[130:131]
	v_mov_b64_e32 v[38:39], v[132:133]
	s_and_saveexec_b64 s[20:21], vcc
	s_cbranch_execz .LBB0_2420
.LBB0_2432:
	v_lshl_add_u64 v[44:45], v[72:73], 2, s[4:5]
	v_mov_b32_e32 v44, v126
	v_pk_add_f32 v[54:55], v[58:59], v[38:39]
	v_pk_add_f32 v[56:57], v[56:57], v[36:37]
	v_mov_b32_e32 v59, v54
	v_mov_b32_e32 v58, v56
	v_mov_b32_e32 v54, v57
	v_lshlrev_b64 v[46:47], 11, v[78:79]
	v_lshl_add_u64 v[46:47], s[82:83], 0, v[46:47]
	v_lshl_add_u64 v[46:47], v[70:71], 1, v[46:47]
	v_pk_mul_f32 v[56:57], v[58:59], v[44:45] op_sel_hi:[1,0]
	v_pk_mul_f32 v[44:45], v[54:55], v[44:45] op_sel_hi:[1,0]
	v_and_b32_sdwa v54, v57, v87 dst_sel:DWORD dst_unused:UNUSED_PAD src0_sel:WORD_1 src1_sel:DWORD
	v_and_b32_sdwa v58, v45, v87 dst_sel:DWORD dst_unused:UNUSED_PAD src0_sel:WORD_1 src1_sel:DWORD
	v_and_b32_sdwa v59, v44, v87 dst_sel:DWORD dst_unused:UNUSED_PAD src0_sel:WORD_1 src1_sel:DWORD
	v_and_b32_sdwa v55, v56, v87 dst_sel:DWORD dst_unused:UNUSED_PAD src0_sel:WORD_1 src1_sel:DWORD
	v_add3_u32 v45, v45, v58, s2
	v_add3_u32 v44, v44, v59, s2
	v_add3_u32 v55, v56, v55, s2
	v_add3_u32 v54, v57, v54, s2
	v_and_b32_e32 v45, 0xffff0000, v45
	v_and_b32_e32 v44, 0xffff0000, v44
	v_or_b32_sdwa v45, v45, v54 dst_sel:DWORD dst_unused:UNUSED_PAD src0_sel:DWORD src1_sel:WORD_1
	v_or_b32_sdwa v44, v44, v55 dst_sel:DWORD dst_unused:UNUSED_PAD src0_sel:DWORD src1_sel:WORD_1
	global_store_dwordx2 v[46:47], v[44:45], off offset:32
	s_or_b64 exec, exec, s[20:21]
	s_and_saveexec_b64 s[20:21], s[0:1]
	s_cbranch_execz .LBB0_2421
.LBB0_2433:
	v_lshl_add_u64 v[44:45], v[72:73], 2, s[4:5]
	v_mov_b32_e32 v44, v127
	v_pk_add_f32 v[50:51], v[50:51], v[38:39]
	v_pk_add_f32 v[48:49], v[48:49], v[36:37]
	v_mov_b32_e32 v55, v50
	v_mov_b32_e32 v54, v48
	v_mov_b32_e32 v50, v49
	v_lshlrev_b64 v[46:47], 11, v[64:65]
	v_lshl_add_u64 v[46:47], s[82:83], 0, v[46:47]
	v_lshl_add_u64 v[46:47], v[70:71], 1, v[46:47]
	v_pk_mul_f32 v[48:49], v[54:55], v[44:45] op_sel_hi:[1,0]
	v_pk_mul_f32 v[44:45], v[50:51], v[44:45] op_sel_hi:[1,0]
	v_and_b32_sdwa v50, v49, v87 dst_sel:DWORD dst_unused:UNUSED_PAD src0_sel:WORD_1 src1_sel:DWORD
	v_and_b32_sdwa v54, v45, v87 dst_sel:DWORD dst_unused:UNUSED_PAD src0_sel:WORD_1 src1_sel:DWORD
	v_and_b32_sdwa v55, v44, v87 dst_sel:DWORD dst_unused:UNUSED_PAD src0_sel:WORD_1 src1_sel:DWORD
	v_and_b32_sdwa v51, v48, v87 dst_sel:DWORD dst_unused:UNUSED_PAD src0_sel:WORD_1 src1_sel:DWORD
	v_add3_u32 v45, v45, v54, s2
	v_add3_u32 v44, v44, v55, s2
	v_add3_u32 v48, v48, v51, s2
	v_add3_u32 v49, v49, v50, s2
	v_and_b32_e32 v45, 0xffff0000, v45
	v_and_b32_e32 v44, 0xffff0000, v44
	v_or_b32_sdwa v45, v45, v49 dst_sel:DWORD dst_unused:UNUSED_PAD src0_sel:DWORD src1_sel:WORD_1
	v_or_b32_sdwa v44, v44, v48 dst_sel:DWORD dst_unused:UNUSED_PAD src0_sel:DWORD src1_sel:WORD_1
	global_store_dwordx2 v[46:47], v[44:45], off offset:32
	s_or_b64 exec, exec, s[20:21]
	s_and_saveexec_b64 s[20:21], s[6:7]
	s_cbranch_execz .LBB0_2422
.LBB0_2434:
	v_lshl_add_u64 v[44:45], v[72:73], 2, s[4:5]
	v_mov_b32_e32 v44, v128
	v_pk_add_f32 v[42:43], v[42:43], v[38:39]
	v_pk_add_f32 v[40:41], v[40:41], v[36:37]
	v_lshlrev_b64 v[46:47], 11, v[60:61]
	v_mov_b32_e32 v49, v42
	v_mov_b32_e32 v42, v41
	v_lshl_add_u64 v[46:47], s[82:83], 0, v[46:47]
	v_mov_b32_e32 v48, v40
	v_lshl_add_u64 v[40:41], v[70:71], 1, v[46:47]
	v_pk_mul_f32 v[42:43], v[42:43], v[44:45] op_sel_hi:[1,0]
	v_pk_mul_f32 v[46:47], v[48:49], v[44:45] op_sel_hi:[1,0]
	v_and_b32_sdwa v48, v43, v87 dst_sel:DWORD dst_unused:UNUSED_PAD src0_sel:WORD_1 src1_sel:DWORD
	v_and_b32_sdwa v49, v42, v87 dst_sel:DWORD dst_unused:UNUSED_PAD src0_sel:WORD_1 src1_sel:DWORD
	v_and_b32_sdwa v44, v47, v87 dst_sel:DWORD dst_unused:UNUSED_PAD src0_sel:WORD_1 src1_sel:DWORD
	v_and_b32_sdwa v45, v46, v87 dst_sel:DWORD dst_unused:UNUSED_PAD src0_sel:WORD_1 src1_sel:DWORD
	v_add3_u32 v43, v43, v48, s2
	v_add3_u32 v42, v42, v49, s2
	v_add3_u32 v45, v46, v45, s2
	v_add3_u32 v44, v47, v44, s2
	v_and_b32_e32 v43, 0xffff0000, v43
	v_and_b32_e32 v42, 0xffff0000, v42
	v_or_b32_sdwa v43, v43, v44 dst_sel:DWORD dst_unused:UNUSED_PAD src0_sel:DWORD src1_sel:WORD_1
	v_or_b32_sdwa v42, v42, v45 dst_sel:DWORD dst_unused:UNUSED_PAD src0_sel:DWORD src1_sel:WORD_1
	global_store_dwordx2 v[40:41], v[42:43], off offset:32
	s_or_b64 exec, exec, s[20:21]
	s_and_saveexec_b64 s[20:21], s[8:9]
	s_cbranch_execz .LBB0_2423
; DEV unsigned pack2(float a, float b) { return (unsigned)f2bf(a) | ((unsigned)f2bf(b) << 16); }
; DEV void phase_moe2(const Params& p, int l, unsigned char* smem) {
;     ...
; #pragma unroll
;         for (int n = 0; n < 4; ++n) {
;           const int col = nt * 128 + wc * 64 + n * 16 + fq * 4;
;           const float4 b4 = *reinterpret_cast<const float4*>(bd + col);
; #pragma unroll
;           for (int m = 0; m < 4; ++m) {
;             const int i = mt * 128 + wr * 64 + m * 16 + fr;
;             if (i < cnt) {
;               const float g = gl[i];
;               *reinterpret_cast<uint2*>(p.out2 + (size_t)(rowoff + i) * 1024 + col) =
;                   make_uint2(pack2((acc[m][n][0] + b4.x) * g, (acc[m][n][1] + b4.y) * g), pack2((acc[m][n][2] + b4.z) * g, (acc[m][n][3] + b4.w) * g));
;             }
;           }
;         }
.LBB0_2435:
	v_lshl_add_u64 v[40:41], v[72:73], 2, s[4:5]
	v_mov_b32_e32 v40, v129
	v_pk_add_f32 v[34:35], v[34:35], v[38:39]
	v_pk_add_f32 v[32:33], v[32:33], v[36:37]
	v_lshlrev_b64 v[42:43], 11, v[52:53]
	v_mov_b32_e32 v39, v34
	v_mov_b32_e32 v34, v33
	v_lshl_add_u64 v[36:37], s[82:83], 0, v[42:43]
	v_mov_b32_e32 v38, v32
	v_lshl_add_u64 v[32:33], v[70:71], 1, v[36:37]
	v_pk_mul_f32 v[34:35], v[34:35], v[40:41] op_sel_hi:[1,0]
	v_pk_mul_f32 v[36:37], v[38:39], v[40:41] op_sel_hi:[1,0]
	v_and_b32_sdwa v40, v35, v87 dst_sel:DWORD dst_unused:UNUSED_PAD src0_sel:WORD_1 src1_sel:DWORD
	v_and_b32_sdwa v41, v34, v87 dst_sel:DWORD dst_unused:UNUSED_PAD src0_sel:WORD_1 src1_sel:DWORD
	v_and_b32_sdwa v38, v37, v87 dst_sel:DWORD dst_unused:UNUSED_PAD src0_sel:WORD_1 src1_sel:DWORD
	v_and_b32_sdwa v39, v36, v87 dst_sel:DWORD dst_unused:UNUSED_PAD src0_sel:WORD_1 src1_sel:DWORD
	v_add3_u32 v35, v35, v40, s2
	v_add3_u32 v34, v34, v41, s2
	v_add3_u32 v36, v36, v39, s2
	v_add3_u32 v37, v37, v38, s2
	v_and_b32_e32 v35, 0xffff0000, v35
	v_and_b32_e32 v34, 0xffff0000, v34
	v_or_b32_sdwa v35, v35, v37 dst_sel:DWORD dst_unused:UNUSED_PAD src0_sel:DWORD src1_sel:WORD_1
	v_or_b32_sdwa v34, v34, v36 dst_sel:DWORD dst_unused:UNUSED_PAD src0_sel:DWORD src1_sel:WORD_1
	global_store_dwordx2 v[32:33], v[34:35], off offset:32
	s_or_b64 exec, exec, s[20:21]
	v_mov_b64_e32 v[32:33], v[134:135]
	v_mov_b64_e32 v[34:35], v[136:137]
	s_and_saveexec_b64 s[20:21], vcc
	s_cbranch_execz .LBB0_2424
.LBB0_2436:
	v_lshl_add_u64 v[36:37], v[72:73], 2, s[4:5]
	v_mov_b32_e32 v36, v126
	v_pk_add_f32 v[30:31], v[30:31], v[34:35]
	v_pk_add_f32 v[28:29], v[28:29], v[32:33]
	v_lshlrev_b64 v[38:39], 11, v[78:79]
	v_mov_b32_e32 v41, v30
	v_mov_b32_e32 v30, v29
	v_lshl_add_u64 v[38:39], s[82:83], 0, v[38:39]
	v_mov_b32_e32 v40, v28
	v_lshl_add_u64 v[28:29], v[70:71], 1, v[38:39]
	v_pk_mul_f32 v[30:31], v[30:31], v[36:37] op_sel_hi:[1,0]
	v_pk_mul_f32 v[38:39], v[40:41], v[36:37] op_sel_hi:[1,0]
	v_and_b32_sdwa v40, v31, v87 dst_sel:DWORD dst_unused:UNUSED_PAD src0_sel:WORD_1 src1_sel:DWORD
	v_and_b32_sdwa v41, v30, v87 dst_sel:DWORD dst_unused:UNUSED_PAD src0_sel:WORD_1 src1_sel:DWORD
	v_and_b32_sdwa v36, v39, v87 dst_sel:DWORD dst_unused:UNUSED_PAD src0_sel:WORD_1 src1_sel:DWORD
	v_and_b32_sdwa v37, v38, v87 dst_sel:DWORD dst_unused:UNUSED_PAD src0_sel:WORD_1 src1_sel:DWORD
	v_add3_u32 v31, v31, v40, s2
	v_add3_u32 v30, v30, v41, s2
	v_add3_u32 v37, v38, v37, s2
	v_add3_u32 v36, v39, v36, s2
	v_and_b32_e32 v31, 0xffff0000, v31
	v_and_b32_e32 v30, 0xffff0000, v30
	v_or_b32_sdwa v31, v31, v36 dst_sel:DWORD dst_unused:UNUSED_PAD src0_sel:DWORD src1_sel:WORD_1
	v_or_b32_sdwa v30, v30, v37 dst_sel:DWORD dst_unused:UNUSED_PAD src0_sel:DWORD src1_sel:WORD_1
	global_store_dwordx2 v[28:29], v[30:31], off offset:64
	s_or_b64 exec, exec, s[20:21]
	s_and_saveexec_b64 s[20:21], s[0:1]
	s_cbranch_execz .LBB0_2425
.LBB0_2437:
	v_lshl_add_u64 v[28:29], v[72:73], 2, s[4:5]
	v_mov_b32_e32 v28, v127
	v_pk_add_f32 v[26:27], v[26:27], v[34:35]
	v_pk_add_f32 v[24:25], v[24:25], v[32:33]
	v_lshlrev_b64 v[30:31], 11, v[64:65]
	v_mov_b32_e32 v37, v26
	v_mov_b32_e32 v26, v25
	v_lshl_add_u64 v[30:31], s[82:83], 0, v[30:31]
	v_mov_b32_e32 v36, v24
	v_lshl_add_u64 v[24:25], v[70:71], 1, v[30:31]
	v_pk_mul_f32 v[26:27], v[26:27], v[28:29] op_sel_hi:[1,0]
	v_pk_mul_f32 v[30:31], v[36:37], v[28:29] op_sel_hi:[1,0]
	v_and_b32_sdwa v36, v27, v87 dst_sel:DWORD dst_unused:UNUSED_PAD src0_sel:WORD_1 src1_sel:DWORD
	v_and_b32_sdwa v37, v26, v87 dst_sel:DWORD dst_unused:UNUSED_PAD src0_sel:WORD_1 src1_sel:DWORD
	v_and_b32_sdwa v28, v31, v87 dst_sel:DWORD dst_unused:UNUSED_PAD src0_sel:WORD_1 src1_sel:DWORD
	v_and_b32_sdwa v29, v30, v87 dst_sel:DWORD dst_unused:UNUSED_PAD src0_sel:WORD_1 src1_sel:DWORD
	v_add3_u32 v27, v27, v36, s2
	v_add3_u32 v26, v26, v37, s2
	v_add3_u32 v29, v30, v29, s2
	v_add3_u32 v28, v31, v28, s2
	v_and_b32_e32 v27, 0xffff0000, v27
	v_and_b32_e32 v26, 0xffff0000, v26
	v_or_b32_sdwa v27, v27, v28 dst_sel:DWORD dst_unused:UNUSED_PAD src0_sel:DWORD src1_sel:WORD_1
	v_or_b32_sdwa v26, v26, v29 dst_sel:DWORD dst_unused:UNUSED_PAD src0_sel:DWORD src1_sel:WORD_1
	global_store_dwordx2 v[24:25], v[26:27], off offset:64
	s_or_b64 exec, exec, s[20:21]
	s_and_saveexec_b64 s[20:21], s[6:7]
	s_cbranch_execz .LBB0_2426
.LBB0_2438:
	v_lshl_add_u64 v[24:25], v[72:73], 2, s[4:5]
	v_mov_b32_e32 v24, v128
	v_pk_add_f32 v[22:23], v[22:23], v[34:35]
	v_pk_add_f32 v[20:21], v[20:21], v[32:33]
	v_lshlrev_b64 v[26:27], 11, v[60:61]
	v_mov_b32_e32 v29, v22
	v_mov_b32_e32 v22, v21
	v_lshl_add_u64 v[26:27], s[82:83], 0, v[26:27]
	v_mov_b32_e32 v28, v20
	v_lshl_add_u64 v[20:21], v[70:71], 1, v[26:27]
	v_pk_mul_f32 v[22:23], v[22:23], v[24:25] op_sel_hi:[1,0]
	v_pk_mul_f32 v[26:27], v[28:29], v[24:25] op_sel_hi:[1,0]
	v_and_b32_sdwa v28, v23, v87 dst_sel:DWORD dst_unused:UNUSED_PAD src0_sel:WORD_1 src1_sel:DWORD
	v_and_b32_sdwa v29, v22, v87 dst_sel:DWORD dst_unused:UNUSED_PAD src0_sel:WORD_1 src1_sel:DWORD
	v_and_b32_sdwa v24, v27, v87 dst_sel:DWORD dst_unused:UNUSED_PAD src0_sel:WORD_1 src1_sel:DWORD
	v_and_b32_sdwa v25, v26, v87 dst_sel:DWORD dst_unused:UNUSED_PAD src0_sel:WORD_1 src1_sel:DWORD
	v_add3_u32 v23, v23, v28, s2
	v_add3_u32 v22, v22, v29, s2
	v_add3_u32 v25, v26, v25, s2
	v_add3_u32 v24, v27, v24, s2
	v_and_b32_e32 v23, 0xffff0000, v23
	v_and_b32_e32 v22, 0xffff0000, v22
	v_or_b32_sdwa v23, v23, v24 dst_sel:DWORD dst_unused:UNUSED_PAD src0_sel:DWORD src1_sel:WORD_1
	v_or_b32_sdwa v22, v22, v25 dst_sel:DWORD dst_unused:UNUSED_PAD src0_sel:DWORD src1_sel:WORD_1
	global_store_dwordx2 v[20:21], v[22:23], off offset:64
	s_or_b64 exec, exec, s[20:21]
	s_and_saveexec_b64 s[20:21], s[8:9]
	s_cbranch_execz .LBB0_2427
; DEV unsigned pack2(float a, float b) { return (unsigned)f2bf(a) | ((unsigned)f2bf(b) << 16); }
; DEV void phase_moe2(const Params& p, int l, unsigned char* smem) {
;     ...
; #pragma unroll
;         for (int n = 0; n < 4; ++n) {
;           const int col = nt * 128 + wc * 64 + n * 16 + fq * 4;
;           const float4 b4 = *reinterpret_cast<const float4*>(bd + col);
; #pragma unroll
;           for (int m = 0; m < 4; ++m) {
;             const int i = mt * 128 + wr * 64 + m * 16 + fr;
;             if (i < cnt) {
;               const float g = gl[i];
;               *reinterpret_cast<uint2*>(p.out2 + (size_t)(rowoff + i) * 1024 + col) =
;                   make_uint2(pack2((acc[m][n][0] + b4.x) * g, (acc[m][n][1] + b4.y) * g), pack2((acc[m][n][2] + b4.z) * g, (acc[m][n][3] + b4.w) * g));
;             }
;           }
;         }
.LBB0_2439:
	v_lshl_add_u64 v[20:21], v[72:73], 2, s[4:5]
	v_mov_b32_e32 v20, v129
	v_pk_add_f32 v[18:19], v[18:19], v[34:35]
	v_pk_add_f32 v[16:17], v[16:17], v[32:33]
	v_lshlrev_b64 v[22:23], 11, v[52:53]
	v_mov_b32_e32 v25, v18
	v_mov_b32_e32 v18, v17
	v_lshl_add_u64 v[22:23], s[82:83], 0, v[22:23]
	v_mov_b32_e32 v24, v16
	v_lshl_add_u64 v[16:17], v[70:71], 1, v[22:23]
	v_pk_mul_f32 v[18:19], v[18:19], v[20:21] op_sel_hi:[1,0]
	v_pk_mul_f32 v[22:23], v[24:25], v[20:21] op_sel_hi:[1,0]
	v_and_b32_sdwa v24, v19, v87 dst_sel:DWORD dst_unused:UNUSED_PAD src0_sel:WORD_1 src1_sel:DWORD
	v_and_b32_sdwa v25, v18, v87 dst_sel:DWORD dst_unused:UNUSED_PAD src0_sel:WORD_1 src1_sel:DWORD
	v_and_b32_sdwa v20, v23, v87 dst_sel:DWORD dst_unused:UNUSED_PAD src0_sel:WORD_1 src1_sel:DWORD
	v_and_b32_sdwa v21, v22, v87 dst_sel:DWORD dst_unused:UNUSED_PAD src0_sel:WORD_1 src1_sel:DWORD
	v_add3_u32 v19, v19, v24, s2
	v_add3_u32 v18, v18, v25, s2
	v_add3_u32 v21, v22, v21, s2
	v_add3_u32 v20, v23, v20, s2
	v_and_b32_e32 v19, 0xffff0000, v19
	v_and_b32_e32 v18, 0xffff0000, v18
	v_or_b32_sdwa v19, v19, v20 dst_sel:DWORD dst_unused:UNUSED_PAD src0_sel:DWORD src1_sel:WORD_1
	v_or_b32_sdwa v18, v18, v21 dst_sel:DWORD dst_unused:UNUSED_PAD src0_sel:DWORD src1_sel:WORD_1
	global_store_dwordx2 v[16:17], v[18:19], off offset:64
	s_or_b64 exec, exec, s[20:21]
	v_mov_b64_e32 v[16:17], v[138:139]
	v_mov_b64_e32 v[18:19], v[140:141]
	s_and_saveexec_b64 s[20:21], vcc
	s_cbranch_execz .LBB0_2428
.LBB0_2440:
	v_lshl_add_u64 v[20:21], v[72:73], 2, s[4:5]
	v_mov_b32_e32 v20, v126
	v_pk_add_f32 v[14:15], v[14:15], v[18:19]
	v_pk_add_f32 v[12:13], v[12:13], v[16:17]
	v_lshlrev_b64 v[22:23], 11, v[78:79]
	v_mov_b32_e32 v25, v14
	v_mov_b32_e32 v14, v13
	v_lshl_add_u64 v[22:23], s[82:83], 0, v[22:23]
	v_mov_b32_e32 v24, v12
	v_lshl_add_u64 v[12:13], v[70:71], 1, v[22:23]
	v_pk_mul_f32 v[14:15], v[14:15], v[20:21] op_sel_hi:[1,0]
	v_pk_mul_f32 v[22:23], v[24:25], v[20:21] op_sel_hi:[1,0]
	v_and_b32_sdwa v24, v15, v87 dst_sel:DWORD dst_unused:UNUSED_PAD src0_sel:WORD_1 src1_sel:DWORD
	v_and_b32_sdwa v25, v14, v87 dst_sel:DWORD dst_unused:UNUSED_PAD src0_sel:WORD_1 src1_sel:DWORD
	v_and_b32_sdwa v20, v23, v87 dst_sel:DWORD dst_unused:UNUSED_PAD src0_sel:WORD_1 src1_sel:DWORD
	v_and_b32_sdwa v21, v22, v87 dst_sel:DWORD dst_unused:UNUSED_PAD src0_sel:WORD_1 src1_sel:DWORD
	v_add3_u32 v15, v15, v24, s2
	v_add3_u32 v14, v14, v25, s2
	v_add3_u32 v21, v22, v21, s2
	v_add3_u32 v20, v23, v20, s2
	v_and_b32_e32 v15, 0xffff0000, v15
	v_and_b32_e32 v14, 0xffff0000, v14
	v_or_b32_sdwa v15, v15, v20 dst_sel:DWORD dst_unused:UNUSED_PAD src0_sel:DWORD src1_sel:WORD_1
	v_or_b32_sdwa v14, v14, v21 dst_sel:DWORD dst_unused:UNUSED_PAD src0_sel:DWORD src1_sel:WORD_1
	global_store_dwordx2 v[12:13], v[14:15], off offset:96
	s_or_b64 exec, exec, s[20:21]
	s_and_saveexec_b64 s[20:21], s[0:1]
	s_cbranch_execz .LBB0_2429
.LBB0_2441:
	v_lshl_add_u64 v[12:13], v[72:73], 2, s[4:5]
	v_mov_b32_e32 v12, v127
	v_pk_add_f32 v[10:11], v[10:11], v[18:19]
	v_pk_add_f32 v[8:9], v[8:9], v[16:17]
	v_lshlrev_b64 v[14:15], 11, v[64:65]
	v_mov_b32_e32 v21, v10
	v_mov_b32_e32 v10, v9
	v_lshl_add_u64 v[14:15], s[82:83], 0, v[14:15]
	v_mov_b32_e32 v20, v8
	v_lshl_add_u64 v[8:9], v[70:71], 1, v[14:15]
	v_pk_mul_f32 v[10:11], v[10:11], v[12:13] op_sel_hi:[1,0]
	v_pk_mul_f32 v[14:15], v[20:21], v[12:13] op_sel_hi:[1,0]
	v_and_b32_sdwa v20, v11, v87 dst_sel:DWORD dst_unused:UNUSED_PAD src0_sel:WORD_1 src1_sel:DWORD
	v_and_b32_sdwa v21, v10, v87 dst_sel:DWORD dst_unused:UNUSED_PAD src0_sel:WORD_1 src1_sel:DWORD
	v_and_b32_sdwa v12, v15, v87 dst_sel:DWORD dst_unused:UNUSED_PAD src0_sel:WORD_1 src1_sel:DWORD
	v_and_b32_sdwa v13, v14, v87 dst_sel:DWORD dst_unused:UNUSED_PAD src0_sel:WORD_1 src1_sel:DWORD
	v_add3_u32 v11, v11, v20, s2
	v_add3_u32 v10, v10, v21, s2
	v_add3_u32 v13, v14, v13, s2
	v_add3_u32 v12, v15, v12, s2
	v_and_b32_e32 v11, 0xffff0000, v11
	v_and_b32_e32 v10, 0xffff0000, v10
	v_or_b32_sdwa v11, v11, v12 dst_sel:DWORD dst_unused:UNUSED_PAD src0_sel:DWORD src1_sel:WORD_1
	v_or_b32_sdwa v10, v10, v13 dst_sel:DWORD dst_unused:UNUSED_PAD src0_sel:DWORD src1_sel:WORD_1
	global_store_dwordx2 v[8:9], v[10:11], off offset:96
	s_or_b64 exec, exec, s[20:21]
	s_and_saveexec_b64 s[0:1], s[6:7]
	s_cbranch_execz .LBB0_2430
.LBB0_2442:
	v_lshl_add_u64 v[8:9], v[72:73], 2, s[4:5]
	v_mov_b32_e32 v8, v128
	v_pk_add_f32 v[6:7], v[6:7], v[18:19]
	v_pk_add_f32 v[4:5], v[4:5], v[16:17]
	v_lshlrev_b64 v[10:11], 11, v[60:61]
	v_mov_b32_e32 v13, v6
	v_mov_b32_e32 v6, v5
	v_lshl_add_u64 v[10:11], s[82:83], 0, v[10:11]
	v_mov_b32_e32 v12, v4
	v_lshl_add_u64 v[4:5], v[70:71], 1, v[10:11]
	v_pk_mul_f32 v[6:7], v[6:7], v[8:9] op_sel_hi:[1,0]
	v_pk_mul_f32 v[10:11], v[12:13], v[8:9] op_sel_hi:[1,0]
	v_and_b32_sdwa v12, v7, v87 dst_sel:DWORD dst_unused:UNUSED_PAD src0_sel:WORD_1 src1_sel:DWORD
	v_and_b32_sdwa v13, v6, v87 dst_sel:DWORD dst_unused:UNUSED_PAD src0_sel:WORD_1 src1_sel:DWORD
	v_and_b32_sdwa v8, v11, v87 dst_sel:DWORD dst_unused:UNUSED_PAD src0_sel:WORD_1 src1_sel:DWORD
	v_and_b32_sdwa v9, v10, v87 dst_sel:DWORD dst_unused:UNUSED_PAD src0_sel:WORD_1 src1_sel:DWORD
	v_add3_u32 v7, v7, v12, s2
	v_add3_u32 v6, v6, v13, s2
	v_add3_u32 v9, v10, v9, s2
	v_add3_u32 v8, v11, v8, s2
	v_and_b32_e32 v7, 0xffff0000, v7
	v_and_b32_e32 v6, 0xffff0000, v6
	v_or_b32_sdwa v7, v7, v8 dst_sel:DWORD dst_unused:UNUSED_PAD src0_sel:DWORD src1_sel:WORD_1
	v_or_b32_sdwa v6, v6, v9 dst_sel:DWORD dst_unused:UNUSED_PAD src0_sel:DWORD src1_sel:WORD_1
	global_store_dwordx2 v[4:5], v[6:7], off offset:96
	s_or_b64 exec, exec, s[0:1]
	s_and_saveexec_b64 s[0:1], s[8:9]
	s_cbranch_execz .LBB0_2407
.LBB0_2443:
	v_lshl_add_u64 v[4:5], v[72:73], 2, s[4:5]
	v_mov_b32_e32 v4, v129
	v_pk_add_f32 v[2:3], v[2:3], v[18:19]
	v_pk_add_f32 v[0:1], v[0:1], v[16:17]
	v_lshlrev_b64 v[6:7], 11, v[52:53]
	v_mov_b32_e32 v9, v2
	v_mov_b32_e32 v2, v1
	v_lshl_add_u64 v[6:7], s[82:83], 0, v[6:7]
	v_mov_b32_e32 v8, v0
	v_lshl_add_u64 v[0:1], v[70:71], 1, v[6:7]
	v_pk_mul_f32 v[2:3], v[2:3], v[4:5] op_sel_hi:[1,0]
	v_pk_mul_f32 v[6:7], v[8:9], v[4:5] op_sel_hi:[1,0]
	v_and_b32_sdwa v8, v3, v87 dst_sel:DWORD dst_unused:UNUSED_PAD src0_sel:WORD_1 src1_sel:DWORD
	v_and_b32_sdwa v9, v2, v87 dst_sel:DWORD dst_unused:UNUSED_PAD src0_sel:WORD_1 src1_sel:DWORD
	v_and_b32_sdwa v4, v7, v87 dst_sel:DWORD dst_unused:UNUSED_PAD src0_sel:WORD_1 src1_sel:DWORD
	v_and_b32_sdwa v5, v6, v87 dst_sel:DWORD dst_unused:UNUSED_PAD src0_sel:WORD_1 src1_sel:DWORD
	v_add3_u32 v3, v3, v8, s2
	v_add3_u32 v2, v2, v9, s2
	v_add3_u32 v5, v6, v5, s2
	v_add3_u32 v4, v7, v4, s2
	v_and_b32_e32 v3, 0xffff0000, v3
	v_and_b32_e32 v2, 0xffff0000, v2
	v_or_b32_sdwa v3, v3, v4 dst_sel:DWORD dst_unused:UNUSED_PAD src0_sel:DWORD src1_sel:WORD_1
	v_or_b32_sdwa v2, v2, v5 dst_sel:DWORD dst_unused:UNUSED_PAD src0_sel:DWORD src1_sel:WORD_1
	global_store_dwordx2 v[0:1], v[2:3], off offset:96
	s_branch .LBB0_2407
